# GEMM K-loops: LDS-DMA loads use SGPR base + 32-bit lane offset instead of a 64-bit VALU add per load (16 VALU adds per trip removed)
# baseline (speedup 1.0000x reference)
; #define PG8_STAGE(bufoff, gbase, voff) do { _Pragma("unroll") for (int _i = 0; _i < 2; ++_i) \
;         __builtin_amdgcn_global_load_lds((const unsigned*)((const char*)(gbase) + (voff)[_i]), (PG8_LAS unsigned*)(lds + (bufoff) + ldsw + _i * 8192), 16, 0, 0); } while (0)
; #define PG8_LDA(dst, b, h) do { _Pragma("unroll") for (int m = 0; m < 4; ++m) _Pragma("unroll") for (int k = 0; k < 2; ++k) dst[m][k] = *(const PG8_LAS bf16x8*)(lds + PG8_SA(b, h) + aoff + m * 2048 + k * 1024); } while (0)
; #define PG8_LDB(dst, b, h) do { _Pragma("unroll") for (int n = 0; n < 2; ++n) _Pragma("unroll") for (int k = 0; k < 2; ++k) dst[n][k] = *(const PG8_LAS bf16x8*)(lds + PG8_SB(b, h) + boff + n * 2048 + k * 1024); } while (0)
; #define PG8_MMA(ai, bj, At, Bt) do { __builtin_amdgcn_s_setprio(1); _Pragma("unroll") for (int m = 0; m < 4; ++m) _Pragma("unroll") for (int n = 0; n < 2; ++n) _Pragma("unroll") for (int k = 0; k < 2; ++k) \
;         acc[ai][bj][m][n] = __builtin_amdgcn_mfma_f32_16x16x32_bf16(Bt[n][k], At[m][k], acc[ai][bj][m][n], 0, 0, 0); __builtin_amdgcn_s_setprio(0); } while (0)
; #define PG8_WAIT_V(n) asm volatile("s_waitcnt vmcnt(" #n ")" ::: "memory")
; #define PG8_WAIT_L(n) asm volatile("s_waitcnt lgkmcnt(" #n ")" ::: "memory")
; template <class Epi, class Sched, bool ALIGN_EPI = false, bool SP2 = false>
; __device__ __forceinline__ void gemm_phase(PG8_LAS unsigned char* lds, const Gemm g, const Sched& S, const Epi& E, const int tid) {
;     ...
;             const bool last = (t == nt - 2);
;             const char* a1 = cA + (size_t)(t + 1) * kstep;
;             const char* a2 = last ? nA : cA + (size_t)(t + 2) * kstep; const char* b2 = last ? nB : cB + (size_t)(t + 2) * kstep;
;             const char* a3 = a2 + kstep; const char* b3 = b2 + kstep;
;             if (last && has_next) S.a_ready(nxt);
;             if constexpr (SP2) {
;             PG8_LDB(B0, 0, 0); PG8_LDB(B1, 0, 1); PG8_SCHED; PG8_LDA(At, 0, 0); PG8_STAGE(PG8_SA(1, 1), a1 + hstepA, voffA);
;             PG8_WAIT_V(8); PG8_WAIT_L(0); PG8_BAR; PG8_MMA(0, 0, At, B0); PG8_MMA(0, 1, At, B1); PG8_BAR; PG8_SCHED;
;             PG8_LDA(At, 0, 1); PG8_STAGE(PG8_SB(0, 0), b2, voffB); PG8_STAGE(PG8_SB(0, 1), b2 + hstep, voffB); PG8_STAGE(PG8_SA(0, 0), a2, voffA);
;             PG8_WAIT_V(8); PG8_WAIT_L(0); PG8_BAR; PG8_MMA(1, 0, At, B0); PG8_MMA(1, 1, At, B1); PG8_BAR; PG8_SCHED;
.Lsp_0:
	ds_read_b128 v[144:147], v154
	ds_read_b128 v[148:151], v154 offset:1024
	ds_read_b128 v[160:163], v154 offset:2048
	ds_read_b128 v[164:167], v154 offset:3072
	ds_read_b128 v[168:171], v155
	ds_read_b128 v[172:175], v155 offset:1024
	ds_read_b128 v[176:179], v155 offset:2048
	ds_read_b128 v[180:183], v155 offset:3072
	s_add_u32 s26, s24, 0xfffc0080
	s_addc_u32 s27, s25, -1
	s_cmp_eq_u32 s58, 12
	s_cselect_b32 s29, s17, s27
	s_cselect_b32 s28, s54, s26
	s_cselect_b32 s27, s15, s57
	s_cselect_b32 s26, s55, s56
	s_add_i32 m0, s39, 0xc000
	ds_read_b128 v[184:187], v156
	ds_read_b128 v[188:191], v156 offset:1024
	ds_read_b128 v[192:195], v156 offset:2048
	ds_read_b128 v[200:203], v156 offset:3072
	ds_read_b128 v[204:207], v156 offset:4096
	ds_read_b128 v[208:211], v156 offset:5120
	ds_read_b128 v[212:215], v156 offset:6144
	ds_read_b128 v[216:219], v156 offset:7168
	global_load_lds_dwordx4 v136, s[24:25]
	s_add_i32 m0, s39, 0xe000
	s_nop 0
	global_load_lds_dwordx4 v138, s[24:25]
	s_waitcnt vmcnt(8)
	s_waitcnt lgkmcnt(0)
	s_barrier
	s_waitcnt lgkmcnt(0)
	v_mfma_f32_16x16x32_bf16 v[124:127], v[144:147], v[184:187], v[124:127]
	v_mfma_f32_16x16x32_bf16 v[120:123], v[160:163], v[184:187], v[120:123]
	v_mfma_f32_16x16x32_bf16 v[108:111], v[144:147], v[192:195], v[108:111]
	v_mfma_f32_16x16x32_bf16 v[104:107], v[160:163], v[192:195], v[104:107]
	v_mfma_f32_16x16x32_bf16 v[92:95], v[144:147], v[204:207], v[92:95]
	v_mfma_f32_16x16x32_bf16 v[88:91], v[160:163], v[204:207], v[88:91]
	v_mfma_f32_16x16x32_bf16 v[76:79], v[144:147], v[212:215], v[76:79]
	v_mfma_f32_16x16x32_bf16 v[72:75], v[160:163], v[212:215], v[72:75]
	v_mfma_f32_16x16x32_bf16 v[124:127], v[148:151], v[188:191], v[124:127]
	v_mfma_f32_16x16x32_bf16 v[120:123], v[164:167], v[188:191], v[120:123]
	v_mfma_f32_16x16x32_bf16 v[108:111], v[148:151], v[200:203], v[108:111]
	v_mfma_f32_16x16x32_bf16 v[104:107], v[164:167], v[200:203], v[104:107]
	v_mfma_f32_16x16x32_bf16 v[92:95], v[148:151], v[208:211], v[92:95]
	v_mfma_f32_16x16x32_bf16 v[88:91], v[164:167], v[208:211], v[88:91]
	v_mfma_f32_16x16x32_bf16 v[76:79], v[148:151], v[216:219], v[76:79]
	v_mfma_f32_16x16x32_bf16 v[72:75], v[164:167], v[216:219], v[72:75]
	v_mfma_f32_16x16x32_bf16 v[116:119], v[168:171], v[184:187], v[116:119]
	v_mfma_f32_16x16x32_bf16 v[112:115], v[176:179], v[184:187], v[112:115]
	v_mfma_f32_16x16x32_bf16 v[100:103], v[168:171], v[192:195], v[100:103]
	v_mfma_f32_16x16x32_bf16 v[96:99], v[176:179], v[192:195], v[96:99]
	v_mfma_f32_16x16x32_bf16 v[84:87], v[168:171], v[204:207], v[84:87]
	v_mfma_f32_16x16x32_bf16 v[80:83], v[176:179], v[204:207], v[80:83]
	v_mfma_f32_16x16x32_bf16 v[68:71], v[168:171], v[212:215], v[68:71]
	v_mfma_f32_16x16x32_bf16 v[64:67], v[176:179], v[212:215], v[64:67]
	v_mfma_f32_16x16x32_bf16 v[116:119], v[172:175], v[188:191], v[116:119]
	v_mfma_f32_16x16x32_bf16 v[112:115], v[180:183], v[188:191], v[112:115]
	v_mfma_f32_16x16x32_bf16 v[100:103], v[172:175], v[200:203], v[100:103]
	v_mfma_f32_16x16x32_bf16 v[96:99], v[180:183], v[200:203], v[96:99]
	v_mfma_f32_16x16x32_bf16 v[84:87], v[172:175], v[208:211], v[84:87]
	v_mfma_f32_16x16x32_bf16 v[80:83], v[180:183], v[208:211], v[80:83]
	v_mfma_f32_16x16x32_bf16 v[68:71], v[172:175], v[216:219], v[68:71]
	v_mfma_f32_16x16x32_bf16 v[64:67], v[180:183], v[216:219], v[64:67]
	s_barrier
	s_mov_b32 m0, s23
	s_mov_b64 s[98:99], s[26:27]
	s_add_u32 s60, s26, 0x40000
	ds_read_b128 v[184:187], v156 offset:16384
	ds_read_b128 v[188:191], v156 offset:17408
	ds_read_b128 v[192:195], v156 offset:18432
	ds_read_b128 v[200:203], v156 offset:19456
	ds_read_b128 v[204:207], v156 offset:20480
	ds_read_b128 v[208:211], v156 offset:21504
	ds_read_b128 v[212:215], v156 offset:22528
	ds_read_b128 v[216:219], v156 offset:23552
	global_load_lds_dwordx4 v132, s[26:27]
	s_mov_b32 m0, s36
	s_addc_u32 s61, s27, 0
	global_load_lds_dwordx4 v128, s[26:27]
	s_mov_b32 m0, s37
	s_nop 0
	global_load_lds_dwordx4 v132, s[60:61]
	s_mov_b32 m0, s38
	s_nop 0
	global_load_lds_dwordx4 v128, s[60:61]
	s_mov_b64 s[100:101], s[28:29]
	s_mov_b32 m0, s39
	s_nop 0
	global_load_lds_dwordx4 v134, s[28:29]
	s_mov_b32 m0, s40
	s_nop 0
	global_load_lds_dwordx4 v130, s[28:29]
	s_waitcnt vmcnt(8)
	s_waitcnt lgkmcnt(0)
	s_barrier
	s_waitcnt lgkmcnt(0)
	v_mfma_f32_16x16x32_bf16 v[60:63], v[144:147], v[184:187], v[60:63]
	v_mfma_f32_16x16x32_bf16 v[56:59], v[160:163], v[184:187], v[56:59]
	v_mfma_f32_16x16x32_bf16 v[44:47], v[144:147], v[192:195], v[44:47]
	v_mfma_f32_16x16x32_bf16 v[40:43], v[160:163], v[192:195], v[40:43]
	v_mfma_f32_16x16x32_bf16 v[28:31], v[144:147], v[204:207], v[28:31]
	v_mfma_f32_16x16x32_bf16 v[24:27], v[160:163], v[204:207], v[24:27]
	v_mfma_f32_16x16x32_bf16 v[12:15], v[144:147], v[212:215], v[12:15]
	v_mfma_f32_16x16x32_bf16 v[8:11], v[160:163], v[212:215], v[8:11]
	v_mfma_f32_16x16x32_bf16 v[60:63], v[148:151], v[188:191], v[60:63]
	v_mfma_f32_16x16x32_bf16 v[56:59], v[164:167], v[188:191], v[56:59]
	v_mfma_f32_16x16x32_bf16 v[44:47], v[148:151], v[200:203], v[44:47]
	v_mfma_f32_16x16x32_bf16 v[40:43], v[164:167], v[200:203], v[40:43]
	v_mfma_f32_16x16x32_bf16 v[28:31], v[148:151], v[208:211], v[28:31]
	v_mfma_f32_16x16x32_bf16 v[24:27], v[164:167], v[208:211], v[24:27]
	v_mfma_f32_16x16x32_bf16 v[12:15], v[148:151], v[216:219], v[12:15]
	v_mfma_f32_16x16x32_bf16 v[8:11], v[164:167], v[216:219], v[8:11]
	v_mfma_f32_16x16x32_bf16 v[52:55], v[168:171], v[184:187], v[52:55]
	v_mfma_f32_16x16x32_bf16 v[48:51], v[176:179], v[184:187], v[48:51]
	v_mfma_f32_16x16x32_bf16 v[36:39], v[168:171], v[192:195], v[36:39]
	v_mfma_f32_16x16x32_bf16 v[32:35], v[176:179], v[192:195], v[32:35]
	v_mfma_f32_16x16x32_bf16 v[20:23], v[168:171], v[204:207], v[20:23]
	v_mfma_f32_16x16x32_bf16 v[16:19], v[176:179], v[204:207], v[16:19]
	v_mfma_f32_16x16x32_bf16 v[4:7], v[168:171], v[212:215], v[4:7]
	v_mfma_f32_16x16x32_bf16 v[0:3], v[176:179], v[212:215], v[0:3]
	v_mfma_f32_16x16x32_bf16 v[52:55], v[172:175], v[188:191], v[52:55]
	v_mfma_f32_16x16x32_bf16 v[48:51], v[180:183], v[188:191], v[48:51]
	v_mfma_f32_16x16x32_bf16 v[36:39], v[172:175], v[200:203], v[36:39]
	v_mfma_f32_16x16x32_bf16 v[32:35], v[180:183], v[200:203], v[32:35]
	v_mfma_f32_16x16x32_bf16 v[20:23], v[172:175], v[208:211], v[20:23]
	v_mfma_f32_16x16x32_bf16 v[16:19], v[180:183], v[208:211], v[16:19]
	v_mfma_f32_16x16x32_bf16 v[4:7], v[172:175], v[216:219], v[4:7]
	v_mfma_f32_16x16x32_bf16 v[0:3], v[180:183], v[216:219], v[0:3]
	s_barrier
; #define PG8_STAGE(bufoff, gbase, voff) do { _Pragma("unroll") for (int _i = 0; _i < 2; ++_i) \
;         __builtin_amdgcn_global_load_lds((const unsigned*)((const char*)(gbase) + (voff)[_i]), (PG8_LAS unsigned*)(lds + (bufoff) + ldsw + _i * 8192), 16, 0, 0); } while (0)
; #define PG8_LDA(dst, b, h) do { _Pragma("unroll") for (int m = 0; m < 4; ++m) _Pragma("unroll") for (int k = 0; k < 2; ++k) dst[m][k] = *(const PG8_LAS bf16x8*)(lds + PG8_SA(b, h) + aoff + m * 2048 + k * 1024); } while (0)
; #define PG8_LDB(dst, b, h) do { _Pragma("unroll") for (int n = 0; n < 2; ++n) _Pragma("unroll") for (int k = 0; k < 2; ++k) dst[n][k] = *(const PG8_LAS bf16x8*)(lds + PG8_SB(b, h) + boff + n * 2048 + k * 1024); } while (0)
; #define PG8_MMA(ai, bj, At, Bt) do { __builtin_amdgcn_s_setprio(1); _Pragma("unroll") for (int m = 0; m < 4; ++m) _Pragma("unroll") for (int n = 0; n < 2; ++n) _Pragma("unroll") for (int k = 0; k < 2; ++k) \
;         acc[ai][bj][m][n] = __builtin_amdgcn_mfma_f32_16x16x32_bf16(Bt[n][k], At[m][k], acc[ai][bj][m][n], 0, 0, 0); __builtin_amdgcn_s_setprio(0); } while (0)
; #define PG8_WAIT_V(n) asm volatile("s_waitcnt vmcnt(" #n ")" ::: "memory")
; #define PG8_WAIT_L(n) asm volatile("s_waitcnt lgkmcnt(" #n ")" ::: "memory")
; #define PG8_BAR __builtin_amdgcn_s_barrier()
; #define PG8_SCHED __builtin_amdgcn_sched_barrier(0)
; template <class Epi, class Sched, bool ALIGN_EPI = false, bool SP2 = false>
; __device__ __forceinline__ void gemm_phase(PG8_LAS unsigned char* lds, const Gemm g, const Sched& S, const Epi& E, const int tid) {
;     ...
;             PG8_LDB(B0, 1, 0); PG8_LDB(B1, 1, 1); PG8_SCHED; PG8_LDA(At, 1, 0); PG8_STAGE(PG8_SA(0, 1), a2 + hstepA, voffA);
;             PG8_WAIT_V(8); PG8_WAIT_L(0); PG8_BAR; PG8_MMA(0, 0, At, B0); PG8_MMA(0, 1, At, B1); PG8_BAR; PG8_SCHED;
;             PG8_LDA(At, 1, 1); PG8_STAGE(PG8_SB(1, 0), b3, voffB); PG8_STAGE(PG8_SB(1, 1), b3 + hstep, voffB); PG8_STAGE(PG8_SA(1, 0), a3, voffA);
;             PG8_WAIT_V(8); PG8_WAIT_L(0); PG8_BAR; PG8_MMA(1, 0, At, B0); PG8_MMA(1, 1, At, B1); PG8_BAR; PG8_SCHED;
	ds_read_b128 v[144:147], v157
	ds_read_b128 v[148:151], v157 offset:1024
	ds_read_b128 v[160:163], v157 offset:2048
	ds_read_b128 v[164:167], v157 offset:3072
	ds_read_b128 v[168:171], v158
	ds_read_b128 v[172:175], v158 offset:1024
	ds_read_b128 v[176:179], v158 offset:2048
	ds_read_b128 v[180:183], v158 offset:3072
	s_add_u32 s28, s28, 0x40000
	s_addc_u32 s29, s29, 0
	s_mov_b32 m0, s41
	ds_read_b128 v[184:187], v156 offset:32768
	ds_read_b128 v[188:191], v156 offset:33792
	ds_read_b128 v[192:195], v156 offset:34816
	ds_read_b128 v[200:203], v156 offset:35840
	ds_read_b128 v[204:207], v156 offset:36864
	ds_read_b128 v[208:211], v156 offset:37888
	ds_read_b128 v[212:215], v156 offset:38912
	ds_read_b128 v[216:219], v156 offset:39936
	global_load_lds_dwordx4 v134, s[28:29]
	s_mov_b32 m0, s42
	s_nop 0
	global_load_lds_dwordx4 v130, s[28:29]
	s_waitcnt vmcnt(8)
	s_waitcnt lgkmcnt(0)
	s_barrier
	s_waitcnt lgkmcnt(0)
	v_mfma_f32_16x16x32_bf16 v[124:127], v[144:147], v[184:187], v[124:127]
	v_mfma_f32_16x16x32_bf16 v[120:123], v[160:163], v[184:187], v[120:123]
	v_mfma_f32_16x16x32_bf16 v[108:111], v[144:147], v[192:195], v[108:111]
	v_mfma_f32_16x16x32_bf16 v[104:107], v[160:163], v[192:195], v[104:107]
	v_mfma_f32_16x16x32_bf16 v[92:95], v[144:147], v[204:207], v[92:95]
	v_mfma_f32_16x16x32_bf16 v[88:91], v[160:163], v[204:207], v[88:91]
	v_mfma_f32_16x16x32_bf16 v[76:79], v[144:147], v[212:215], v[76:79]
	v_mfma_f32_16x16x32_bf16 v[72:75], v[160:163], v[212:215], v[72:75]
	v_mfma_f32_16x16x32_bf16 v[124:127], v[148:151], v[188:191], v[124:127]
	v_mfma_f32_16x16x32_bf16 v[120:123], v[164:167], v[188:191], v[120:123]
	v_mfma_f32_16x16x32_bf16 v[108:111], v[148:151], v[200:203], v[108:111]
	v_mfma_f32_16x16x32_bf16 v[104:107], v[164:167], v[200:203], v[104:107]
	v_mfma_f32_16x16x32_bf16 v[92:95], v[148:151], v[208:211], v[92:95]
	v_mfma_f32_16x16x32_bf16 v[88:91], v[164:167], v[208:211], v[88:91]
	v_mfma_f32_16x16x32_bf16 v[76:79], v[148:151], v[216:219], v[76:79]
	v_mfma_f32_16x16x32_bf16 v[72:75], v[164:167], v[216:219], v[72:75]
	v_mfma_f32_16x16x32_bf16 v[116:119], v[168:171], v[184:187], v[116:119]
	v_mfma_f32_16x16x32_bf16 v[112:115], v[176:179], v[184:187], v[112:115]
	v_mfma_f32_16x16x32_bf16 v[100:103], v[168:171], v[192:195], v[100:103]
	v_mfma_f32_16x16x32_bf16 v[96:99], v[176:179], v[192:195], v[96:99]
	v_mfma_f32_16x16x32_bf16 v[84:87], v[168:171], v[204:207], v[84:87]
	v_mfma_f32_16x16x32_bf16 v[80:83], v[176:179], v[204:207], v[80:83]
	v_mfma_f32_16x16x32_bf16 v[68:71], v[168:171], v[212:215], v[68:71]
	v_mfma_f32_16x16x32_bf16 v[64:67], v[176:179], v[212:215], v[64:67]
	v_mfma_f32_16x16x32_bf16 v[116:119], v[172:175], v[188:191], v[116:119]
	v_mfma_f32_16x16x32_bf16 v[112:115], v[180:183], v[188:191], v[112:115]
	v_mfma_f32_16x16x32_bf16 v[100:103], v[172:175], v[200:203], v[100:103]
	v_mfma_f32_16x16x32_bf16 v[96:99], v[180:183], v[200:203], v[96:99]
	v_mfma_f32_16x16x32_bf16 v[84:87], v[172:175], v[208:211], v[84:87]
	v_mfma_f32_16x16x32_bf16 v[80:83], v[180:183], v[208:211], v[80:83]
	v_mfma_f32_16x16x32_bf16 v[68:71], v[172:175], v[216:219], v[68:71]
	v_mfma_f32_16x16x32_bf16 v[64:67], v[180:183], v[216:219], v[64:67]
	s_barrier
	s_mov_b32 m0, s45
	s_add_u32 s98, s98, s10
	s_addc_u32 s99, s99, s11
	s_add_u32 s26, s26, 0x40080
	ds_read_b128 v[184:187], v156 offset:49152
	ds_read_b128 v[188:191], v156 offset:50176
	ds_read_b128 v[192:195], v156 offset:51200
	ds_read_b128 v[200:203], v156 offset:52224
	ds_read_b128 v[204:207], v156 offset:53248
	ds_read_b128 v[208:211], v156 offset:54272
	ds_read_b128 v[212:215], v156 offset:55296
	ds_read_b128 v[216:219], v156 offset:56320
	global_load_lds_dwordx4 v132, s[98:99]
	s_mov_b32 m0, s46
	s_addc_u32 s27, s27, 0
	global_load_lds_dwordx4 v128, s[98:99]
	s_mov_b32 m0, s49
	s_nop 0
	global_load_lds_dwordx4 v132, s[26:27]
	s_mov_b32 m0, s50
	s_nop 0
	global_load_lds_dwordx4 v128, s[26:27]
	s_add_u32 s100, s100, s10
	s_addc_u32 s101, s101, s11
	s_mov_b32 m0, s47
	s_nop 0
	global_load_lds_dwordx4 v134, s[100:101]
	s_mov_b32 m0, s48
	s_nop 0
	global_load_lds_dwordx4 v130, s[100:101]
	s_waitcnt vmcnt(8)
	s_waitcnt lgkmcnt(0)
	s_barrier
; #define PG8_MMA(ai, bj, At, Bt) do { __builtin_amdgcn_s_setprio(1); _Pragma("unroll") for (int m = 0; m < 4; ++m) _Pragma("unroll") for (int n = 0; n < 2; ++n) _Pragma("unroll") for (int k = 0; k < 2; ++k) \
;         acc[ai][bj][m][n] = __builtin_amdgcn_mfma_f32_16x16x32_bf16(Bt[n][k], At[m][k], acc[ai][bj][m][n], 0, 0, 0); __builtin_amdgcn_s_setprio(0); } while (0)
; #define PG8_WAIT_V(n) asm volatile("s_waitcnt vmcnt(" #n ")" ::: "memory")
; #define PG8_WAIT_L(n) asm volatile("s_waitcnt lgkmcnt(" #n ")" ::: "memory")
; #define PG8_BAR __builtin_amdgcn_s_barrier()
; #define PG8_SCHED __builtin_amdgcn_sched_barrier(0)
; __device__ __forceinline__ float ss_scale(const u64* ss, int row) { return __builtin_amdgcn_rsqf((float)ss[row] * (1.f / 4294967296.f / 1024.f) + EPS); }
; template <class Epi, class Sched, bool ALIGN_EPI = false, bool SP2 = false>
; __device__ __forceinline__ void gemm_phase(PG8_LAS unsigned char* lds, const Gemm g, const Sched& S, const Epi& E, const int tid) {
;     ...
;             PG8_WAIT_V(8); PG8_WAIT_L(0); PG8_BAR; PG8_MMA(1, 0, At, B0); PG8_MMA(1, 1, At, B1); PG8_BAR; PG8_SCHED;
;     __device__ __forceinline__ void operator()(const f32x4 (&acc)[2][2][4][2], const pg8::Unit& u, int wr, int wc, int fr, int fq) const {
;         const int row0 = u.pm * 256 + wr * 64 + fr, col0 = u.pn * 128 + wc * 32 + 8 * fq;
; #pragma unroll
;         for (int ai = 0; ai < 2; ++ai)
; #pragma unroll
;             for (int m = 0; m < 4; ++m) {
;                 const int row = row0 + ai * 128 + m * 16;
;                 float s = ss_scale(ss, row);
	s_waitcnt lgkmcnt(0)
	v_mfma_f32_16x16x32_bf16 v[60:63], v[144:147], v[184:187], v[60:63]
	v_mfma_f32_16x16x32_bf16 v[56:59], v[160:163], v[184:187], v[56:59]
	v_mfma_f32_16x16x32_bf16 v[44:47], v[144:147], v[192:195], v[44:47]
	v_mfma_f32_16x16x32_bf16 v[40:43], v[160:163], v[192:195], v[40:43]
	v_mfma_f32_16x16x32_bf16 v[28:31], v[144:147], v[204:207], v[28:31]
	v_mfma_f32_16x16x32_bf16 v[24:27], v[160:163], v[204:207], v[24:27]
	v_mfma_f32_16x16x32_bf16 v[12:15], v[144:147], v[212:215], v[12:15]
	v_mfma_f32_16x16x32_bf16 v[8:11], v[160:163], v[212:215], v[8:11]
	v_mfma_f32_16x16x32_bf16 v[60:63], v[148:151], v[188:191], v[60:63]
	v_mfma_f32_16x16x32_bf16 v[56:59], v[164:167], v[188:191], v[56:59]
	v_mfma_f32_16x16x32_bf16 v[44:47], v[148:151], v[200:203], v[44:47]
	v_mfma_f32_16x16x32_bf16 v[40:43], v[164:167], v[200:203], v[40:43]
	v_mfma_f32_16x16x32_bf16 v[28:31], v[148:151], v[208:211], v[28:31]
	v_mfma_f32_16x16x32_bf16 v[24:27], v[164:167], v[208:211], v[24:27]
	v_mfma_f32_16x16x32_bf16 v[12:15], v[148:151], v[216:219], v[12:15]
	v_mfma_f32_16x16x32_bf16 v[8:11], v[164:167], v[216:219], v[8:11]
	v_mfma_f32_16x16x32_bf16 v[52:55], v[168:171], v[184:187], v[52:55]
	v_mfma_f32_16x16x32_bf16 v[48:51], v[176:179], v[184:187], v[48:51]
	v_mfma_f32_16x16x32_bf16 v[36:39], v[168:171], v[192:195], v[36:39]
	v_mfma_f32_16x16x32_bf16 v[32:35], v[176:179], v[192:195], v[32:35]
	v_mfma_f32_16x16x32_bf16 v[20:23], v[168:171], v[204:207], v[20:23]
	v_mfma_f32_16x16x32_bf16 v[16:19], v[176:179], v[204:207], v[16:19]
	v_mfma_f32_16x16x32_bf16 v[4:7], v[168:171], v[212:215], v[4:7]
	v_mfma_f32_16x16x32_bf16 v[0:3], v[176:179], v[212:215], v[0:3]
	v_mfma_f32_16x16x32_bf16 v[52:55], v[172:175], v[188:191], v[52:55]
	v_mfma_f32_16x16x32_bf16 v[48:51], v[180:183], v[188:191], v[48:51]
	v_mfma_f32_16x16x32_bf16 v[36:39], v[172:175], v[200:203], v[36:39]
	v_mfma_f32_16x16x32_bf16 v[32:35], v[180:183], v[200:203], v[32:35]
	v_mfma_f32_16x16x32_bf16 v[20:23], v[172:175], v[208:211], v[20:23]
	v_mfma_f32_16x16x32_bf16 v[16:19], v[180:183], v[208:211], v[16:19]
	v_mfma_f32_16x16x32_bf16 v[4:7], v[172:175], v[216:219], v[4:7]
	v_mfma_f32_16x16x32_bf16 v[0:3], v[180:183], v[216:219], v[0:3]
	s_barrier
	s_add_i32 s58, s58, 2
	s_add_u32 s24, s24, 0x100
	s_addc_u32 s25, s25, 0
	s_add_u32 s56, s56, 0x100
	s_addc_u32 s57, s57, 0
	s_cmp_gt_u32 s58, 13
	s_cbranch_scc0 .LBB0_279
	s_setprio 0
	v_lshl_add_u32 v144, s22, 8, v152
	v_mov_b32_e32 v145, 0
	v_lshl_add_u64 v[150:151], v[144:145], 3, s[6:7]
	global_load_dwordx2 v[176:177], v[150:151], off
	global_load_dwordx2 v[178:179], v[150:151], off offset:128
	global_load_dwordx2 v[180:181], v[150:151], off offset:256
	global_load_dwordx2 v[182:183], v[150:151], off offset:384
	global_load_dwordx2 v[184:185], v[150:151], off offset:1024
	global_load_dwordx2 v[186:187], v[150:151], off offset:1152
	global_load_dwordx2 v[188:189], v[150:151], off offset:1280
	global_load_dwordx2 v[190:191], v[150:151], off offset:1408
	v_lshl_or_b32 v148, s53, 7, v153
	v_mul_u32_u24_e32 v146, s52, v144
	v_lshl_add_u32 v146, v148, 1, v146
	v_mov_b32_e32 v147, 0
	v_lshl_add_u64 v[146:147], v[146:147], 0, s[8:9]
	v_mov_b32_e32 v164, 1.0
	v_mov_b32_e32 v165, 1.0
	s_mov_b32 s101, 0
	s_and_b64 vcc, exec, s[12:13]
	s_cbranch_vccz .LBB0_282
	s_barrier

; #define PG8_STAGE(bufoff, gbase, voff) do { _Pragma("unroll") for (int _i = 0; _i < 2; ++_i) \
;         __builtin_amdgcn_global_load_lds((const unsigned*)((const char*)(gbase) + (voff)[_i]), (PG8_LAS unsigned*)(lds + (bufoff) + ldsw + _i * 8192), 16, 0, 0); } while (0)
; #define PG8_LDA(dst, b, h) do { _Pragma("unroll") for (int m = 0; m < 4; ++m) _Pragma("unroll") for (int k = 0; k < 2; ++k) dst[m][k] = *(const PG8_LAS bf16x8*)(lds + PG8_SA(b, h) + aoff + m * 2048 + k * 1024); } while (0)
; #define PG8_LDB(dst, b, h) do { _Pragma("unroll") for (int n = 0; n < 2; ++n) _Pragma("unroll") for (int k = 0; k < 2; ++k) dst[n][k] = *(const PG8_LAS bf16x8*)(lds + PG8_SB(b, h) + boff + n * 2048 + k * 1024); } while (0)
; #define PG8_MMA(ai, bj, At, Bt) do { __builtin_amdgcn_s_setprio(1); _Pragma("unroll") for (int m = 0; m < 4; ++m) _Pragma("unroll") for (int n = 0; n < 2; ++n) _Pragma("unroll") for (int k = 0; k < 2; ++k) \
;         acc[ai][bj][m][n] = __builtin_amdgcn_mfma_f32_16x16x32_bf16(Bt[n][k], At[m][k], acc[ai][bj][m][n], 0, 0, 0); __builtin_amdgcn_s_setprio(0); } while (0)
; #define PG8_WAIT_V(n) asm volatile("s_waitcnt vmcnt(" #n ")" ::: "memory")
; #define PG8_WAIT_L(n) asm volatile("s_waitcnt lgkmcnt(" #n ")" ::: "memory")
; template <class Epi, class Sched, bool ALIGN_EPI = false, bool SP2 = false>
; __device__ __forceinline__ void gemm_phase(PG8_LAS unsigned char* lds, const Gemm g, const Sched& S, const Epi& E, const int tid) {
;     ...
;             const bool last = (t == nt - 2);
;             const char* a1 = cA + (size_t)(t + 1) * kstep;
;             const char* a2 = last ? nA : cA + (size_t)(t + 2) * kstep; const char* b2 = last ? nB : cB + (size_t)(t + 2) * kstep;
;             const char* a3 = a2 + kstep; const char* b3 = b2 + kstep;
;             if (last && has_next) S.a_ready(nxt);
;             if constexpr (SP2) {
;             PG8_LDB(B0, 0, 0); PG8_LDB(B1, 0, 1); PG8_SCHED; PG8_LDA(At, 0, 0); PG8_STAGE(PG8_SA(1, 1), a1 + hstepA, voffA);
;             PG8_WAIT_V(8); PG8_WAIT_L(0); PG8_BAR; PG8_MMA(0, 0, At, B0); PG8_MMA(0, 1, At, B1); PG8_BAR; PG8_SCHED;
;             PG8_LDA(At, 0, 1); PG8_STAGE(PG8_SB(0, 0), b2, voffB); PG8_STAGE(PG8_SB(0, 1), b2 + hstep, voffB); PG8_STAGE(PG8_SA(0, 0), a2, voffA);
;             PG8_WAIT_V(8); PG8_WAIT_L(0); PG8_BAR; PG8_MMA(1, 0, At, B0); PG8_MMA(1, 1, At, B1); PG8_BAR; PG8_SCHED;
.Lsp_1:
	ds_read_b128 v[144:147], v150
	ds_read_b128 v[156:159], v150 offset:1024
	ds_read_b128 v[160:163], v150 offset:2048
	ds_read_b128 v[164:167], v150 offset:3072
	ds_read_b128 v[168:171], v151
	ds_read_b128 v[172:175], v151 offset:1024
	ds_read_b128 v[176:179], v151 offset:2048
	ds_read_b128 v[180:183], v151 offset:3072
	s_add_u32 s24, s22, 0x100
	s_addc_u32 s25, s23, 0
	s_cmp_eq_u32 s59, 40
	s_cselect_b32 s29, s7, s25
	s_cselect_b32 s28, s6, s24
	s_cselect_b32 s27, s21, s58
	s_cselect_b32 s26, s20, s57
	s_add_i32 m0, s38, 0xc000
	ds_read_b128 v[184:187], v152
	ds_read_b128 v[188:191], v152 offset:1024
	ds_read_b128 v[192:195], v152 offset:2048
	ds_read_b128 v[200:203], v152 offset:3072
	ds_read_b128 v[204:207], v152 offset:4096
	ds_read_b128 v[208:211], v152 offset:5120
	ds_read_b128 v[212:215], v152 offset:6144
	ds_read_b128 v[216:219], v152 offset:7168
	global_load_lds_dwordx4 v136, s[22:23]
	s_add_i32 m0, s38, 0xe000
	s_nop 0
	global_load_lds_dwordx4 v138, s[22:23]
	s_waitcnt vmcnt(8)
	s_waitcnt lgkmcnt(0)
	s_barrier
	s_waitcnt lgkmcnt(0)
	v_mfma_f32_16x16x32_bf16 v[124:127], v[144:147], v[184:187], v[124:127]
	v_mfma_f32_16x16x32_bf16 v[120:123], v[160:163], v[184:187], v[120:123]
	v_mfma_f32_16x16x32_bf16 v[108:111], v[144:147], v[192:195], v[108:111]
	v_mfma_f32_16x16x32_bf16 v[104:107], v[160:163], v[192:195], v[104:107]
	v_mfma_f32_16x16x32_bf16 v[92:95], v[144:147], v[204:207], v[92:95]
	v_mfma_f32_16x16x32_bf16 v[88:91], v[160:163], v[204:207], v[88:91]
	v_mfma_f32_16x16x32_bf16 v[76:79], v[144:147], v[212:215], v[76:79]
	v_mfma_f32_16x16x32_bf16 v[72:75], v[160:163], v[212:215], v[72:75]
	v_mfma_f32_16x16x32_bf16 v[124:127], v[156:159], v[188:191], v[124:127]
	v_mfma_f32_16x16x32_bf16 v[120:123], v[164:167], v[188:191], v[120:123]
	v_mfma_f32_16x16x32_bf16 v[108:111], v[156:159], v[200:203], v[108:111]
	v_mfma_f32_16x16x32_bf16 v[104:107], v[164:167], v[200:203], v[104:107]
	v_mfma_f32_16x16x32_bf16 v[92:95], v[156:159], v[208:211], v[92:95]
	v_mfma_f32_16x16x32_bf16 v[88:91], v[164:167], v[208:211], v[88:91]
	v_mfma_f32_16x16x32_bf16 v[76:79], v[156:159], v[216:219], v[76:79]
	v_mfma_f32_16x16x32_bf16 v[72:75], v[164:167], v[216:219], v[72:75]
	v_mfma_f32_16x16x32_bf16 v[116:119], v[168:171], v[184:187], v[116:119]
	v_mfma_f32_16x16x32_bf16 v[112:115], v[176:179], v[184:187], v[112:115]
	v_mfma_f32_16x16x32_bf16 v[100:103], v[168:171], v[192:195], v[100:103]
	v_mfma_f32_16x16x32_bf16 v[96:99], v[176:179], v[192:195], v[96:99]
	v_mfma_f32_16x16x32_bf16 v[84:87], v[168:171], v[204:207], v[84:87]
	v_mfma_f32_16x16x32_bf16 v[80:83], v[176:179], v[204:207], v[80:83]
	v_mfma_f32_16x16x32_bf16 v[68:71], v[168:171], v[212:215], v[68:71]
	v_mfma_f32_16x16x32_bf16 v[64:67], v[176:179], v[212:215], v[64:67]
	v_mfma_f32_16x16x32_bf16 v[116:119], v[172:175], v[188:191], v[116:119]
	v_mfma_f32_16x16x32_bf16 v[112:115], v[180:183], v[188:191], v[112:115]
	v_mfma_f32_16x16x32_bf16 v[100:103], v[172:175], v[200:203], v[100:103]
	v_mfma_f32_16x16x32_bf16 v[96:99], v[180:183], v[200:203], v[96:99]
	v_mfma_f32_16x16x32_bf16 v[84:87], v[172:175], v[208:211], v[84:87]
	v_mfma_f32_16x16x32_bf16 v[80:83], v[180:183], v[208:211], v[80:83]
	v_mfma_f32_16x16x32_bf16 v[68:71], v[172:175], v[216:219], v[68:71]
	v_mfma_f32_16x16x32_bf16 v[64:67], v[180:183], v[216:219], v[64:67]
	s_barrier
	s_mov_b32 m0, s34
	s_mov_b64 s[98:99], s[26:27]
	s_add_u32 s22, s26, 0xb0000
	ds_read_b128 v[184:187], v152 offset:16384
	ds_read_b128 v[188:191], v152 offset:17408
	ds_read_b128 v[192:195], v152 offset:18432
	ds_read_b128 v[200:203], v152 offset:19456
	ds_read_b128 v[204:207], v152 offset:20480
	ds_read_b128 v[208:211], v152 offset:21504
	ds_read_b128 v[212:215], v152 offset:22528
	ds_read_b128 v[216:219], v152 offset:23552
	global_load_lds_dwordx4 v130, s[26:27]
	s_mov_b32 m0, s35
	s_addc_u32 s23, s27, 0
	global_load_lds_dwordx4 v134, s[26:27]
	s_mov_b32 m0, s36
	s_nop 0
	global_load_lds_dwordx4 v130, s[22:23]
	s_mov_b32 m0, s37
	s_nop 0
	global_load_lds_dwordx4 v134, s[22:23]
	s_mov_b64 s[100:101], s[28:29]
	s_mov_b32 m0, s38
	s_nop 0
	global_load_lds_dwordx4 v128, s[28:29]
	s_mov_b32 m0, s39
	s_nop 0
	global_load_lds_dwordx4 v132, s[28:29]
	s_waitcnt vmcnt(8)
	s_waitcnt lgkmcnt(0)
	s_barrier
	s_waitcnt lgkmcnt(0)
	v_mfma_f32_16x16x32_bf16 v[60:63], v[144:147], v[184:187], v[60:63]
	v_mfma_f32_16x16x32_bf16 v[56:59], v[160:163], v[184:187], v[56:59]
	v_mfma_f32_16x16x32_bf16 v[44:47], v[144:147], v[192:195], v[44:47]
	v_mfma_f32_16x16x32_bf16 v[40:43], v[160:163], v[192:195], v[40:43]
	v_mfma_f32_16x16x32_bf16 v[28:31], v[144:147], v[204:207], v[28:31]
	v_mfma_f32_16x16x32_bf16 v[24:27], v[160:163], v[204:207], v[24:27]
	v_mfma_f32_16x16x32_bf16 v[12:15], v[144:147], v[212:215], v[12:15]
	v_mfma_f32_16x16x32_bf16 v[8:11], v[160:163], v[212:215], v[8:11]
	v_mfma_f32_16x16x32_bf16 v[60:63], v[156:159], v[188:191], v[60:63]
	v_mfma_f32_16x16x32_bf16 v[56:59], v[164:167], v[188:191], v[56:59]
	v_mfma_f32_16x16x32_bf16 v[44:47], v[156:159], v[200:203], v[44:47]
	v_mfma_f32_16x16x32_bf16 v[40:43], v[164:167], v[200:203], v[40:43]
	v_mfma_f32_16x16x32_bf16 v[28:31], v[156:159], v[208:211], v[28:31]
	v_mfma_f32_16x16x32_bf16 v[24:27], v[164:167], v[208:211], v[24:27]
	v_mfma_f32_16x16x32_bf16 v[12:15], v[156:159], v[216:219], v[12:15]
	v_mfma_f32_16x16x32_bf16 v[8:11], v[164:167], v[216:219], v[8:11]
	v_mfma_f32_16x16x32_bf16 v[52:55], v[168:171], v[184:187], v[52:55]
	v_mfma_f32_16x16x32_bf16 v[48:51], v[176:179], v[184:187], v[48:51]
	v_mfma_f32_16x16x32_bf16 v[36:39], v[168:171], v[192:195], v[36:39]
	v_mfma_f32_16x16x32_bf16 v[32:35], v[176:179], v[192:195], v[32:35]
	v_mfma_f32_16x16x32_bf16 v[20:23], v[168:171], v[204:207], v[20:23]
	v_mfma_f32_16x16x32_bf16 v[16:19], v[176:179], v[204:207], v[16:19]
	v_mfma_f32_16x16x32_bf16 v[4:7], v[168:171], v[212:215], v[4:7]
	v_mfma_f32_16x16x32_bf16 v[0:3], v[176:179], v[212:215], v[0:3]
	v_mfma_f32_16x16x32_bf16 v[52:55], v[172:175], v[188:191], v[52:55]
	v_mfma_f32_16x16x32_bf16 v[48:51], v[180:183], v[188:191], v[48:51]
	v_mfma_f32_16x16x32_bf16 v[36:39], v[172:175], v[200:203], v[36:39]
	v_mfma_f32_16x16x32_bf16 v[32:35], v[180:183], v[200:203], v[32:35]
	v_mfma_f32_16x16x32_bf16 v[20:23], v[172:175], v[208:211], v[20:23]
	v_mfma_f32_16x16x32_bf16 v[16:19], v[180:183], v[208:211], v[16:19]
	v_mfma_f32_16x16x32_bf16 v[4:7], v[172:175], v[216:219], v[4:7]
	v_mfma_f32_16x16x32_bf16 v[0:3], v[180:183], v[216:219], v[0:3]
	s_barrier
; #define PG8_STAGE(bufoff, gbase, voff) do { _Pragma("unroll") for (int _i = 0; _i < 2; ++_i) \
;         __builtin_amdgcn_global_load_lds((const unsigned*)((const char*)(gbase) + (voff)[_i]), (PG8_LAS unsigned*)(lds + (bufoff) + ldsw + _i * 8192), 16, 0, 0); } while (0)
; #define PG8_LDA(dst, b, h) do { _Pragma("unroll") for (int m = 0; m < 4; ++m) _Pragma("unroll") for (int k = 0; k < 2; ++k) dst[m][k] = *(const PG8_LAS bf16x8*)(lds + PG8_SA(b, h) + aoff + m * 2048 + k * 1024); } while (0)
; #define PG8_LDB(dst, b, h) do { _Pragma("unroll") for (int n = 0; n < 2; ++n) _Pragma("unroll") for (int k = 0; k < 2; ++k) dst[n][k] = *(const PG8_LAS bf16x8*)(lds + PG8_SB(b, h) + boff + n * 2048 + k * 1024); } while (0)
; #define PG8_MMA(ai, bj, At, Bt) do { __builtin_amdgcn_s_setprio(1); _Pragma("unroll") for (int m = 0; m < 4; ++m) _Pragma("unroll") for (int n = 0; n < 2; ++n) _Pragma("unroll") for (int k = 0; k < 2; ++k) \
;         acc[ai][bj][m][n] = __builtin_amdgcn_mfma_f32_16x16x32_bf16(Bt[n][k], At[m][k], acc[ai][bj][m][n], 0, 0, 0); __builtin_amdgcn_s_setprio(0); } while (0)
; #define PG8_WAIT_V(n) asm volatile("s_waitcnt vmcnt(" #n ")" ::: "memory")
; #define PG8_WAIT_L(n) asm volatile("s_waitcnt lgkmcnt(" #n ")" ::: "memory")
; #define PG8_BAR __builtin_amdgcn_s_barrier()
; #define PG8_SCHED __builtin_amdgcn_sched_barrier(0)
; template <class Epi, class Sched, bool ALIGN_EPI = false, bool SP2 = false>
; __device__ __forceinline__ void gemm_phase(PG8_LAS unsigned char* lds, const Gemm g, const Sched& S, const Epi& E, const int tid) {
;     ...
;             PG8_LDB(B0, 1, 0); PG8_LDB(B1, 1, 1); PG8_SCHED; PG8_LDA(At, 1, 0); PG8_STAGE(PG8_SA(0, 1), a2 + hstepA, voffA);
;             PG8_WAIT_V(8); PG8_WAIT_L(0); PG8_BAR; PG8_MMA(0, 0, At, B0); PG8_MMA(0, 1, At, B1); PG8_BAR; PG8_SCHED;
;             PG8_LDA(At, 1, 1); PG8_STAGE(PG8_SB(1, 0), b3, voffB); PG8_STAGE(PG8_SB(1, 1), b3 + hstep, voffB); PG8_STAGE(PG8_SA(1, 0), a3, voffA);
;             PG8_WAIT_V(8); PG8_WAIT_L(0); PG8_BAR; PG8_MMA(1, 0, At, B0); PG8_MMA(1, 1, At, B1); PG8_BAR; PG8_SCHED;
	ds_read_b128 v[144:147], v153
	ds_read_b128 v[156:159], v153 offset:1024
	ds_read_b128 v[160:163], v153 offset:2048
	ds_read_b128 v[164:167], v153 offset:3072
	ds_read_b128 v[168:171], v154
	ds_read_b128 v[172:175], v154 offset:1024
	ds_read_b128 v[176:179], v154 offset:2048
	ds_read_b128 v[180:183], v154 offset:3072
	s_add_u32 s22, s28, 0xb0000
	s_addc_u32 s23, s29, 0
	s_mov_b32 m0, s40
	ds_read_b128 v[184:187], v152 offset:32768
	ds_read_b128 v[188:191], v152 offset:33792
	ds_read_b128 v[192:195], v152 offset:34816
	ds_read_b128 v[200:203], v152 offset:35840
	ds_read_b128 v[204:207], v152 offset:36864
	ds_read_b128 v[208:211], v152 offset:37888
	ds_read_b128 v[212:215], v152 offset:38912
	ds_read_b128 v[216:219], v152 offset:39936
	global_load_lds_dwordx4 v128, s[22:23]
	s_mov_b32 m0, s41
	s_nop 0
	global_load_lds_dwordx4 v132, s[22:23]
	s_waitcnt vmcnt(8)
	s_waitcnt lgkmcnt(0)
	s_barrier
	s_waitcnt lgkmcnt(0)
	v_mfma_f32_16x16x32_bf16 v[124:127], v[144:147], v[184:187], v[124:127]
	v_mfma_f32_16x16x32_bf16 v[120:123], v[160:163], v[184:187], v[120:123]
	v_mfma_f32_16x16x32_bf16 v[108:111], v[144:147], v[192:195], v[108:111]
	v_mfma_f32_16x16x32_bf16 v[104:107], v[160:163], v[192:195], v[104:107]
	v_mfma_f32_16x16x32_bf16 v[92:95], v[144:147], v[204:207], v[92:95]
	v_mfma_f32_16x16x32_bf16 v[88:91], v[160:163], v[204:207], v[88:91]
	v_mfma_f32_16x16x32_bf16 v[76:79], v[144:147], v[212:215], v[76:79]
	v_mfma_f32_16x16x32_bf16 v[72:75], v[160:163], v[212:215], v[72:75]
	v_mfma_f32_16x16x32_bf16 v[124:127], v[156:159], v[188:191], v[124:127]
	v_mfma_f32_16x16x32_bf16 v[120:123], v[164:167], v[188:191], v[120:123]
	v_mfma_f32_16x16x32_bf16 v[108:111], v[156:159], v[200:203], v[108:111]
	v_mfma_f32_16x16x32_bf16 v[104:107], v[164:167], v[200:203], v[104:107]
	v_mfma_f32_16x16x32_bf16 v[92:95], v[156:159], v[208:211], v[92:95]
	v_mfma_f32_16x16x32_bf16 v[88:91], v[164:167], v[208:211], v[88:91]
	v_mfma_f32_16x16x32_bf16 v[76:79], v[156:159], v[216:219], v[76:79]
	v_mfma_f32_16x16x32_bf16 v[72:75], v[164:167], v[216:219], v[72:75]
	v_mfma_f32_16x16x32_bf16 v[116:119], v[168:171], v[184:187], v[116:119]
	v_mfma_f32_16x16x32_bf16 v[112:115], v[176:179], v[184:187], v[112:115]
	v_mfma_f32_16x16x32_bf16 v[100:103], v[168:171], v[192:195], v[100:103]
	v_mfma_f32_16x16x32_bf16 v[96:99], v[176:179], v[192:195], v[96:99]
	v_mfma_f32_16x16x32_bf16 v[84:87], v[168:171], v[204:207], v[84:87]
	v_mfma_f32_16x16x32_bf16 v[80:83], v[176:179], v[204:207], v[80:83]
	v_mfma_f32_16x16x32_bf16 v[68:71], v[168:171], v[212:215], v[68:71]
	v_mfma_f32_16x16x32_bf16 v[64:67], v[176:179], v[212:215], v[64:67]
	v_mfma_f32_16x16x32_bf16 v[116:119], v[172:175], v[188:191], v[116:119]
	v_mfma_f32_16x16x32_bf16 v[112:115], v[180:183], v[188:191], v[112:115]
	v_mfma_f32_16x16x32_bf16 v[100:103], v[172:175], v[200:203], v[100:103]
	v_mfma_f32_16x16x32_bf16 v[96:99], v[180:183], v[200:203], v[96:99]
	v_mfma_f32_16x16x32_bf16 v[84:87], v[172:175], v[208:211], v[84:87]
	v_mfma_f32_16x16x32_bf16 v[80:83], v[180:183], v[208:211], v[80:83]
	v_mfma_f32_16x16x32_bf16 v[68:71], v[172:175], v[216:219], v[68:71]
	v_mfma_f32_16x16x32_bf16 v[64:67], v[180:183], v[216:219], v[64:67]
	s_barrier
	s_mov_b32 m0, s44
	s_add_u32 s98, s98, s14
	s_addc_u32 s99, s99, s15
	s_add_u32 s22, s26, 0xb0080
	ds_read_b128 v[184:187], v152 offset:49152
	ds_read_b128 v[188:191], v152 offset:50176
	ds_read_b128 v[192:195], v152 offset:51200
	ds_read_b128 v[200:203], v152 offset:52224
	ds_read_b128 v[204:207], v152 offset:53248
	ds_read_b128 v[208:211], v152 offset:54272
	ds_read_b128 v[212:215], v152 offset:55296
	ds_read_b128 v[216:219], v152 offset:56320
	global_load_lds_dwordx4 v130, s[98:99]
	s_mov_b32 m0, s45
	s_addc_u32 s23, s27, 0
	global_load_lds_dwordx4 v134, s[98:99]
	s_mov_b32 m0, s48
	s_nop 0
	global_load_lds_dwordx4 v130, s[22:23]
	s_mov_b32 m0, s49
	s_nop 0
	global_load_lds_dwordx4 v134, s[22:23]
	s_add_u32 s100, s100, s14
	s_addc_u32 s101, s101, s15
	s_mov_b32 m0, s46
	s_nop 0
	global_load_lds_dwordx4 v128, s[100:101]
	s_mov_b32 m0, s47
	s_nop 0
	global_load_lds_dwordx4 v132, s[100:101]
	s_waitcnt vmcnt(8)
	s_waitcnt lgkmcnt(0)
	s_barrier
	s_waitcnt lgkmcnt(0)
	v_mfma_f32_16x16x32_bf16 v[60:63], v[144:147], v[184:187], v[60:63]
	v_mfma_f32_16x16x32_bf16 v[56:59], v[160:163], v[184:187], v[56:59]
	v_mfma_f32_16x16x32_bf16 v[44:47], v[144:147], v[192:195], v[44:47]
	v_mfma_f32_16x16x32_bf16 v[40:43], v[160:163], v[192:195], v[40:43]
	v_mfma_f32_16x16x32_bf16 v[28:31], v[144:147], v[204:207], v[28:31]
	v_mfma_f32_16x16x32_bf16 v[24:27], v[160:163], v[204:207], v[24:27]
	v_mfma_f32_16x16x32_bf16 v[12:15], v[144:147], v[212:215], v[12:15]
	v_mfma_f32_16x16x32_bf16 v[8:11], v[160:163], v[212:215], v[8:11]
	v_mfma_f32_16x16x32_bf16 v[60:63], v[156:159], v[188:191], v[60:63]
	v_mfma_f32_16x16x32_bf16 v[56:59], v[164:167], v[188:191], v[56:59]
	v_mfma_f32_16x16x32_bf16 v[44:47], v[156:159], v[200:203], v[44:47]
	v_mfma_f32_16x16x32_bf16 v[40:43], v[164:167], v[200:203], v[40:43]
	v_mfma_f32_16x16x32_bf16 v[28:31], v[156:159], v[208:211], v[28:31]
	v_mfma_f32_16x16x32_bf16 v[24:27], v[164:167], v[208:211], v[24:27]
	v_mfma_f32_16x16x32_bf16 v[12:15], v[156:159], v[216:219], v[12:15]
	v_mfma_f32_16x16x32_bf16 v[8:11], v[164:167], v[216:219], v[8:11]
	v_mfma_f32_16x16x32_bf16 v[52:55], v[168:171], v[184:187], v[52:55]
	v_mfma_f32_16x16x32_bf16 v[48:51], v[176:179], v[184:187], v[48:51]
	v_mfma_f32_16x16x32_bf16 v[36:39], v[168:171], v[192:195], v[36:39]
	v_mfma_f32_16x16x32_bf16 v[32:35], v[176:179], v[192:195], v[32:35]
	v_mfma_f32_16x16x32_bf16 v[20:23], v[168:171], v[204:207], v[20:23]
	v_mfma_f32_16x16x32_bf16 v[16:19], v[176:179], v[204:207], v[16:19]
	v_mfma_f32_16x16x32_bf16 v[4:7], v[168:171], v[212:215], v[4:7]
	v_mfma_f32_16x16x32_bf16 v[0:3], v[176:179], v[212:215], v[0:3]
	v_mfma_f32_16x16x32_bf16 v[52:55], v[172:175], v[188:191], v[52:55]
	v_mfma_f32_16x16x32_bf16 v[48:51], v[180:183], v[188:191], v[48:51]
	v_mfma_f32_16x16x32_bf16 v[36:39], v[172:175], v[200:203], v[36:39]
	v_mfma_f32_16x16x32_bf16 v[32:35], v[180:183], v[200:203], v[32:35]
	v_mfma_f32_16x16x32_bf16 v[20:23], v[172:175], v[208:211], v[20:23]
	v_mfma_f32_16x16x32_bf16 v[16:19], v[180:183], v[208:211], v[16:19]
	v_mfma_f32_16x16x32_bf16 v[4:7], v[172:175], v[216:219], v[4:7]
	v_mfma_f32_16x16x32_bf16 v[0:3], v[180:183], v[216:219], v[0:3]
	s_barrier
	s_add_i32 s59, s59, 2
	s_add_u32 s57, s57, 0x100
	s_addc_u32 s58, s58, 0
	s_cmp_gt_u32 s59, 41
	s_mov_b64 s[22:23], s[24:25]
	s_cbranch_scc0 .LBB0_353
	s_setprio 0
	s_and_b64 vcc, exec, s[16:17]
	s_cbranch_vccnz .LBB0_357
	s_andn2_b64 vcc, exec, s[18:19]
	s_cbranch_vccz .LBB0_358

; #define PG8_STAGE(bufoff, gbase, voff) do { _Pragma("unroll") for (int _i = 0; _i < 2; ++_i) \
;         __builtin_amdgcn_global_load_lds((const unsigned*)((const char*)(gbase) + (voff)[_i]), (PG8_LAS unsigned*)(lds + (bufoff) + ldsw + _i * 8192), 16, 0, 0); } while (0)
; #define PG8_LDA(dst, b, h) do { _Pragma("unroll") for (int m = 0; m < 4; ++m) _Pragma("unroll") for (int k = 0; k < 2; ++k) dst[m][k] = *(const PG8_LAS bf16x8*)(lds + PG8_SA(b, h) + aoff + m * 2048 + k * 1024); } while (0)
; #define PG8_LDB(dst, b, h) do { _Pragma("unroll") for (int n = 0; n < 2; ++n) _Pragma("unroll") for (int k = 0; k < 2; ++k) dst[n][k] = *(const PG8_LAS bf16x8*)(lds + PG8_SB(b, h) + boff + n * 2048 + k * 1024); } while (0)
; #define PG8_MMA(ai, bj, At, Bt) do { __builtin_amdgcn_s_setprio(1); _Pragma("unroll") for (int m = 0; m < 4; ++m) _Pragma("unroll") for (int n = 0; n < 2; ++n) _Pragma("unroll") for (int k = 0; k < 2; ++k) \
;         acc[ai][bj][m][n] = __builtin_amdgcn_mfma_f32_16x16x32_bf16(Bt[n][k], At[m][k], acc[ai][bj][m][n], 0, 0, 0); __builtin_amdgcn_s_setprio(0); } while (0)
; #define PG8_WAIT_V(n) asm volatile("s_waitcnt vmcnt(" #n ")" ::: "memory")
; #define PG8_WAIT_L(n) asm volatile("s_waitcnt lgkmcnt(" #n ")" ::: "memory")
; template <class Epi, class Sched, bool ALIGN_EPI = false, bool SP2 = false>
; __device__ __forceinline__ void gemm_phase(PG8_LAS unsigned char* lds, const Gemm g, const Sched& S, const Epi& E, const int tid) {
;     ...
;             const bool last = (t == nt - 2);
;             const char* a1 = cA + (size_t)(t + 1) * kstep;
;             const char* a2 = last ? nA : cA + (size_t)(t + 2) * kstep; const char* b2 = last ? nB : cB + (size_t)(t + 2) * kstep;
;             const char* a3 = a2 + kstep; const char* b3 = b2 + kstep;
;             if (last && has_next) S.a_ready(nxt);
;             if constexpr (SP2) {
;             PG8_LDB(B0, 0, 0); PG8_LDB(B1, 0, 1); PG8_SCHED; PG8_LDA(At, 0, 0); PG8_STAGE(PG8_SA(1, 1), a1 + hstepA, voffA);
;             PG8_WAIT_V(8); PG8_WAIT_L(0); PG8_BAR; PG8_MMA(0, 0, At, B0); PG8_MMA(0, 1, At, B1); PG8_BAR; PG8_SCHED;
;             PG8_LDA(At, 0, 1); PG8_STAGE(PG8_SB(0, 0), b2, voffB); PG8_STAGE(PG8_SB(0, 1), b2 + hstep, voffB); PG8_STAGE(PG8_SA(0, 0), a2, voffA);
;             PG8_WAIT_V(8); PG8_WAIT_L(0); PG8_BAR; PG8_MMA(1, 0, At, B0); PG8_MMA(1, 1, At, B1); PG8_BAR; PG8_SCHED;
.Lsp_2:
	ds_read_b128 v[152:155], v174
	ds_read_b128 v[156:159], v174 offset:1024
	ds_read_b128 v[160:163], v174 offset:2048
	ds_read_b128 v[164:167], v174 offset:3072
	ds_read_b128 v[168:171], v175
	ds_read_b128 v[182:185], v175 offset:1024
	ds_read_b128 v[186:189], v175 offset:2048
	ds_read_b128 v[190:193], v175 offset:3072
	s_add_u32 s34, s30, 0xfffc0080
	s_addc_u32 s35, s31, -1
	s_cmp_eq_u32 s39, 12
	s_cselect_b32 s37, s0, s35
	s_cselect_b32 s36, s21, s34
	s_cselect_b32 s35, s23, s38
	s_cselect_b32 s34, s25, s33
	s_add_i32 m0, s57, 0xc000
	ds_read_b128 v[194:197], v176
	ds_read_b128 v[200:203], v176 offset:1024
	ds_read_b128 v[204:207], v176 offset:2048
	ds_read_b128 v[208:211], v176 offset:3072
	ds_read_b128 v[212:215], v176 offset:4096
	ds_read_b128 v[216:219], v176 offset:5120
	ds_read_b128 v[220:223], v176 offset:6144
	ds_read_b128 v[224:227], v176 offset:7168
	global_load_lds_dwordx4 v142, s[30:31]
	s_add_i32 m0, s57, 0xe000
	s_nop 0
	global_load_lds_dwordx4 v144, s[30:31]
	s_waitcnt vmcnt(8)
	s_waitcnt lgkmcnt(0)
	s_barrier
	s_waitcnt lgkmcnt(0)
	v_mfma_f32_16x16x32_bf16 v[124:127], v[152:155], v[194:197], v[124:127]
	v_mfma_f32_16x16x32_bf16 v[120:123], v[160:163], v[194:197], v[120:123]
	v_mfma_f32_16x16x32_bf16 v[108:111], v[152:155], v[204:207], v[108:111]
	v_mfma_f32_16x16x32_bf16 v[104:107], v[160:163], v[204:207], v[104:107]
	v_mfma_f32_16x16x32_bf16 v[92:95], v[152:155], v[212:215], v[92:95]
	v_mfma_f32_16x16x32_bf16 v[88:91], v[160:163], v[212:215], v[88:91]
	v_mfma_f32_16x16x32_bf16 v[76:79], v[152:155], v[220:223], v[76:79]
	v_mfma_f32_16x16x32_bf16 v[72:75], v[160:163], v[220:223], v[72:75]
	v_mfma_f32_16x16x32_bf16 v[124:127], v[156:159], v[200:203], v[124:127]
	v_mfma_f32_16x16x32_bf16 v[120:123], v[164:167], v[200:203], v[120:123]
	v_mfma_f32_16x16x32_bf16 v[108:111], v[156:159], v[208:211], v[108:111]
	v_mfma_f32_16x16x32_bf16 v[104:107], v[164:167], v[208:211], v[104:107]
	v_mfma_f32_16x16x32_bf16 v[92:95], v[156:159], v[216:219], v[92:95]
	v_mfma_f32_16x16x32_bf16 v[88:91], v[164:167], v[216:219], v[88:91]
	v_mfma_f32_16x16x32_bf16 v[76:79], v[156:159], v[224:227], v[76:79]
	v_mfma_f32_16x16x32_bf16 v[72:75], v[164:167], v[224:227], v[72:75]
	v_mfma_f32_16x16x32_bf16 v[116:119], v[168:171], v[194:197], v[116:119]
	v_mfma_f32_16x16x32_bf16 v[112:115], v[186:189], v[194:197], v[112:115]
	v_mfma_f32_16x16x32_bf16 v[100:103], v[168:171], v[204:207], v[100:103]
	v_mfma_f32_16x16x32_bf16 v[96:99], v[186:189], v[204:207], v[96:99]
	v_mfma_f32_16x16x32_bf16 v[84:87], v[168:171], v[212:215], v[84:87]
	v_mfma_f32_16x16x32_bf16 v[80:83], v[186:189], v[212:215], v[80:83]
	v_mfma_f32_16x16x32_bf16 v[68:71], v[168:171], v[220:223], v[68:71]
	v_mfma_f32_16x16x32_bf16 v[64:67], v[186:189], v[220:223], v[64:67]
	v_mfma_f32_16x16x32_bf16 v[116:119], v[182:185], v[200:203], v[116:119]
	v_mfma_f32_16x16x32_bf16 v[112:115], v[190:193], v[200:203], v[112:115]
	v_mfma_f32_16x16x32_bf16 v[100:103], v[182:185], v[208:211], v[100:103]
	v_mfma_f32_16x16x32_bf16 v[96:99], v[190:193], v[208:211], v[96:99]
	v_mfma_f32_16x16x32_bf16 v[84:87], v[182:185], v[216:219], v[84:87]
	v_mfma_f32_16x16x32_bf16 v[80:83], v[190:193], v[216:219], v[80:83]
	v_mfma_f32_16x16x32_bf16 v[68:71], v[182:185], v[224:227], v[68:71]
	v_mfma_f32_16x16x32_bf16 v[64:67], v[190:193], v[224:227], v[64:67]
	s_barrier
	s_mov_b32 m0, s53
	s_mov_b64 s[98:99], s[34:35]
	s_add_u32 s44, s34, 0x40000
	ds_read_b128 v[194:197], v176 offset:16384
	ds_read_b128 v[200:203], v176 offset:17408
	ds_read_b128 v[204:207], v176 offset:18432
	ds_read_b128 v[208:211], v176 offset:19456
	ds_read_b128 v[212:215], v176 offset:20480
	ds_read_b128 v[216:219], v176 offset:21504
	ds_read_b128 v[220:223], v176 offset:22528
	ds_read_b128 v[224:227], v176 offset:23552
	global_load_lds_dwordx4 v132, s[34:35]
	s_mov_b32 m0, s54
	s_addc_u32 s45, s35, 0
	global_load_lds_dwordx4 v128, s[34:35]
	s_mov_b32 m0, s55
	s_nop 0
	global_load_lds_dwordx4 v132, s[44:45]
	s_mov_b32 m0, s56
	s_nop 0
	global_load_lds_dwordx4 v128, s[44:45]
	s_mov_b64 s[100:101], s[36:37]
	s_mov_b32 m0, s57
	s_nop 0
	global_load_lds_dwordx4 v134, s[36:37]
	s_mov_b32 m0, s58
	s_nop 0
	global_load_lds_dwordx4 v130, s[36:37]
	s_waitcnt vmcnt(8)
	s_waitcnt lgkmcnt(0)
	s_barrier
	s_waitcnt lgkmcnt(0)
	v_mfma_f32_16x16x32_bf16 v[60:63], v[152:155], v[194:197], v[60:63]
	v_mfma_f32_16x16x32_bf16 v[56:59], v[160:163], v[194:197], v[56:59]
	v_mfma_f32_16x16x32_bf16 v[44:47], v[152:155], v[204:207], v[44:47]
	v_mfma_f32_16x16x32_bf16 v[40:43], v[160:163], v[204:207], v[40:43]
	v_mfma_f32_16x16x32_bf16 v[28:31], v[152:155], v[212:215], v[28:31]
	v_mfma_f32_16x16x32_bf16 v[24:27], v[160:163], v[212:215], v[24:27]
	v_mfma_f32_16x16x32_bf16 v[12:15], v[152:155], v[220:223], v[12:15]
	v_mfma_f32_16x16x32_bf16 v[8:11], v[160:163], v[220:223], v[8:11]
	v_mfma_f32_16x16x32_bf16 v[60:63], v[156:159], v[200:203], v[60:63]
	v_mfma_f32_16x16x32_bf16 v[56:59], v[164:167], v[200:203], v[56:59]
	v_mfma_f32_16x16x32_bf16 v[44:47], v[156:159], v[208:211], v[44:47]
	v_mfma_f32_16x16x32_bf16 v[40:43], v[164:167], v[208:211], v[40:43]
	v_mfma_f32_16x16x32_bf16 v[28:31], v[156:159], v[216:219], v[28:31]
	v_mfma_f32_16x16x32_bf16 v[24:27], v[164:167], v[216:219], v[24:27]
	v_mfma_f32_16x16x32_bf16 v[12:15], v[156:159], v[224:227], v[12:15]
	v_mfma_f32_16x16x32_bf16 v[8:11], v[164:167], v[224:227], v[8:11]
	v_mfma_f32_16x16x32_bf16 v[52:55], v[168:171], v[194:197], v[52:55]
	v_mfma_f32_16x16x32_bf16 v[48:51], v[186:189], v[194:197], v[48:51]
	v_mfma_f32_16x16x32_bf16 v[36:39], v[168:171], v[204:207], v[36:39]
	v_mfma_f32_16x16x32_bf16 v[32:35], v[186:189], v[204:207], v[32:35]
	v_mfma_f32_16x16x32_bf16 v[20:23], v[168:171], v[212:215], v[20:23]
	v_mfma_f32_16x16x32_bf16 v[16:19], v[186:189], v[212:215], v[16:19]
	v_mfma_f32_16x16x32_bf16 v[4:7], v[168:171], v[220:223], v[4:7]
	v_mfma_f32_16x16x32_bf16 v[0:3], v[186:189], v[220:223], v[0:3]
	v_mfma_f32_16x16x32_bf16 v[52:55], v[182:185], v[200:203], v[52:55]
	v_mfma_f32_16x16x32_bf16 v[48:51], v[190:193], v[200:203], v[48:51]
	v_mfma_f32_16x16x32_bf16 v[36:39], v[182:185], v[208:211], v[36:39]
	v_mfma_f32_16x16x32_bf16 v[32:35], v[190:193], v[208:211], v[32:35]
	v_mfma_f32_16x16x32_bf16 v[20:23], v[182:185], v[216:219], v[20:23]
	v_mfma_f32_16x16x32_bf16 v[16:19], v[190:193], v[216:219], v[16:19]
	v_mfma_f32_16x16x32_bf16 v[4:7], v[182:185], v[224:227], v[4:7]
	v_mfma_f32_16x16x32_bf16 v[0:3], v[190:193], v[224:227], v[0:3]
	s_barrier
; #define PG8_STAGE(bufoff, gbase, voff) do { _Pragma("unroll") for (int _i = 0; _i < 2; ++_i) \
;         __builtin_amdgcn_global_load_lds((const unsigned*)((const char*)(gbase) + (voff)[_i]), (PG8_LAS unsigned*)(lds + (bufoff) + ldsw + _i * 8192), 16, 0, 0); } while (0)
; #define PG8_LDA(dst, b, h) do { _Pragma("unroll") for (int m = 0; m < 4; ++m) _Pragma("unroll") for (int k = 0; k < 2; ++k) dst[m][k] = *(const PG8_LAS bf16x8*)(lds + PG8_SA(b, h) + aoff + m * 2048 + k * 1024); } while (0)
; #define PG8_LDB(dst, b, h) do { _Pragma("unroll") for (int n = 0; n < 2; ++n) _Pragma("unroll") for (int k = 0; k < 2; ++k) dst[n][k] = *(const PG8_LAS bf16x8*)(lds + PG8_SB(b, h) + boff + n * 2048 + k * 1024); } while (0)
; #define PG8_MMA(ai, bj, At, Bt) do { __builtin_amdgcn_s_setprio(1); _Pragma("unroll") for (int m = 0; m < 4; ++m) _Pragma("unroll") for (int n = 0; n < 2; ++n) _Pragma("unroll") for (int k = 0; k < 2; ++k) \
;         acc[ai][bj][m][n] = __builtin_amdgcn_mfma_f32_16x16x32_bf16(Bt[n][k], At[m][k], acc[ai][bj][m][n], 0, 0, 0); __builtin_amdgcn_s_setprio(0); } while (0)
; #define PG8_WAIT_V(n) asm volatile("s_waitcnt vmcnt(" #n ")" ::: "memory")
; #define PG8_WAIT_L(n) asm volatile("s_waitcnt lgkmcnt(" #n ")" ::: "memory")
; #define PG8_BAR __builtin_amdgcn_s_barrier()
; #define PG8_SCHED __builtin_amdgcn_sched_barrier(0)
; template <class Epi, class Sched, bool ALIGN_EPI = false, bool SP2 = false>
; __device__ __forceinline__ void gemm_phase(PG8_LAS unsigned char* lds, const Gemm g, const Sched& S, const Epi& E, const int tid) {
;     ...
;             PG8_LDB(B0, 1, 0); PG8_LDB(B1, 1, 1); PG8_SCHED; PG8_LDA(At, 1, 0); PG8_STAGE(PG8_SA(0, 1), a2 + hstepA, voffA);
;             PG8_WAIT_V(8); PG8_WAIT_L(0); PG8_BAR; PG8_MMA(0, 0, At, B0); PG8_MMA(0, 1, At, B1); PG8_BAR; PG8_SCHED;
;             PG8_LDA(At, 1, 1); PG8_STAGE(PG8_SB(1, 0), b3, voffB); PG8_STAGE(PG8_SB(1, 1), b3 + hstep, voffB); PG8_STAGE(PG8_SA(1, 0), a3, voffA);
;             PG8_WAIT_V(8); PG8_WAIT_L(0); PG8_BAR; PG8_MMA(1, 0, At, B0); PG8_MMA(1, 1, At, B1); PG8_BAR; PG8_SCHED;
	ds_read_b128 v[152:155], v177
	ds_read_b128 v[156:159], v177 offset:1024
	ds_read_b128 v[160:163], v177 offset:2048
	ds_read_b128 v[164:167], v177 offset:3072
	ds_read_b128 v[168:171], v178
	ds_read_b128 v[182:185], v178 offset:1024
	ds_read_b128 v[186:189], v178 offset:2048
	ds_read_b128 v[190:193], v178 offset:3072
	s_add_u32 s36, s36, 0x40000
	s_addc_u32 s37, s37, 0
	s_mov_b32 m0, s59
	ds_read_b128 v[194:197], v176 offset:32768
	ds_read_b128 v[200:203], v176 offset:33792
	ds_read_b128 v[204:207], v176 offset:34816
	ds_read_b128 v[208:211], v176 offset:35840
	ds_read_b128 v[212:215], v176 offset:36864
	ds_read_b128 v[216:219], v176 offset:37888
	ds_read_b128 v[220:223], v176 offset:38912
	ds_read_b128 v[224:227], v176 offset:39936
	global_load_lds_dwordx4 v134, s[36:37]
	s_mov_b32 m0, s60
	s_nop 0
	global_load_lds_dwordx4 v130, s[36:37]
	s_waitcnt vmcnt(8)
	s_waitcnt lgkmcnt(0)
	s_barrier
	s_waitcnt lgkmcnt(0)
	v_mfma_f32_16x16x32_bf16 v[124:127], v[152:155], v[194:197], v[124:127]
	v_mfma_f32_16x16x32_bf16 v[120:123], v[160:163], v[194:197], v[120:123]
	v_mfma_f32_16x16x32_bf16 v[108:111], v[152:155], v[204:207], v[108:111]
	v_mfma_f32_16x16x32_bf16 v[104:107], v[160:163], v[204:207], v[104:107]
	v_mfma_f32_16x16x32_bf16 v[92:95], v[152:155], v[212:215], v[92:95]
	v_mfma_f32_16x16x32_bf16 v[88:91], v[160:163], v[212:215], v[88:91]
	v_mfma_f32_16x16x32_bf16 v[76:79], v[152:155], v[220:223], v[76:79]
	v_mfma_f32_16x16x32_bf16 v[72:75], v[160:163], v[220:223], v[72:75]
	v_mfma_f32_16x16x32_bf16 v[124:127], v[156:159], v[200:203], v[124:127]
	v_mfma_f32_16x16x32_bf16 v[120:123], v[164:167], v[200:203], v[120:123]
	v_mfma_f32_16x16x32_bf16 v[108:111], v[156:159], v[208:211], v[108:111]
	v_mfma_f32_16x16x32_bf16 v[104:107], v[164:167], v[208:211], v[104:107]
	v_mfma_f32_16x16x32_bf16 v[92:95], v[156:159], v[216:219], v[92:95]
	v_mfma_f32_16x16x32_bf16 v[88:91], v[164:167], v[216:219], v[88:91]
	v_mfma_f32_16x16x32_bf16 v[76:79], v[156:159], v[224:227], v[76:79]
	v_mfma_f32_16x16x32_bf16 v[72:75], v[164:167], v[224:227], v[72:75]
	v_mfma_f32_16x16x32_bf16 v[116:119], v[168:171], v[194:197], v[116:119]
	v_mfma_f32_16x16x32_bf16 v[112:115], v[186:189], v[194:197], v[112:115]
	v_mfma_f32_16x16x32_bf16 v[100:103], v[168:171], v[204:207], v[100:103]
	v_mfma_f32_16x16x32_bf16 v[96:99], v[186:189], v[204:207], v[96:99]
	v_mfma_f32_16x16x32_bf16 v[84:87], v[168:171], v[212:215], v[84:87]
	v_mfma_f32_16x16x32_bf16 v[80:83], v[186:189], v[212:215], v[80:83]
	v_mfma_f32_16x16x32_bf16 v[68:71], v[168:171], v[220:223], v[68:71]
	v_mfma_f32_16x16x32_bf16 v[64:67], v[186:189], v[220:223], v[64:67]
	v_mfma_f32_16x16x32_bf16 v[116:119], v[182:185], v[200:203], v[116:119]
	v_mfma_f32_16x16x32_bf16 v[112:115], v[190:193], v[200:203], v[112:115]
	v_mfma_f32_16x16x32_bf16 v[100:103], v[182:185], v[208:211], v[100:103]
	v_mfma_f32_16x16x32_bf16 v[96:99], v[190:193], v[208:211], v[96:99]
	v_mfma_f32_16x16x32_bf16 v[84:87], v[182:185], v[216:219], v[84:87]
	v_mfma_f32_16x16x32_bf16 v[80:83], v[190:193], v[216:219], v[80:83]
	v_mfma_f32_16x16x32_bf16 v[68:71], v[182:185], v[224:227], v[68:71]
	v_mfma_f32_16x16x32_bf16 v[64:67], v[190:193], v[224:227], v[64:67]
	s_barrier
	s_mov_b32 m0, s62
	s_add_u32 s98, s98, s16
	s_addc_u32 s99, s99, s17
	s_add_u32 s34, s34, 0x40080
	ds_read_b128 v[194:197], v176 offset:49152
	ds_read_b128 v[200:203], v176 offset:50176
	ds_read_b128 v[204:207], v176 offset:51200
	ds_read_b128 v[208:211], v176 offset:52224
	ds_read_b128 v[212:215], v176 offset:53248
	ds_read_b128 v[216:219], v176 offset:54272
	ds_read_b128 v[220:223], v176 offset:55296
	ds_read_b128 v[224:227], v176 offset:56320
	global_load_lds_dwordx4 v132, s[98:99]
	s_mov_b32 m0, s63
	s_addc_u32 s35, s35, 0
	global_load_lds_dwordx4 v128, s[98:99]
	s_mov_b32 m0, s68
	s_nop 0
	global_load_lds_dwordx4 v132, s[34:35]
	s_mov_b32 m0, s69
	s_nop 0
	global_load_lds_dwordx4 v128, s[34:35]
	s_add_u32 s100, s100, s16
	s_addc_u32 s101, s101, s17
	s_mov_b32 m0, s64
	s_nop 0
	global_load_lds_dwordx4 v134, s[100:101]
	s_mov_b32 m0, s65
	s_nop 0
	global_load_lds_dwordx4 v130, s[100:101]
	s_waitcnt vmcnt(8)
	s_waitcnt lgkmcnt(0)
	s_barrier
	s_waitcnt lgkmcnt(0)
	v_mfma_f32_16x16x32_bf16 v[60:63], v[152:155], v[194:197], v[60:63]
	v_mfma_f32_16x16x32_bf16 v[56:59], v[160:163], v[194:197], v[56:59]
	v_mfma_f32_16x16x32_bf16 v[44:47], v[152:155], v[204:207], v[44:47]
	v_mfma_f32_16x16x32_bf16 v[40:43], v[160:163], v[204:207], v[40:43]
	v_mfma_f32_16x16x32_bf16 v[28:31], v[152:155], v[212:215], v[28:31]
	v_mfma_f32_16x16x32_bf16 v[24:27], v[160:163], v[212:215], v[24:27]
	v_mfma_f32_16x16x32_bf16 v[12:15], v[152:155], v[220:223], v[12:15]
	v_mfma_f32_16x16x32_bf16 v[8:11], v[160:163], v[220:223], v[8:11]
	v_mfma_f32_16x16x32_bf16 v[60:63], v[156:159], v[200:203], v[60:63]
	v_mfma_f32_16x16x32_bf16 v[56:59], v[164:167], v[200:203], v[56:59]
	v_mfma_f32_16x16x32_bf16 v[44:47], v[156:159], v[208:211], v[44:47]
	v_mfma_f32_16x16x32_bf16 v[40:43], v[164:167], v[208:211], v[40:43]
	v_mfma_f32_16x16x32_bf16 v[28:31], v[156:159], v[216:219], v[28:31]
	v_mfma_f32_16x16x32_bf16 v[24:27], v[164:167], v[216:219], v[24:27]
	v_mfma_f32_16x16x32_bf16 v[12:15], v[156:159], v[224:227], v[12:15]
	v_mfma_f32_16x16x32_bf16 v[8:11], v[164:167], v[224:227], v[8:11]
	v_mfma_f32_16x16x32_bf16 v[52:55], v[168:171], v[194:197], v[52:55]
	v_mfma_f32_16x16x32_bf16 v[48:51], v[186:189], v[194:197], v[48:51]
	v_mfma_f32_16x16x32_bf16 v[36:39], v[168:171], v[204:207], v[36:39]
	v_mfma_f32_16x16x32_bf16 v[32:35], v[186:189], v[204:207], v[32:35]
	v_mfma_f32_16x16x32_bf16 v[20:23], v[168:171], v[212:215], v[20:23]
	v_mfma_f32_16x16x32_bf16 v[16:19], v[186:189], v[212:215], v[16:19]
	v_mfma_f32_16x16x32_bf16 v[4:7], v[168:171], v[220:223], v[4:7]
	v_mfma_f32_16x16x32_bf16 v[0:3], v[186:189], v[220:223], v[0:3]
	v_mfma_f32_16x16x32_bf16 v[52:55], v[182:185], v[200:203], v[52:55]
	v_mfma_f32_16x16x32_bf16 v[48:51], v[190:193], v[200:203], v[48:51]
	v_mfma_f32_16x16x32_bf16 v[36:39], v[182:185], v[208:211], v[36:39]
	v_mfma_f32_16x16x32_bf16 v[32:35], v[190:193], v[208:211], v[32:35]
	v_mfma_f32_16x16x32_bf16 v[20:23], v[182:185], v[216:219], v[20:23]
	v_mfma_f32_16x16x32_bf16 v[16:19], v[190:193], v[216:219], v[16:19]
	v_mfma_f32_16x16x32_bf16 v[4:7], v[182:185], v[224:227], v[4:7]
	v_mfma_f32_16x16x32_bf16 v[0:3], v[190:193], v[224:227], v[0:3]
	s_barrier
	s_add_i32 s39, s39, 2
	s_add_u32 s30, s30, 0x100
	s_addc_u32 s31, s31, 0
	s_add_u32 s33, s33, 0x100
	s_addc_u32 s38, s38, 0
	s_cmp_gt_u32 s39, 13
	s_cbranch_scc0 .LBB0_437
	s_setprio 0
	s_and_b64 vcc, exec, s[18:19]
	s_cbranch_vccz .LBB0_440
	s_barrier

; #define PG8_STAGE(bufoff, gbase, voff) do { _Pragma("unroll") for (int _i = 0; _i < 2; ++_i) \
;         __builtin_amdgcn_global_load_lds((const unsigned*)((const char*)(gbase) + (voff)[_i]), (PG8_LAS unsigned*)(lds + (bufoff) + ldsw + _i * 8192), 16, 0, 0); } while (0)
; #define PG8_LDA(dst, b, h) do { _Pragma("unroll") for (int m = 0; m < 4; ++m) _Pragma("unroll") for (int k = 0; k < 2; ++k) dst[m][k] = *(const PG8_LAS bf16x8*)(lds + PG8_SA(b, h) + aoff + m * 2048 + k * 1024); } while (0)
; #define PG8_LDB(dst, b, h) do { _Pragma("unroll") for (int n = 0; n < 2; ++n) _Pragma("unroll") for (int k = 0; k < 2; ++k) dst[n][k] = *(const PG8_LAS bf16x8*)(lds + PG8_SB(b, h) + boff + n * 2048 + k * 1024); } while (0)
; #define PG8_MMA(ai, bj, At, Bt) do { __builtin_amdgcn_s_setprio(1); _Pragma("unroll") for (int m = 0; m < 4; ++m) _Pragma("unroll") for (int n = 0; n < 2; ++n) _Pragma("unroll") for (int k = 0; k < 2; ++k) \
;         acc[ai][bj][m][n] = __builtin_amdgcn_mfma_f32_16x16x32_bf16(Bt[n][k], At[m][k], acc[ai][bj][m][n], 0, 0, 0); __builtin_amdgcn_s_setprio(0); } while (0)
; #define PG8_WAIT_V(n) asm volatile("s_waitcnt vmcnt(" #n ")" ::: "memory")
; #define PG8_WAIT_L(n) asm volatile("s_waitcnt lgkmcnt(" #n ")" ::: "memory")
; template <class Epi, class Sched, bool ALIGN_EPI = false, bool SP2 = false>
; __device__ __forceinline__ void gemm_phase(PG8_LAS unsigned char* lds, const Gemm g, const Sched& S, const Epi& E, const int tid) {
;     ...
;             const bool last = (t == nt - 2);
;             const char* a1 = cA + (size_t)(t + 1) * kstep;
;             const char* a2 = last ? nA : cA + (size_t)(t + 2) * kstep; const char* b2 = last ? nB : cB + (size_t)(t + 2) * kstep;
;             const char* a3 = a2 + kstep; const char* b3 = b2 + kstep;
;             if (last && has_next) S.a_ready(nxt);
;             if constexpr (SP2) {
;             PG8_LDB(B0, 0, 0); PG8_LDB(B1, 0, 1); PG8_SCHED; PG8_LDA(At, 0, 0); PG8_STAGE(PG8_SA(1, 1), a1 + hstepA, voffA);
;             PG8_WAIT_V(8); PG8_WAIT_L(0); PG8_BAR; PG8_MMA(0, 0, At, B0); PG8_MMA(0, 1, At, B1); PG8_BAR; PG8_SCHED;
;             PG8_LDA(At, 0, 1); PG8_STAGE(PG8_SB(0, 0), b2, voffB); PG8_STAGE(PG8_SB(0, 1), b2 + hstep, voffB); PG8_STAGE(PG8_SA(0, 0), a2, voffA);
;             PG8_WAIT_V(8); PG8_WAIT_L(0); PG8_BAR; PG8_MMA(1, 0, At, B0); PG8_MMA(1, 1, At, B1); PG8_BAR; PG8_SCHED;
.Lsp_3:
	ds_read_b128 v[144:147], v150
	ds_read_b128 v[156:159], v150 offset:1024
	ds_read_b128 v[160:163], v150 offset:2048
	ds_read_b128 v[164:167], v150 offset:3072
	ds_read_b128 v[168:171], v151
	ds_read_b128 v[172:175], v151 offset:1024
	ds_read_b128 v[176:179], v151 offset:2048
	ds_read_b128 v[180:183], v151 offset:3072
	s_add_u32 s6, s28, 0x100
	s_addc_u32 s7, s29, 0
	s_cmp_eq_u32 s61, 12
	s_cselect_b32 s35, s23, s7
	s_cselect_b32 s34, s22, s6
	s_cselect_b32 s31, s21, s60
	s_cselect_b32 s30, s58, s59
	s_add_i32 m0, s41, 0xc000
	ds_read_b128 v[184:187], v152
	ds_read_b128 v[188:191], v152 offset:1024
	ds_read_b128 v[192:195], v152 offset:2048
	ds_read_b128 v[200:203], v152 offset:3072
	ds_read_b128 v[204:207], v152 offset:4096
	ds_read_b128 v[208:211], v152 offset:5120
	ds_read_b128 v[212:215], v152 offset:6144
	ds_read_b128 v[216:219], v152 offset:7168
	global_load_lds_dwordx4 v136, s[28:29]
	s_add_i32 m0, s41, 0xe000
	s_nop 0
	global_load_lds_dwordx4 v138, s[28:29]
	s_waitcnt vmcnt(8)
	s_waitcnt lgkmcnt(0)
	s_barrier
	s_waitcnt lgkmcnt(0)
	v_mfma_f32_16x16x32_bf16 v[124:127], v[144:147], v[184:187], v[124:127]
	v_mfma_f32_16x16x32_bf16 v[120:123], v[160:163], v[184:187], v[120:123]
	v_mfma_f32_16x16x32_bf16 v[108:111], v[144:147], v[192:195], v[108:111]
	v_mfma_f32_16x16x32_bf16 v[104:107], v[160:163], v[192:195], v[104:107]
	v_mfma_f32_16x16x32_bf16 v[92:95], v[144:147], v[204:207], v[92:95]
	v_mfma_f32_16x16x32_bf16 v[88:91], v[160:163], v[204:207], v[88:91]
	v_mfma_f32_16x16x32_bf16 v[76:79], v[144:147], v[212:215], v[76:79]
	v_mfma_f32_16x16x32_bf16 v[72:75], v[160:163], v[212:215], v[72:75]
	v_mfma_f32_16x16x32_bf16 v[124:127], v[156:159], v[188:191], v[124:127]
	v_mfma_f32_16x16x32_bf16 v[120:123], v[164:167], v[188:191], v[120:123]
	v_mfma_f32_16x16x32_bf16 v[108:111], v[156:159], v[200:203], v[108:111]
	v_mfma_f32_16x16x32_bf16 v[104:107], v[164:167], v[200:203], v[104:107]
	v_mfma_f32_16x16x32_bf16 v[92:95], v[156:159], v[208:211], v[92:95]
	v_mfma_f32_16x16x32_bf16 v[88:91], v[164:167], v[208:211], v[88:91]
	v_mfma_f32_16x16x32_bf16 v[76:79], v[156:159], v[216:219], v[76:79]
	v_mfma_f32_16x16x32_bf16 v[72:75], v[164:167], v[216:219], v[72:75]
	v_mfma_f32_16x16x32_bf16 v[116:119], v[168:171], v[184:187], v[116:119]
	v_mfma_f32_16x16x32_bf16 v[112:115], v[176:179], v[184:187], v[112:115]
	v_mfma_f32_16x16x32_bf16 v[100:103], v[168:171], v[192:195], v[100:103]
	v_mfma_f32_16x16x32_bf16 v[96:99], v[176:179], v[192:195], v[96:99]
	v_mfma_f32_16x16x32_bf16 v[84:87], v[168:171], v[204:207], v[84:87]
	v_mfma_f32_16x16x32_bf16 v[80:83], v[176:179], v[204:207], v[80:83]
	v_mfma_f32_16x16x32_bf16 v[68:71], v[168:171], v[212:215], v[68:71]
	v_mfma_f32_16x16x32_bf16 v[64:67], v[176:179], v[212:215], v[64:67]
	v_mfma_f32_16x16x32_bf16 v[116:119], v[172:175], v[188:191], v[116:119]
	v_mfma_f32_16x16x32_bf16 v[112:115], v[180:183], v[188:191], v[112:115]
	v_mfma_f32_16x16x32_bf16 v[100:103], v[172:175], v[200:203], v[100:103]
	v_mfma_f32_16x16x32_bf16 v[96:99], v[180:183], v[200:203], v[96:99]
	v_mfma_f32_16x16x32_bf16 v[84:87], v[172:175], v[208:211], v[84:87]
	v_mfma_f32_16x16x32_bf16 v[80:83], v[180:183], v[208:211], v[80:83]
	v_mfma_f32_16x16x32_bf16 v[68:71], v[172:175], v[216:219], v[68:71]
	v_mfma_f32_16x16x32_bf16 v[64:67], v[180:183], v[216:219], v[64:67]
	s_barrier
	s_mov_b32 m0, s27
	s_mov_b64 s[98:99], s[30:31]
	s_add_u32 s28, s30, 0x40000
	ds_read_b128 v[184:187], v152 offset:16384
	ds_read_b128 v[188:191], v152 offset:17408
	ds_read_b128 v[192:195], v152 offset:18432
	ds_read_b128 v[200:203], v152 offset:19456
	ds_read_b128 v[204:207], v152 offset:20480
	ds_read_b128 v[208:211], v152 offset:21504
	ds_read_b128 v[212:215], v152 offset:22528
	ds_read_b128 v[216:219], v152 offset:23552
	global_load_lds_dwordx4 v130, s[30:31]
	s_mov_b32 m0, s38
	s_addc_u32 s29, s31, 0
	global_load_lds_dwordx4 v134, s[30:31]
	s_mov_b32 m0, s39
	s_nop 0
	global_load_lds_dwordx4 v130, s[28:29]
	s_mov_b32 m0, s40
	s_nop 0
	global_load_lds_dwordx4 v134, s[28:29]
	s_mov_b64 s[100:101], s[34:35]
	s_mov_b32 m0, s41
	s_nop 0
	global_load_lds_dwordx4 v128, s[34:35]
	s_mov_b32 m0, s42
	s_nop 0
	global_load_lds_dwordx4 v132, s[34:35]
	s_waitcnt vmcnt(8)
	s_waitcnt lgkmcnt(0)
	s_barrier
	s_waitcnt lgkmcnt(0)
	v_mfma_f32_16x16x32_bf16 v[60:63], v[144:147], v[184:187], v[60:63]
	v_mfma_f32_16x16x32_bf16 v[56:59], v[160:163], v[184:187], v[56:59]
	v_mfma_f32_16x16x32_bf16 v[44:47], v[144:147], v[192:195], v[44:47]
	v_mfma_f32_16x16x32_bf16 v[40:43], v[160:163], v[192:195], v[40:43]
	v_mfma_f32_16x16x32_bf16 v[28:31], v[144:147], v[204:207], v[28:31]
	v_mfma_f32_16x16x32_bf16 v[24:27], v[160:163], v[204:207], v[24:27]
	v_mfma_f32_16x16x32_bf16 v[12:15], v[144:147], v[212:215], v[12:15]
	v_mfma_f32_16x16x32_bf16 v[8:11], v[160:163], v[212:215], v[8:11]
	v_mfma_f32_16x16x32_bf16 v[60:63], v[156:159], v[188:191], v[60:63]
	v_mfma_f32_16x16x32_bf16 v[56:59], v[164:167], v[188:191], v[56:59]
	v_mfma_f32_16x16x32_bf16 v[44:47], v[156:159], v[200:203], v[44:47]
	v_mfma_f32_16x16x32_bf16 v[40:43], v[164:167], v[200:203], v[40:43]
	v_mfma_f32_16x16x32_bf16 v[28:31], v[156:159], v[208:211], v[28:31]
	v_mfma_f32_16x16x32_bf16 v[24:27], v[164:167], v[208:211], v[24:27]
	v_mfma_f32_16x16x32_bf16 v[12:15], v[156:159], v[216:219], v[12:15]
	v_mfma_f32_16x16x32_bf16 v[8:11], v[164:167], v[216:219], v[8:11]
	v_mfma_f32_16x16x32_bf16 v[52:55], v[168:171], v[184:187], v[52:55]
	v_mfma_f32_16x16x32_bf16 v[48:51], v[176:179], v[184:187], v[48:51]
	v_mfma_f32_16x16x32_bf16 v[36:39], v[168:171], v[192:195], v[36:39]
	v_mfma_f32_16x16x32_bf16 v[32:35], v[176:179], v[192:195], v[32:35]
	v_mfma_f32_16x16x32_bf16 v[20:23], v[168:171], v[204:207], v[20:23]
	v_mfma_f32_16x16x32_bf16 v[16:19], v[176:179], v[204:207], v[16:19]
	v_mfma_f32_16x16x32_bf16 v[4:7], v[168:171], v[212:215], v[4:7]
	v_mfma_f32_16x16x32_bf16 v[0:3], v[176:179], v[212:215], v[0:3]
	v_mfma_f32_16x16x32_bf16 v[52:55], v[172:175], v[188:191], v[52:55]
	v_mfma_f32_16x16x32_bf16 v[48:51], v[180:183], v[188:191], v[48:51]
	v_mfma_f32_16x16x32_bf16 v[36:39], v[172:175], v[200:203], v[36:39]
	v_mfma_f32_16x16x32_bf16 v[32:35], v[180:183], v[200:203], v[32:35]
	v_mfma_f32_16x16x32_bf16 v[20:23], v[172:175], v[208:211], v[20:23]
	v_mfma_f32_16x16x32_bf16 v[16:19], v[180:183], v[208:211], v[16:19]
	v_mfma_f32_16x16x32_bf16 v[4:7], v[172:175], v[216:219], v[4:7]
	v_mfma_f32_16x16x32_bf16 v[0:3], v[180:183], v[216:219], v[0:3]
	s_barrier
; #define PG8_STAGE(bufoff, gbase, voff) do { _Pragma("unroll") for (int _i = 0; _i < 2; ++_i) \
;         __builtin_amdgcn_global_load_lds((const unsigned*)((const char*)(gbase) + (voff)[_i]), (PG8_LAS unsigned*)(lds + (bufoff) + ldsw + _i * 8192), 16, 0, 0); } while (0)
; #define PG8_LDA(dst, b, h) do { _Pragma("unroll") for (int m = 0; m < 4; ++m) _Pragma("unroll") for (int k = 0; k < 2; ++k) dst[m][k] = *(const PG8_LAS bf16x8*)(lds + PG8_SA(b, h) + aoff + m * 2048 + k * 1024); } while (0)
; #define PG8_LDB(dst, b, h) do { _Pragma("unroll") for (int n = 0; n < 2; ++n) _Pragma("unroll") for (int k = 0; k < 2; ++k) dst[n][k] = *(const PG8_LAS bf16x8*)(lds + PG8_SB(b, h) + boff + n * 2048 + k * 1024); } while (0)
; #define PG8_MMA(ai, bj, At, Bt) do { __builtin_amdgcn_s_setprio(1); _Pragma("unroll") for (int m = 0; m < 4; ++m) _Pragma("unroll") for (int n = 0; n < 2; ++n) _Pragma("unroll") for (int k = 0; k < 2; ++k) \
;         acc[ai][bj][m][n] = __builtin_amdgcn_mfma_f32_16x16x32_bf16(Bt[n][k], At[m][k], acc[ai][bj][m][n], 0, 0, 0); __builtin_amdgcn_s_setprio(0); } while (0)
; #define PG8_WAIT_V(n) asm volatile("s_waitcnt vmcnt(" #n ")" ::: "memory")
; #define PG8_WAIT_L(n) asm volatile("s_waitcnt lgkmcnt(" #n ")" ::: "memory")
; #define PG8_BAR __builtin_amdgcn_s_barrier()
; #define PG8_SCHED __builtin_amdgcn_sched_barrier(0)
; template <class Epi, class Sched, bool ALIGN_EPI = false, bool SP2 = false>
; __device__ __forceinline__ void gemm_phase(PG8_LAS unsigned char* lds, const Gemm g, const Sched& S, const Epi& E, const int tid) {
;     ...
;             PG8_LDB(B0, 1, 0); PG8_LDB(B1, 1, 1); PG8_SCHED; PG8_LDA(At, 1, 0); PG8_STAGE(PG8_SA(0, 1), a2 + hstepA, voffA);
;             PG8_WAIT_V(8); PG8_WAIT_L(0); PG8_BAR; PG8_MMA(0, 0, At, B0); PG8_MMA(0, 1, At, B1); PG8_BAR; PG8_SCHED;
;             PG8_LDA(At, 1, 1); PG8_STAGE(PG8_SB(1, 0), b3, voffB); PG8_STAGE(PG8_SB(1, 1), b3 + hstep, voffB); PG8_STAGE(PG8_SA(1, 0), a3, voffA);
;             PG8_WAIT_V(8); PG8_WAIT_L(0); PG8_BAR; PG8_MMA(1, 0, At, B0); PG8_MMA(1, 1, At, B1); PG8_BAR; PG8_SCHED;
	ds_read_b128 v[144:147], v153
	ds_read_b128 v[156:159], v153 offset:1024
	ds_read_b128 v[160:163], v153 offset:2048
	ds_read_b128 v[164:167], v153 offset:3072
	ds_read_b128 v[168:171], v154
	ds_read_b128 v[172:175], v154 offset:1024
	ds_read_b128 v[176:179], v154 offset:2048
	ds_read_b128 v[180:183], v154 offset:3072
	s_add_u32 s28, s34, 0xe0000
	s_addc_u32 s29, s35, 0
	s_mov_b32 m0, s43
	ds_read_b128 v[184:187], v152 offset:32768
	ds_read_b128 v[188:191], v152 offset:33792
	ds_read_b128 v[192:195], v152 offset:34816
	ds_read_b128 v[200:203], v152 offset:35840
	ds_read_b128 v[204:207], v152 offset:36864
	ds_read_b128 v[208:211], v152 offset:37888
	ds_read_b128 v[212:215], v152 offset:38912
	ds_read_b128 v[216:219], v152 offset:39936
	global_load_lds_dwordx4 v128, s[28:29]
	s_mov_b32 m0, s44
	s_nop 0
	global_load_lds_dwordx4 v132, s[28:29]
	s_waitcnt vmcnt(8)
	s_waitcnt lgkmcnt(0)
	s_barrier
	s_waitcnt lgkmcnt(0)
	v_mfma_f32_16x16x32_bf16 v[124:127], v[144:147], v[184:187], v[124:127]
	v_mfma_f32_16x16x32_bf16 v[120:123], v[160:163], v[184:187], v[120:123]
	v_mfma_f32_16x16x32_bf16 v[108:111], v[144:147], v[192:195], v[108:111]
	v_mfma_f32_16x16x32_bf16 v[104:107], v[160:163], v[192:195], v[104:107]
	v_mfma_f32_16x16x32_bf16 v[92:95], v[144:147], v[204:207], v[92:95]
	v_mfma_f32_16x16x32_bf16 v[88:91], v[160:163], v[204:207], v[88:91]
	v_mfma_f32_16x16x32_bf16 v[76:79], v[144:147], v[212:215], v[76:79]
	v_mfma_f32_16x16x32_bf16 v[72:75], v[160:163], v[212:215], v[72:75]
	v_mfma_f32_16x16x32_bf16 v[124:127], v[156:159], v[188:191], v[124:127]
	v_mfma_f32_16x16x32_bf16 v[120:123], v[164:167], v[188:191], v[120:123]
	v_mfma_f32_16x16x32_bf16 v[108:111], v[156:159], v[200:203], v[108:111]
	v_mfma_f32_16x16x32_bf16 v[104:107], v[164:167], v[200:203], v[104:107]
	v_mfma_f32_16x16x32_bf16 v[92:95], v[156:159], v[208:211], v[92:95]
	v_mfma_f32_16x16x32_bf16 v[88:91], v[164:167], v[208:211], v[88:91]
	v_mfma_f32_16x16x32_bf16 v[76:79], v[156:159], v[216:219], v[76:79]
	v_mfma_f32_16x16x32_bf16 v[72:75], v[164:167], v[216:219], v[72:75]
	v_mfma_f32_16x16x32_bf16 v[116:119], v[168:171], v[184:187], v[116:119]
	v_mfma_f32_16x16x32_bf16 v[112:115], v[176:179], v[184:187], v[112:115]
	v_mfma_f32_16x16x32_bf16 v[100:103], v[168:171], v[192:195], v[100:103]
	v_mfma_f32_16x16x32_bf16 v[96:99], v[176:179], v[192:195], v[96:99]
	v_mfma_f32_16x16x32_bf16 v[84:87], v[168:171], v[204:207], v[84:87]
	v_mfma_f32_16x16x32_bf16 v[80:83], v[176:179], v[204:207], v[80:83]
	v_mfma_f32_16x16x32_bf16 v[68:71], v[168:171], v[212:215], v[68:71]
	v_mfma_f32_16x16x32_bf16 v[64:67], v[176:179], v[212:215], v[64:67]
	v_mfma_f32_16x16x32_bf16 v[116:119], v[172:175], v[188:191], v[116:119]
	v_mfma_f32_16x16x32_bf16 v[112:115], v[180:183], v[188:191], v[112:115]
	v_mfma_f32_16x16x32_bf16 v[100:103], v[172:175], v[200:203], v[100:103]
	v_mfma_f32_16x16x32_bf16 v[96:99], v[180:183], v[200:203], v[96:99]
	v_mfma_f32_16x16x32_bf16 v[84:87], v[172:175], v[208:211], v[84:87]
	v_mfma_f32_16x16x32_bf16 v[80:83], v[180:183], v[208:211], v[80:83]
	v_mfma_f32_16x16x32_bf16 v[68:71], v[172:175], v[216:219], v[68:71]
	v_mfma_f32_16x16x32_bf16 v[64:67], v[180:183], v[216:219], v[64:67]
	s_barrier
	s_mov_b32 m0, s47
	s_add_u32 s98, s98, s14
	s_addc_u32 s99, s99, s15
	s_add_u32 s28, s30, 0x40080
	ds_read_b128 v[184:187], v152 offset:49152
	ds_read_b128 v[188:191], v152 offset:50176
	ds_read_b128 v[192:195], v152 offset:51200
	ds_read_b128 v[200:203], v152 offset:52224
	ds_read_b128 v[204:207], v152 offset:53248
	ds_read_b128 v[208:211], v152 offset:54272
	ds_read_b128 v[212:215], v152 offset:55296
	ds_read_b128 v[216:219], v152 offset:56320
	global_load_lds_dwordx4 v130, s[98:99]
	s_mov_b32 m0, s48
	s_addc_u32 s29, s31, 0
	global_load_lds_dwordx4 v134, s[98:99]
	s_mov_b32 m0, s51
	s_nop 0
	global_load_lds_dwordx4 v130, s[28:29]
	s_mov_b32 m0, s52
	s_nop 0
	global_load_lds_dwordx4 v134, s[28:29]
	s_add_u32 s100, s100, s14
	s_addc_u32 s101, s101, s15
	s_mov_b32 m0, s49
	s_nop 0
	global_load_lds_dwordx4 v128, s[100:101]
	s_mov_b32 m0, s50
	s_nop 0
	global_load_lds_dwordx4 v132, s[100:101]
	s_waitcnt vmcnt(8)
	s_waitcnt lgkmcnt(0)
	s_barrier
	s_waitcnt lgkmcnt(0)
	v_mfma_f32_16x16x32_bf16 v[60:63], v[144:147], v[184:187], v[60:63]
	v_mfma_f32_16x16x32_bf16 v[56:59], v[160:163], v[184:187], v[56:59]
	v_mfma_f32_16x16x32_bf16 v[44:47], v[144:147], v[192:195], v[44:47]
	v_mfma_f32_16x16x32_bf16 v[40:43], v[160:163], v[192:195], v[40:43]
	v_mfma_f32_16x16x32_bf16 v[28:31], v[144:147], v[204:207], v[28:31]
	v_mfma_f32_16x16x32_bf16 v[24:27], v[160:163], v[204:207], v[24:27]
	v_mfma_f32_16x16x32_bf16 v[12:15], v[144:147], v[212:215], v[12:15]
	v_mfma_f32_16x16x32_bf16 v[8:11], v[160:163], v[212:215], v[8:11]
	v_mfma_f32_16x16x32_bf16 v[60:63], v[156:159], v[188:191], v[60:63]
	v_mfma_f32_16x16x32_bf16 v[56:59], v[164:167], v[188:191], v[56:59]
	v_mfma_f32_16x16x32_bf16 v[44:47], v[156:159], v[200:203], v[44:47]
	v_mfma_f32_16x16x32_bf16 v[40:43], v[164:167], v[200:203], v[40:43]
	v_mfma_f32_16x16x32_bf16 v[28:31], v[156:159], v[208:211], v[28:31]
	v_mfma_f32_16x16x32_bf16 v[24:27], v[164:167], v[208:211], v[24:27]
	v_mfma_f32_16x16x32_bf16 v[12:15], v[156:159], v[216:219], v[12:15]
	v_mfma_f32_16x16x32_bf16 v[8:11], v[164:167], v[216:219], v[8:11]
	v_mfma_f32_16x16x32_bf16 v[52:55], v[168:171], v[184:187], v[52:55]
	v_mfma_f32_16x16x32_bf16 v[48:51], v[176:179], v[184:187], v[48:51]
	v_mfma_f32_16x16x32_bf16 v[36:39], v[168:171], v[192:195], v[36:39]
	v_mfma_f32_16x16x32_bf16 v[32:35], v[176:179], v[192:195], v[32:35]
	v_mfma_f32_16x16x32_bf16 v[20:23], v[168:171], v[204:207], v[20:23]
	v_mfma_f32_16x16x32_bf16 v[16:19], v[176:179], v[204:207], v[16:19]
	v_mfma_f32_16x16x32_bf16 v[4:7], v[168:171], v[212:215], v[4:7]
	v_mfma_f32_16x16x32_bf16 v[0:3], v[176:179], v[212:215], v[0:3]
	v_mfma_f32_16x16x32_bf16 v[52:55], v[172:175], v[188:191], v[52:55]
	v_mfma_f32_16x16x32_bf16 v[48:51], v[180:183], v[188:191], v[48:51]
	v_mfma_f32_16x16x32_bf16 v[36:39], v[172:175], v[200:203], v[36:39]
	v_mfma_f32_16x16x32_bf16 v[32:35], v[180:183], v[200:203], v[32:35]
	v_mfma_f32_16x16x32_bf16 v[20:23], v[172:175], v[208:211], v[20:23]
	v_mfma_f32_16x16x32_bf16 v[16:19], v[180:183], v[208:211], v[16:19]
	v_mfma_f32_16x16x32_bf16 v[4:7], v[172:175], v[216:219], v[4:7]
	v_mfma_f32_16x16x32_bf16 v[0:3], v[180:183], v[216:219], v[0:3]
	s_barrier
	s_add_i32 s61, s61, 2
	s_add_u32 s59, s59, 0x100
	s_addc_u32 s60, s60, 0
	s_cmp_gt_u32 s61, 13
	s_mov_b64 s[28:29], s[6:7]
	s_cbranch_scc0 .LBB0_765
	s_setprio 0
	s_and_b64 vcc, exec, s[16:17]
	s_cbranch_vccnz .LBB0_769
	s_andn2_b64 vcc, exec, s[18:19]
	s_cbranch_vccz .LBB0_770

; #define PG8_STAGE(bufoff, gbase, voff) do { _Pragma("unroll") for (int _i = 0; _i < 2; ++_i) \
;         __builtin_amdgcn_global_load_lds((const unsigned*)((const char*)(gbase) + (voff)[_i]), (PG8_LAS unsigned*)(lds + (bufoff) + ldsw + _i * 8192), 16, 0, 0); } while (0)
; #define PG8_LDA(dst, b, h) do { _Pragma("unroll") for (int m = 0; m < 4; ++m) _Pragma("unroll") for (int k = 0; k < 2; ++k) dst[m][k] = *(const PG8_LAS bf16x8*)(lds + PG8_SA(b, h) + aoff + m * 2048 + k * 1024); } while (0)
; #define PG8_LDB(dst, b, h) do { _Pragma("unroll") for (int n = 0; n < 2; ++n) _Pragma("unroll") for (int k = 0; k < 2; ++k) dst[n][k] = *(const PG8_LAS bf16x8*)(lds + PG8_SB(b, h) + boff + n * 2048 + k * 1024); } while (0)
; #define PG8_MMA(ai, bj, At, Bt) do { __builtin_amdgcn_s_setprio(1); _Pragma("unroll") for (int m = 0; m < 4; ++m) _Pragma("unroll") for (int n = 0; n < 2; ++n) _Pragma("unroll") for (int k = 0; k < 2; ++k) \
;         acc[ai][bj][m][n] = __builtin_amdgcn_mfma_f32_16x16x32_bf16(Bt[n][k], At[m][k], acc[ai][bj][m][n], 0, 0, 0); __builtin_amdgcn_s_setprio(0); } while (0)
; #define PG8_WAIT_V(n) asm volatile("s_waitcnt vmcnt(" #n ")" ::: "memory")
; #define PG8_WAIT_L(n) asm volatile("s_waitcnt lgkmcnt(" #n ")" ::: "memory")
; template <class Epi, class Sched, bool ALIGN_EPI = false, bool SP2 = false>
; __device__ __forceinline__ void gemm_phase(PG8_LAS unsigned char* lds, const Gemm g, const Sched& S, const Epi& E, const int tid) {
;     ...
;             const bool last = (t == nt - 2);
;             const char* a1 = cA + (size_t)(t + 1) * kstep;
;             const char* a2 = last ? nA : cA + (size_t)(t + 2) * kstep; const char* b2 = last ? nB : cB + (size_t)(t + 2) * kstep;
;             const char* a3 = a2 + kstep; const char* b3 = b2 + kstep;
;             if (last && has_next) S.a_ready(nxt);
;             if constexpr (SP2) {
;             PG8_LDB(B0, 0, 0); PG8_LDB(B1, 0, 1); PG8_SCHED; PG8_LDA(At, 0, 0); PG8_STAGE(PG8_SA(1, 1), a1 + hstepA, voffA);
;             PG8_WAIT_V(8); PG8_WAIT_L(0); PG8_BAR; PG8_MMA(0, 0, At, B0); PG8_MMA(0, 1, At, B1); PG8_BAR; PG8_SCHED;
;             PG8_LDA(At, 0, 1); PG8_STAGE(PG8_SB(0, 0), b2, voffB); PG8_STAGE(PG8_SB(0, 1), b2 + hstep, voffB); PG8_STAGE(PG8_SA(0, 0), a2, voffA);
;             PG8_WAIT_V(8); PG8_WAIT_L(0); PG8_BAR; PG8_MMA(1, 0, At, B0); PG8_MMA(1, 1, At, B1); PG8_BAR; PG8_SCHED;
.Lsp_4:
	ds_read_b128 v[144:147], v154
	ds_read_b128 v[148:151], v154 offset:1024
	ds_read_b128 v[160:163], v154 offset:2048
	ds_read_b128 v[164:167], v154 offset:3072
	ds_read_b128 v[168:171], v155
	ds_read_b128 v[172:175], v155 offset:1024
	ds_read_b128 v[176:179], v155 offset:2048
	ds_read_b128 v[180:183], v155 offset:3072
	s_add_u32 s26, s24, 0xfffc0080
	s_addc_u32 s27, s25, -1
	s_cmp_eq_u32 s58, 12
	s_cselect_b32 s29, s17, s27
	s_cselect_b32 s28, s54, s26
	s_cselect_b32 s27, s15, s57
	s_cselect_b32 s26, s55, s56
	s_add_i32 m0, s39, 0xc000
	ds_read_b128 v[184:187], v156
	ds_read_b128 v[188:191], v156 offset:1024
	ds_read_b128 v[192:195], v156 offset:2048
	ds_read_b128 v[200:203], v156 offset:3072
	ds_read_b128 v[204:207], v156 offset:4096
	ds_read_b128 v[208:211], v156 offset:5120
	ds_read_b128 v[212:215], v156 offset:6144
	ds_read_b128 v[216:219], v156 offset:7168
	global_load_lds_dwordx4 v136, s[24:25]
	s_add_i32 m0, s39, 0xe000
	s_nop 0
	global_load_lds_dwordx4 v138, s[24:25]
	s_waitcnt vmcnt(8)
	s_waitcnt lgkmcnt(0)
	s_barrier
	s_waitcnt lgkmcnt(0)
	v_mfma_f32_16x16x32_bf16 v[124:127], v[144:147], v[184:187], v[124:127]
	v_mfma_f32_16x16x32_bf16 v[120:123], v[160:163], v[184:187], v[120:123]
	v_mfma_f32_16x16x32_bf16 v[108:111], v[144:147], v[192:195], v[108:111]
	v_mfma_f32_16x16x32_bf16 v[104:107], v[160:163], v[192:195], v[104:107]
	v_mfma_f32_16x16x32_bf16 v[92:95], v[144:147], v[204:207], v[92:95]
	v_mfma_f32_16x16x32_bf16 v[88:91], v[160:163], v[204:207], v[88:91]
	v_mfma_f32_16x16x32_bf16 v[76:79], v[144:147], v[212:215], v[76:79]
	v_mfma_f32_16x16x32_bf16 v[72:75], v[160:163], v[212:215], v[72:75]
	v_mfma_f32_16x16x32_bf16 v[124:127], v[148:151], v[188:191], v[124:127]
	v_mfma_f32_16x16x32_bf16 v[120:123], v[164:167], v[188:191], v[120:123]
	v_mfma_f32_16x16x32_bf16 v[108:111], v[148:151], v[200:203], v[108:111]
	v_mfma_f32_16x16x32_bf16 v[104:107], v[164:167], v[200:203], v[104:107]
	v_mfma_f32_16x16x32_bf16 v[92:95], v[148:151], v[208:211], v[92:95]
	v_mfma_f32_16x16x32_bf16 v[88:91], v[164:167], v[208:211], v[88:91]
	v_mfma_f32_16x16x32_bf16 v[76:79], v[148:151], v[216:219], v[76:79]
	v_mfma_f32_16x16x32_bf16 v[72:75], v[164:167], v[216:219], v[72:75]
	v_mfma_f32_16x16x32_bf16 v[116:119], v[168:171], v[184:187], v[116:119]
	v_mfma_f32_16x16x32_bf16 v[112:115], v[176:179], v[184:187], v[112:115]
	v_mfma_f32_16x16x32_bf16 v[100:103], v[168:171], v[192:195], v[100:103]
	v_mfma_f32_16x16x32_bf16 v[96:99], v[176:179], v[192:195], v[96:99]
	v_mfma_f32_16x16x32_bf16 v[84:87], v[168:171], v[204:207], v[84:87]
	v_mfma_f32_16x16x32_bf16 v[80:83], v[176:179], v[204:207], v[80:83]
	v_mfma_f32_16x16x32_bf16 v[68:71], v[168:171], v[212:215], v[68:71]
	v_mfma_f32_16x16x32_bf16 v[64:67], v[176:179], v[212:215], v[64:67]
	v_mfma_f32_16x16x32_bf16 v[116:119], v[172:175], v[188:191], v[116:119]
	v_mfma_f32_16x16x32_bf16 v[112:115], v[180:183], v[188:191], v[112:115]
	v_mfma_f32_16x16x32_bf16 v[100:103], v[172:175], v[200:203], v[100:103]
	v_mfma_f32_16x16x32_bf16 v[96:99], v[180:183], v[200:203], v[96:99]
	v_mfma_f32_16x16x32_bf16 v[84:87], v[172:175], v[208:211], v[84:87]
	v_mfma_f32_16x16x32_bf16 v[80:83], v[180:183], v[208:211], v[80:83]
	v_mfma_f32_16x16x32_bf16 v[68:71], v[172:175], v[216:219], v[68:71]
	v_mfma_f32_16x16x32_bf16 v[64:67], v[180:183], v[216:219], v[64:67]
	s_barrier
	s_mov_b32 m0, s23
	s_mov_b64 s[98:99], s[26:27]
	s_add_u32 s60, s26, 0x40000
	ds_read_b128 v[184:187], v156 offset:16384
	ds_read_b128 v[188:191], v156 offset:17408
	ds_read_b128 v[192:195], v156 offset:18432
	ds_read_b128 v[200:203], v156 offset:19456
	ds_read_b128 v[204:207], v156 offset:20480
	ds_read_b128 v[208:211], v156 offset:21504
	ds_read_b128 v[212:215], v156 offset:22528
	ds_read_b128 v[216:219], v156 offset:23552
	global_load_lds_dwordx4 v132, s[26:27]
	s_mov_b32 m0, s36
	s_addc_u32 s61, s27, 0
	global_load_lds_dwordx4 v128, s[26:27]
	s_mov_b32 m0, s37
	s_nop 0
	global_load_lds_dwordx4 v132, s[60:61]
	s_mov_b32 m0, s38
	s_nop 0
	global_load_lds_dwordx4 v128, s[60:61]
	s_mov_b64 s[100:101], s[28:29]
	s_mov_b32 m0, s39
	s_nop 0
	global_load_lds_dwordx4 v134, s[28:29]
	s_mov_b32 m0, s40
	s_nop 0
	global_load_lds_dwordx4 v130, s[28:29]
	s_waitcnt vmcnt(8)
	s_waitcnt lgkmcnt(0)
	s_barrier
	s_waitcnt lgkmcnt(0)
	v_mfma_f32_16x16x32_bf16 v[60:63], v[144:147], v[184:187], v[60:63]
	v_mfma_f32_16x16x32_bf16 v[56:59], v[160:163], v[184:187], v[56:59]
	v_mfma_f32_16x16x32_bf16 v[44:47], v[144:147], v[192:195], v[44:47]
	v_mfma_f32_16x16x32_bf16 v[40:43], v[160:163], v[192:195], v[40:43]
	v_mfma_f32_16x16x32_bf16 v[28:31], v[144:147], v[204:207], v[28:31]
	v_mfma_f32_16x16x32_bf16 v[24:27], v[160:163], v[204:207], v[24:27]
	v_mfma_f32_16x16x32_bf16 v[12:15], v[144:147], v[212:215], v[12:15]
	v_mfma_f32_16x16x32_bf16 v[8:11], v[160:163], v[212:215], v[8:11]
	v_mfma_f32_16x16x32_bf16 v[60:63], v[148:151], v[188:191], v[60:63]
	v_mfma_f32_16x16x32_bf16 v[56:59], v[164:167], v[188:191], v[56:59]
	v_mfma_f32_16x16x32_bf16 v[44:47], v[148:151], v[200:203], v[44:47]
	v_mfma_f32_16x16x32_bf16 v[40:43], v[164:167], v[200:203], v[40:43]
	v_mfma_f32_16x16x32_bf16 v[28:31], v[148:151], v[208:211], v[28:31]
	v_mfma_f32_16x16x32_bf16 v[24:27], v[164:167], v[208:211], v[24:27]
	v_mfma_f32_16x16x32_bf16 v[12:15], v[148:151], v[216:219], v[12:15]
	v_mfma_f32_16x16x32_bf16 v[8:11], v[164:167], v[216:219], v[8:11]
	v_mfma_f32_16x16x32_bf16 v[52:55], v[168:171], v[184:187], v[52:55]
	v_mfma_f32_16x16x32_bf16 v[48:51], v[176:179], v[184:187], v[48:51]
	v_mfma_f32_16x16x32_bf16 v[36:39], v[168:171], v[192:195], v[36:39]
	v_mfma_f32_16x16x32_bf16 v[32:35], v[176:179], v[192:195], v[32:35]
	v_mfma_f32_16x16x32_bf16 v[20:23], v[168:171], v[204:207], v[20:23]
	v_mfma_f32_16x16x32_bf16 v[16:19], v[176:179], v[204:207], v[16:19]
	v_mfma_f32_16x16x32_bf16 v[4:7], v[168:171], v[212:215], v[4:7]
	v_mfma_f32_16x16x32_bf16 v[0:3], v[176:179], v[212:215], v[0:3]
	v_mfma_f32_16x16x32_bf16 v[52:55], v[172:175], v[188:191], v[52:55]
	v_mfma_f32_16x16x32_bf16 v[48:51], v[180:183], v[188:191], v[48:51]
	v_mfma_f32_16x16x32_bf16 v[36:39], v[172:175], v[200:203], v[36:39]
	v_mfma_f32_16x16x32_bf16 v[32:35], v[180:183], v[200:203], v[32:35]
	v_mfma_f32_16x16x32_bf16 v[20:23], v[172:175], v[208:211], v[20:23]
	v_mfma_f32_16x16x32_bf16 v[16:19], v[180:183], v[208:211], v[16:19]
	v_mfma_f32_16x16x32_bf16 v[4:7], v[172:175], v[216:219], v[4:7]
	v_mfma_f32_16x16x32_bf16 v[0:3], v[180:183], v[216:219], v[0:3]
	s_barrier
; #define PG8_STAGE(bufoff, gbase, voff) do { _Pragma("unroll") for (int _i = 0; _i < 2; ++_i) \
;         __builtin_amdgcn_global_load_lds((const unsigned*)((const char*)(gbase) + (voff)[_i]), (PG8_LAS unsigned*)(lds + (bufoff) + ldsw + _i * 8192), 16, 0, 0); } while (0)
; #define PG8_LDA(dst, b, h) do { _Pragma("unroll") for (int m = 0; m < 4; ++m) _Pragma("unroll") for (int k = 0; k < 2; ++k) dst[m][k] = *(const PG8_LAS bf16x8*)(lds + PG8_SA(b, h) + aoff + m * 2048 + k * 1024); } while (0)
; #define PG8_LDB(dst, b, h) do { _Pragma("unroll") for (int n = 0; n < 2; ++n) _Pragma("unroll") for (int k = 0; k < 2; ++k) dst[n][k] = *(const PG8_LAS bf16x8*)(lds + PG8_SB(b, h) + boff + n * 2048 + k * 1024); } while (0)
; #define PG8_MMA(ai, bj, At, Bt) do { __builtin_amdgcn_s_setprio(1); _Pragma("unroll") for (int m = 0; m < 4; ++m) _Pragma("unroll") for (int n = 0; n < 2; ++n) _Pragma("unroll") for (int k = 0; k < 2; ++k) \
;         acc[ai][bj][m][n] = __builtin_amdgcn_mfma_f32_16x16x32_bf16(Bt[n][k], At[m][k], acc[ai][bj][m][n], 0, 0, 0); __builtin_amdgcn_s_setprio(0); } while (0)
; #define PG8_WAIT_V(n) asm volatile("s_waitcnt vmcnt(" #n ")" ::: "memory")
; #define PG8_WAIT_L(n) asm volatile("s_waitcnt lgkmcnt(" #n ")" ::: "memory")
; #define PG8_BAR __builtin_amdgcn_s_barrier()
; #define PG8_SCHED __builtin_amdgcn_sched_barrier(0)
; template <class Epi, class Sched, bool ALIGN_EPI = false, bool SP2 = false>
; __device__ __forceinline__ void gemm_phase(PG8_LAS unsigned char* lds, const Gemm g, const Sched& S, const Epi& E, const int tid) {
;     ...
;             PG8_LDB(B0, 1, 0); PG8_LDB(B1, 1, 1); PG8_SCHED; PG8_LDA(At, 1, 0); PG8_STAGE(PG8_SA(0, 1), a2 + hstepA, voffA);
;             PG8_WAIT_V(8); PG8_WAIT_L(0); PG8_BAR; PG8_MMA(0, 0, At, B0); PG8_MMA(0, 1, At, B1); PG8_BAR; PG8_SCHED;
;             PG8_LDA(At, 1, 1); PG8_STAGE(PG8_SB(1, 0), b3, voffB); PG8_STAGE(PG8_SB(1, 1), b3 + hstep, voffB); PG8_STAGE(PG8_SA(1, 0), a3, voffA);
	ds_read_b128 v[144:147], v157
	ds_read_b128 v[148:151], v157 offset:1024
	ds_read_b128 v[160:163], v157 offset:2048
	ds_read_b128 v[164:167], v157 offset:3072
	ds_read_b128 v[168:171], v158
	ds_read_b128 v[172:175], v158 offset:1024
	ds_read_b128 v[176:179], v158 offset:2048
	ds_read_b128 v[180:183], v158 offset:3072
	s_add_u32 s28, s28, 0x40000
	s_addc_u32 s29, s29, 0
	s_mov_b32 m0, s41
	ds_read_b128 v[184:187], v156 offset:32768
	ds_read_b128 v[188:191], v156 offset:33792
	ds_read_b128 v[192:195], v156 offset:34816
	ds_read_b128 v[200:203], v156 offset:35840
	ds_read_b128 v[204:207], v156 offset:36864
	ds_read_b128 v[208:211], v156 offset:37888
	ds_read_b128 v[212:215], v156 offset:38912
	ds_read_b128 v[216:219], v156 offset:39936
	global_load_lds_dwordx4 v134, s[28:29]
	s_mov_b32 m0, s42
	s_nop 0
	global_load_lds_dwordx4 v130, s[28:29]
	s_waitcnt vmcnt(8)
	s_waitcnt lgkmcnt(0)
	s_barrier
	s_waitcnt lgkmcnt(0)
	v_mfma_f32_16x16x32_bf16 v[124:127], v[144:147], v[184:187], v[124:127]
	v_mfma_f32_16x16x32_bf16 v[120:123], v[160:163], v[184:187], v[120:123]
	v_mfma_f32_16x16x32_bf16 v[108:111], v[144:147], v[192:195], v[108:111]
	v_mfma_f32_16x16x32_bf16 v[104:107], v[160:163], v[192:195], v[104:107]
	v_mfma_f32_16x16x32_bf16 v[92:95], v[144:147], v[204:207], v[92:95]
	v_mfma_f32_16x16x32_bf16 v[88:91], v[160:163], v[204:207], v[88:91]
	v_mfma_f32_16x16x32_bf16 v[76:79], v[144:147], v[212:215], v[76:79]
	v_mfma_f32_16x16x32_bf16 v[72:75], v[160:163], v[212:215], v[72:75]
	v_mfma_f32_16x16x32_bf16 v[124:127], v[148:151], v[188:191], v[124:127]
	v_mfma_f32_16x16x32_bf16 v[120:123], v[164:167], v[188:191], v[120:123]
	v_mfma_f32_16x16x32_bf16 v[108:111], v[148:151], v[200:203], v[108:111]
	v_mfma_f32_16x16x32_bf16 v[104:107], v[164:167], v[200:203], v[104:107]
	v_mfma_f32_16x16x32_bf16 v[92:95], v[148:151], v[208:211], v[92:95]
	v_mfma_f32_16x16x32_bf16 v[88:91], v[164:167], v[208:211], v[88:91]
	v_mfma_f32_16x16x32_bf16 v[76:79], v[148:151], v[216:219], v[76:79]
	v_mfma_f32_16x16x32_bf16 v[72:75], v[164:167], v[216:219], v[72:75]
	v_mfma_f32_16x16x32_bf16 v[116:119], v[168:171], v[184:187], v[116:119]
	v_mfma_f32_16x16x32_bf16 v[112:115], v[176:179], v[184:187], v[112:115]
	v_mfma_f32_16x16x32_bf16 v[100:103], v[168:171], v[192:195], v[100:103]
	v_mfma_f32_16x16x32_bf16 v[96:99], v[176:179], v[192:195], v[96:99]
	v_mfma_f32_16x16x32_bf16 v[84:87], v[168:171], v[204:207], v[84:87]
	v_mfma_f32_16x16x32_bf16 v[80:83], v[176:179], v[204:207], v[80:83]
	v_mfma_f32_16x16x32_bf16 v[68:71], v[168:171], v[212:215], v[68:71]
	v_mfma_f32_16x16x32_bf16 v[64:67], v[176:179], v[212:215], v[64:67]
	v_mfma_f32_16x16x32_bf16 v[116:119], v[172:175], v[188:191], v[116:119]
	v_mfma_f32_16x16x32_bf16 v[112:115], v[180:183], v[188:191], v[112:115]
	v_mfma_f32_16x16x32_bf16 v[100:103], v[172:175], v[200:203], v[100:103]
	v_mfma_f32_16x16x32_bf16 v[96:99], v[180:183], v[200:203], v[96:99]
	v_mfma_f32_16x16x32_bf16 v[84:87], v[172:175], v[208:211], v[84:87]
	v_mfma_f32_16x16x32_bf16 v[80:83], v[180:183], v[208:211], v[80:83]
	v_mfma_f32_16x16x32_bf16 v[68:71], v[172:175], v[216:219], v[68:71]
	v_mfma_f32_16x16x32_bf16 v[64:67], v[180:183], v[216:219], v[64:67]
	s_barrier
	s_mov_b32 m0, s45
	s_add_u32 s98, s98, s10
	s_addc_u32 s99, s99, s11
	s_add_u32 s26, s26, 0x40080
	ds_read_b128 v[184:187], v156 offset:49152
	ds_read_b128 v[188:191], v156 offset:50176
	ds_read_b128 v[192:195], v156 offset:51200
	ds_read_b128 v[200:203], v156 offset:52224
	ds_read_b128 v[204:207], v156 offset:53248
	ds_read_b128 v[208:211], v156 offset:54272
	ds_read_b128 v[212:215], v156 offset:55296
	ds_read_b128 v[216:219], v156 offset:56320
	global_load_lds_dwordx4 v132, s[98:99]
	s_mov_b32 m0, s46
	s_addc_u32 s27, s27, 0
	global_load_lds_dwordx4 v128, s[98:99]
	s_mov_b32 m0, s49
	s_nop 0
	global_load_lds_dwordx4 v132, s[26:27]
	s_mov_b32 m0, s50
	s_nop 0
	global_load_lds_dwordx4 v128, s[26:27]
	s_add_u32 s100, s100, s10
	s_addc_u32 s101, s101, s11
	s_mov_b32 m0, s47
	s_nop 0
	global_load_lds_dwordx4 v134, s[100:101]
	s_mov_b32 m0, s48
	s_nop 0
	global_load_lds_dwordx4 v130, s[100:101]
	s_waitcnt vmcnt(8)
	s_waitcnt lgkmcnt(0)
	s_barrier
; #define PG8_MMA(ai, bj, At, Bt) do { __builtin_amdgcn_s_setprio(1); _Pragma("unroll") for (int m = 0; m < 4; ++m) _Pragma("unroll") for (int n = 0; n < 2; ++n) _Pragma("unroll") for (int k = 0; k < 2; ++k) \
;         acc[ai][bj][m][n] = __builtin_amdgcn_mfma_f32_16x16x32_bf16(Bt[n][k], At[m][k], acc[ai][bj][m][n], 0, 0, 0); __builtin_amdgcn_s_setprio(0); } while (0)
; #define PG8_WAIT_V(n) asm volatile("s_waitcnt vmcnt(" #n ")" ::: "memory")
; #define PG8_WAIT_L(n) asm volatile("s_waitcnt lgkmcnt(" #n ")" ::: "memory")
; #define PG8_BAR __builtin_amdgcn_s_barrier()
; #define PG8_SCHED __builtin_amdgcn_sched_barrier(0)
; __device__ __forceinline__ float ss_scale(const u64* ss, int row) { return __builtin_amdgcn_rsqf((float)ss[row] * (1.f / 4294967296.f / 1024.f) + EPS); }
; template <class Epi, class Sched, bool ALIGN_EPI = false, bool SP2 = false>
; __device__ __forceinline__ void gemm_phase(PG8_LAS unsigned char* lds, const Gemm g, const Sched& S, const Epi& E, const int tid) {
;     ...
;             PG8_WAIT_V(8); PG8_WAIT_L(0); PG8_BAR; PG8_MMA(1, 0, At, B0); PG8_MMA(1, 1, At, B1); PG8_BAR; PG8_SCHED;
;     __device__ __forceinline__ void operator()(const f32x4 (&acc)[2][2][4][2], const pg8::Unit& u, int wr, int wc, int fr, int fq) const {
;         const int row0 = u.pm * 256 + wr * 64 + fr, col0 = u.pn * 128 + wc * 32 + 8 * fq;
; #pragma unroll
;         for (int ai = 0; ai < 2; ++ai)
; #pragma unroll
;             for (int m = 0; m < 4; ++m) {
;                 const int row = row0 + ai * 128 + m * 16;
;                 float s = ss_scale(ss, row);
	s_waitcnt lgkmcnt(0)
	v_mfma_f32_16x16x32_bf16 v[60:63], v[144:147], v[184:187], v[60:63]
	v_mfma_f32_16x16x32_bf16 v[56:59], v[160:163], v[184:187], v[56:59]
	v_mfma_f32_16x16x32_bf16 v[44:47], v[144:147], v[192:195], v[44:47]
	v_mfma_f32_16x16x32_bf16 v[40:43], v[160:163], v[192:195], v[40:43]
	v_mfma_f32_16x16x32_bf16 v[28:31], v[144:147], v[204:207], v[28:31]
	v_mfma_f32_16x16x32_bf16 v[24:27], v[160:163], v[204:207], v[24:27]
	v_mfma_f32_16x16x32_bf16 v[12:15], v[144:147], v[212:215], v[12:15]
	v_mfma_f32_16x16x32_bf16 v[8:11], v[160:163], v[212:215], v[8:11]
	v_mfma_f32_16x16x32_bf16 v[60:63], v[148:151], v[188:191], v[60:63]
	v_mfma_f32_16x16x32_bf16 v[56:59], v[164:167], v[188:191], v[56:59]
	v_mfma_f32_16x16x32_bf16 v[44:47], v[148:151], v[200:203], v[44:47]
	v_mfma_f32_16x16x32_bf16 v[40:43], v[164:167], v[200:203], v[40:43]
	v_mfma_f32_16x16x32_bf16 v[28:31], v[148:151], v[208:211], v[28:31]
	v_mfma_f32_16x16x32_bf16 v[24:27], v[164:167], v[208:211], v[24:27]
	v_mfma_f32_16x16x32_bf16 v[12:15], v[148:151], v[216:219], v[12:15]
	v_mfma_f32_16x16x32_bf16 v[8:11], v[164:167], v[216:219], v[8:11]
	v_mfma_f32_16x16x32_bf16 v[52:55], v[168:171], v[184:187], v[52:55]
	v_mfma_f32_16x16x32_bf16 v[48:51], v[176:179], v[184:187], v[48:51]
	v_mfma_f32_16x16x32_bf16 v[36:39], v[168:171], v[192:195], v[36:39]
	v_mfma_f32_16x16x32_bf16 v[32:35], v[176:179], v[192:195], v[32:35]
	v_mfma_f32_16x16x32_bf16 v[20:23], v[168:171], v[204:207], v[20:23]
	v_mfma_f32_16x16x32_bf16 v[16:19], v[176:179], v[204:207], v[16:19]
	v_mfma_f32_16x16x32_bf16 v[4:7], v[168:171], v[212:215], v[4:7]
	v_mfma_f32_16x16x32_bf16 v[0:3], v[176:179], v[212:215], v[0:3]
	v_mfma_f32_16x16x32_bf16 v[52:55], v[172:175], v[188:191], v[52:55]
	v_mfma_f32_16x16x32_bf16 v[48:51], v[180:183], v[188:191], v[48:51]
	v_mfma_f32_16x16x32_bf16 v[36:39], v[172:175], v[200:203], v[36:39]
	v_mfma_f32_16x16x32_bf16 v[32:35], v[180:183], v[200:203], v[32:35]
	v_mfma_f32_16x16x32_bf16 v[20:23], v[172:175], v[208:211], v[20:23]
	v_mfma_f32_16x16x32_bf16 v[16:19], v[180:183], v[208:211], v[16:19]
	v_mfma_f32_16x16x32_bf16 v[4:7], v[172:175], v[216:219], v[4:7]
	v_mfma_f32_16x16x32_bf16 v[0:3], v[180:183], v[216:219], v[0:3]
	s_barrier
	s_add_i32 s58, s58, 2
	s_add_u32 s24, s24, 0x100
	s_addc_u32 s25, s25, 0
	s_add_u32 s56, s56, 0x100
	s_addc_u32 s57, s57, 0
	s_cmp_gt_u32 s58, 13
	s_cbranch_scc0 .LBB0_849
	s_setprio 0
	v_lshl_add_u32 v144, s22, 8, v152
	v_mov_b32_e32 v145, 0
	v_lshl_add_u64 v[150:151], v[144:145], 3, s[8:9]
	global_load_dwordx2 v[176:177], v[150:151], off
	global_load_dwordx2 v[178:179], v[150:151], off offset:128
	global_load_dwordx2 v[180:181], v[150:151], off offset:256
	global_load_dwordx2 v[182:183], v[150:151], off offset:384
	global_load_dwordx2 v[184:185], v[150:151], off offset:1024
	global_load_dwordx2 v[186:187], v[150:151], off offset:1152
	global_load_dwordx2 v[188:189], v[150:151], off offset:1280
	global_load_dwordx2 v[190:191], v[150:151], off offset:1408
	v_lshl_or_b32 v148, s53, 7, v153
	v_mul_u32_u24_e32 v146, s52, v144
	v_lshl_add_u32 v146, v148, 1, v146
	v_mov_b32_e32 v147, 0
	v_lshl_add_u64 v[146:147], v[146:147], 0, s[6:7]
	v_mov_b32_e32 v164, 1.0
	v_mov_b32_e32 v165, 1.0
	s_mov_b32 s101, 0
	s_and_b64 vcc, exec, s[12:13]
	s_cbranch_vccz .LBB0_852
	s_barrier

; #define PG8_STAGE(bufoff, gbase, voff) do { _Pragma("unroll") for (int _i = 0; _i < 2; ++_i) \
;         __builtin_amdgcn_global_load_lds((const unsigned*)((const char*)(gbase) + (voff)[_i]), (PG8_LAS unsigned*)(lds + (bufoff) + ldsw + _i * 8192), 16, 0, 0); } while (0)
; #define PG8_LDA(dst, b, h) do { _Pragma("unroll") for (int m = 0; m < 4; ++m) _Pragma("unroll") for (int k = 0; k < 2; ++k) dst[m][k] = *(const PG8_LAS bf16x8*)(lds + PG8_SA(b, h) + aoff + m * 2048 + k * 1024); } while (0)
; #define PG8_LDB(dst, b, h) do { _Pragma("unroll") for (int n = 0; n < 2; ++n) _Pragma("unroll") for (int k = 0; k < 2; ++k) dst[n][k] = *(const PG8_LAS bf16x8*)(lds + PG8_SB(b, h) + boff + n * 2048 + k * 1024); } while (0)
; #define PG8_MMA(ai, bj, At, Bt) do { __builtin_amdgcn_s_setprio(1); _Pragma("unroll") for (int m = 0; m < 4; ++m) _Pragma("unroll") for (int n = 0; n < 2; ++n) _Pragma("unroll") for (int k = 0; k < 2; ++k) \
;         acc[ai][bj][m][n] = __builtin_amdgcn_mfma_f32_16x16x32_bf16(Bt[n][k], At[m][k], acc[ai][bj][m][n], 0, 0, 0); __builtin_amdgcn_s_setprio(0); } while (0)
; #define PG8_WAIT_V(n) asm volatile("s_waitcnt vmcnt(" #n ")" ::: "memory")
; #define PG8_WAIT_L(n) asm volatile("s_waitcnt lgkmcnt(" #n ")" ::: "memory")
; template <class Epi, class Sched, bool ALIGN_EPI = false, bool SP2 = false>
; __device__ __forceinline__ void gemm_phase(PG8_LAS unsigned char* lds, const Gemm g, const Sched& S, const Epi& E, const int tid) {
;     ...
;             const bool last = (t == nt - 2);
;             const char* a1 = cA + (size_t)(t + 1) * kstep;
;             const char* a2 = last ? nA : cA + (size_t)(t + 2) * kstep; const char* b2 = last ? nB : cB + (size_t)(t + 2) * kstep;
;             const char* a3 = a2 + kstep; const char* b3 = b2 + kstep;
;             if (last && has_next) S.a_ready(nxt);
;             if constexpr (SP2) {
;             PG8_LDB(B0, 0, 0); PG8_LDB(B1, 0, 1); PG8_SCHED; PG8_LDA(At, 0, 0); PG8_STAGE(PG8_SA(1, 1), a1 + hstepA, voffA);
;             PG8_WAIT_V(8); PG8_WAIT_L(0); PG8_BAR; PG8_MMA(0, 0, At, B0); PG8_MMA(0, 1, At, B1); PG8_BAR; PG8_SCHED;
;             PG8_LDA(At, 0, 1); PG8_STAGE(PG8_SB(0, 0), b2, voffB); PG8_STAGE(PG8_SB(0, 1), b2 + hstep, voffB); PG8_STAGE(PG8_SA(0, 0), a2, voffA);
;             PG8_WAIT_V(8); PG8_WAIT_L(0); PG8_BAR; PG8_MMA(1, 0, At, B0); PG8_MMA(1, 1, At, B1); PG8_BAR; PG8_SCHED;
.Lsp_5:
	ds_read_b128 v[144:147], v166
	ds_read_b128 v[148:151], v166 offset:1024
	ds_read_b128 v[152:155], v166 offset:2048
	ds_read_b128 v[156:159], v166 offset:3072
	ds_read_b128 v[160:163], v167
	ds_read_b128 v[172:175], v167 offset:1024
	ds_read_b128 v[176:179], v167 offset:2048
	ds_read_b128 v[180:183], v167 offset:3072
	s_add_u32 s28, s26, 0x100
	s_addc_u32 s29, s27, 0
	s_cmp_eq_u32 s63, 40
	s_cselect_b32 s35, s7, s29
	s_cselect_b32 s34, s6, s28
	s_cselect_b32 s31, s25, s62
	s_cselect_b32 s30, s24, s61
	s_add_i32 m0, s42, 0xc000
	ds_read_b128 v[184:187], v168
	ds_read_b128 v[188:191], v168 offset:1024
	ds_read_b128 v[192:195], v168 offset:2048
	ds_read_b128 v[200:203], v168 offset:3072
	ds_read_b128 v[204:207], v168 offset:4096
	ds_read_b128 v[208:211], v168 offset:5120
	ds_read_b128 v[212:215], v168 offset:6144
	ds_read_b128 v[216:219], v168 offset:7168
	global_load_lds_dwordx4 v136, s[26:27]
	s_add_i32 m0, s42, 0xe000
	s_nop 0
	global_load_lds_dwordx4 v138, s[26:27]
	s_waitcnt vmcnt(8)
	s_waitcnt lgkmcnt(0)
	s_barrier
	s_waitcnt lgkmcnt(0)
	v_mfma_f32_16x16x32_bf16 v[124:127], v[144:147], v[184:187], v[124:127]
	v_mfma_f32_16x16x32_bf16 v[120:123], v[152:155], v[184:187], v[120:123]
	v_mfma_f32_16x16x32_bf16 v[108:111], v[144:147], v[192:195], v[108:111]
	v_mfma_f32_16x16x32_bf16 v[104:107], v[152:155], v[192:195], v[104:107]
	v_mfma_f32_16x16x32_bf16 v[92:95], v[144:147], v[204:207], v[92:95]
	v_mfma_f32_16x16x32_bf16 v[88:91], v[152:155], v[204:207], v[88:91]
	v_mfma_f32_16x16x32_bf16 v[76:79], v[144:147], v[212:215], v[76:79]
	v_mfma_f32_16x16x32_bf16 v[72:75], v[152:155], v[212:215], v[72:75]
	v_mfma_f32_16x16x32_bf16 v[124:127], v[148:151], v[188:191], v[124:127]
	v_mfma_f32_16x16x32_bf16 v[120:123], v[156:159], v[188:191], v[120:123]
	v_mfma_f32_16x16x32_bf16 v[108:111], v[148:151], v[200:203], v[108:111]
	v_mfma_f32_16x16x32_bf16 v[104:107], v[156:159], v[200:203], v[104:107]
	v_mfma_f32_16x16x32_bf16 v[92:95], v[148:151], v[208:211], v[92:95]
	v_mfma_f32_16x16x32_bf16 v[88:91], v[156:159], v[208:211], v[88:91]
	v_mfma_f32_16x16x32_bf16 v[76:79], v[148:151], v[216:219], v[76:79]
	v_mfma_f32_16x16x32_bf16 v[72:75], v[156:159], v[216:219], v[72:75]
	v_mfma_f32_16x16x32_bf16 v[116:119], v[160:163], v[184:187], v[116:119]
	v_mfma_f32_16x16x32_bf16 v[112:115], v[176:179], v[184:187], v[112:115]
	v_mfma_f32_16x16x32_bf16 v[100:103], v[160:163], v[192:195], v[100:103]
	v_mfma_f32_16x16x32_bf16 v[96:99], v[176:179], v[192:195], v[96:99]
	v_mfma_f32_16x16x32_bf16 v[84:87], v[160:163], v[204:207], v[84:87]
	v_mfma_f32_16x16x32_bf16 v[80:83], v[176:179], v[204:207], v[80:83]
	v_mfma_f32_16x16x32_bf16 v[68:71], v[160:163], v[212:215], v[68:71]
	v_mfma_f32_16x16x32_bf16 v[64:67], v[176:179], v[212:215], v[64:67]
	v_mfma_f32_16x16x32_bf16 v[116:119], v[172:175], v[188:191], v[116:119]
	v_mfma_f32_16x16x32_bf16 v[112:115], v[180:183], v[188:191], v[112:115]
	v_mfma_f32_16x16x32_bf16 v[100:103], v[172:175], v[200:203], v[100:103]
	v_mfma_f32_16x16x32_bf16 v[96:99], v[180:183], v[200:203], v[96:99]
	v_mfma_f32_16x16x32_bf16 v[84:87], v[172:175], v[208:211], v[84:87]
	v_mfma_f32_16x16x32_bf16 v[80:83], v[180:183], v[208:211], v[80:83]
	v_mfma_f32_16x16x32_bf16 v[68:71], v[172:175], v[216:219], v[68:71]
	v_mfma_f32_16x16x32_bf16 v[64:67], v[180:183], v[216:219], v[64:67]
	s_barrier
	s_mov_b32 m0, s38
	s_mov_b64 s[98:99], s[30:31]
	s_add_u32 s26, s30, 0xb0000
	ds_read_b128 v[184:187], v168 offset:16384
	ds_read_b128 v[188:191], v168 offset:17408
	ds_read_b128 v[192:195], v168 offset:18432
	ds_read_b128 v[200:203], v168 offset:19456
	ds_read_b128 v[204:207], v168 offset:20480
	ds_read_b128 v[208:211], v168 offset:21504
	ds_read_b128 v[212:215], v168 offset:22528
	ds_read_b128 v[216:219], v168 offset:23552
	global_load_lds_dwordx4 v130, s[30:31]
	s_mov_b32 m0, s39
	s_addc_u32 s27, s31, 0
	global_load_lds_dwordx4 v134, s[30:31]
	s_mov_b32 m0, s40
	s_nop 0
	global_load_lds_dwordx4 v130, s[26:27]
	s_mov_b32 m0, s41
	s_nop 0
	global_load_lds_dwordx4 v134, s[26:27]
	s_mov_b64 s[100:101], s[34:35]
	s_mov_b32 m0, s42
	s_nop 0
	global_load_lds_dwordx4 v128, s[34:35]
	s_mov_b32 m0, s43
	s_nop 0
	global_load_lds_dwordx4 v132, s[34:35]
	s_waitcnt vmcnt(8)
	s_waitcnt lgkmcnt(0)
	s_barrier
	s_waitcnt lgkmcnt(0)
	v_mfma_f32_16x16x32_bf16 v[60:63], v[144:147], v[184:187], v[60:63]
	v_mfma_f32_16x16x32_bf16 v[56:59], v[152:155], v[184:187], v[56:59]
	v_mfma_f32_16x16x32_bf16 v[44:47], v[144:147], v[192:195], v[44:47]
	v_mfma_f32_16x16x32_bf16 v[40:43], v[152:155], v[192:195], v[40:43]
	v_mfma_f32_16x16x32_bf16 v[28:31], v[144:147], v[204:207], v[28:31]
	v_mfma_f32_16x16x32_bf16 v[24:27], v[152:155], v[204:207], v[24:27]
	v_mfma_f32_16x16x32_bf16 v[12:15], v[144:147], v[212:215], v[12:15]
	v_mfma_f32_16x16x32_bf16 v[8:11], v[152:155], v[212:215], v[8:11]
	v_mfma_f32_16x16x32_bf16 v[60:63], v[148:151], v[188:191], v[60:63]
	v_mfma_f32_16x16x32_bf16 v[56:59], v[156:159], v[188:191], v[56:59]
	v_mfma_f32_16x16x32_bf16 v[44:47], v[148:151], v[200:203], v[44:47]
	v_mfma_f32_16x16x32_bf16 v[40:43], v[156:159], v[200:203], v[40:43]
	v_mfma_f32_16x16x32_bf16 v[28:31], v[148:151], v[208:211], v[28:31]
	v_mfma_f32_16x16x32_bf16 v[24:27], v[156:159], v[208:211], v[24:27]
	v_mfma_f32_16x16x32_bf16 v[12:15], v[148:151], v[216:219], v[12:15]
	v_mfma_f32_16x16x32_bf16 v[8:11], v[156:159], v[216:219], v[8:11]
	v_mfma_f32_16x16x32_bf16 v[52:55], v[160:163], v[184:187], v[52:55]
	v_mfma_f32_16x16x32_bf16 v[48:51], v[176:179], v[184:187], v[48:51]
	v_mfma_f32_16x16x32_bf16 v[36:39], v[160:163], v[192:195], v[36:39]
	v_mfma_f32_16x16x32_bf16 v[32:35], v[176:179], v[192:195], v[32:35]
	v_mfma_f32_16x16x32_bf16 v[20:23], v[160:163], v[204:207], v[20:23]
	v_mfma_f32_16x16x32_bf16 v[16:19], v[176:179], v[204:207], v[16:19]
	v_mfma_f32_16x16x32_bf16 v[4:7], v[160:163], v[212:215], v[4:7]
	v_mfma_f32_16x16x32_bf16 v[0:3], v[176:179], v[212:215], v[0:3]
	v_mfma_f32_16x16x32_bf16 v[52:55], v[172:175], v[188:191], v[52:55]
	v_mfma_f32_16x16x32_bf16 v[48:51], v[180:183], v[188:191], v[48:51]
	v_mfma_f32_16x16x32_bf16 v[36:39], v[172:175], v[200:203], v[36:39]
	v_mfma_f32_16x16x32_bf16 v[32:35], v[180:183], v[200:203], v[32:35]
	v_mfma_f32_16x16x32_bf16 v[20:23], v[172:175], v[208:211], v[20:23]
	v_mfma_f32_16x16x32_bf16 v[16:19], v[180:183], v[208:211], v[16:19]
	v_mfma_f32_16x16x32_bf16 v[4:7], v[172:175], v[216:219], v[4:7]
	v_mfma_f32_16x16x32_bf16 v[0:3], v[180:183], v[216:219], v[0:3]
	s_barrier
; #define PG8_STAGE(bufoff, gbase, voff) do { _Pragma("unroll") for (int _i = 0; _i < 2; ++_i) \
;         __builtin_amdgcn_global_load_lds((const unsigned*)((const char*)(gbase) + (voff)[_i]), (PG8_LAS unsigned*)(lds + (bufoff) + ldsw + _i * 8192), 16, 0, 0); } while (0)
; #define PG8_LDA(dst, b, h) do { _Pragma("unroll") for (int m = 0; m < 4; ++m) _Pragma("unroll") for (int k = 0; k < 2; ++k) dst[m][k] = *(const PG8_LAS bf16x8*)(lds + PG8_SA(b, h) + aoff + m * 2048 + k * 1024); } while (0)
; #define PG8_LDB(dst, b, h) do { _Pragma("unroll") for (int n = 0; n < 2; ++n) _Pragma("unroll") for (int k = 0; k < 2; ++k) dst[n][k] = *(const PG8_LAS bf16x8*)(lds + PG8_SB(b, h) + boff + n * 2048 + k * 1024); } while (0)
; #define PG8_MMA(ai, bj, At, Bt) do { __builtin_amdgcn_s_setprio(1); _Pragma("unroll") for (int m = 0; m < 4; ++m) _Pragma("unroll") for (int n = 0; n < 2; ++n) _Pragma("unroll") for (int k = 0; k < 2; ++k) \
;         acc[ai][bj][m][n] = __builtin_amdgcn_mfma_f32_16x16x32_bf16(Bt[n][k], At[m][k], acc[ai][bj][m][n], 0, 0, 0); __builtin_amdgcn_s_setprio(0); } while (0)
; #define PG8_WAIT_V(n) asm volatile("s_waitcnt vmcnt(" #n ")" ::: "memory")
; #define PG8_WAIT_L(n) asm volatile("s_waitcnt lgkmcnt(" #n ")" ::: "memory")
; #define PG8_BAR __builtin_amdgcn_s_barrier()
; #define PG8_SCHED __builtin_amdgcn_sched_barrier(0)
; template <class Epi, class Sched, bool ALIGN_EPI = false, bool SP2 = false>
; __device__ __forceinline__ void gemm_phase(PG8_LAS unsigned char* lds, const Gemm g, const Sched& S, const Epi& E, const int tid) {
;     ...
;             PG8_LDB(B0, 1, 0); PG8_LDB(B1, 1, 1); PG8_SCHED; PG8_LDA(At, 1, 0); PG8_STAGE(PG8_SA(0, 1), a2 + hstepA, voffA);
;             PG8_WAIT_V(8); PG8_WAIT_L(0); PG8_BAR; PG8_MMA(0, 0, At, B0); PG8_MMA(0, 1, At, B1); PG8_BAR; PG8_SCHED;
;             PG8_LDA(At, 1, 1); PG8_STAGE(PG8_SB(1, 0), b3, voffB); PG8_STAGE(PG8_SB(1, 1), b3 + hstep, voffB); PG8_STAGE(PG8_SA(1, 0), a3, voffA);
;             PG8_WAIT_V(8); PG8_WAIT_L(0); PG8_BAR; PG8_MMA(1, 0, At, B0); PG8_MMA(1, 1, At, B1); PG8_BAR; PG8_SCHED;
	ds_read_b128 v[144:147], v169
	ds_read_b128 v[148:151], v169 offset:1024
	ds_read_b128 v[152:155], v169 offset:2048
	ds_read_b128 v[156:159], v169 offset:3072
	ds_read_b128 v[160:163], v170
	ds_read_b128 v[172:175], v170 offset:1024
	ds_read_b128 v[176:179], v170 offset:2048
	ds_read_b128 v[180:183], v170 offset:3072
	s_add_u32 s26, s34, 0xb0000
	s_addc_u32 s27, s35, 0
	s_mov_b32 m0, s44
	ds_read_b128 v[184:187], v168 offset:32768
	ds_read_b128 v[188:191], v168 offset:33792
	ds_read_b128 v[192:195], v168 offset:34816
	ds_read_b128 v[200:203], v168 offset:35840
	ds_read_b128 v[204:207], v168 offset:36864
	ds_read_b128 v[208:211], v168 offset:37888
	ds_read_b128 v[212:215], v168 offset:38912
	ds_read_b128 v[216:219], v168 offset:39936
	global_load_lds_dwordx4 v128, s[26:27]
	s_mov_b32 m0, s45
	s_nop 0
	global_load_lds_dwordx4 v132, s[26:27]
	s_waitcnt vmcnt(8)
	s_waitcnt lgkmcnt(0)
	s_barrier
	s_waitcnt lgkmcnt(0)
	v_mfma_f32_16x16x32_bf16 v[124:127], v[144:147], v[184:187], v[124:127]
	v_mfma_f32_16x16x32_bf16 v[120:123], v[152:155], v[184:187], v[120:123]
	v_mfma_f32_16x16x32_bf16 v[108:111], v[144:147], v[192:195], v[108:111]
	v_mfma_f32_16x16x32_bf16 v[104:107], v[152:155], v[192:195], v[104:107]
	v_mfma_f32_16x16x32_bf16 v[92:95], v[144:147], v[204:207], v[92:95]
	v_mfma_f32_16x16x32_bf16 v[88:91], v[152:155], v[204:207], v[88:91]
	v_mfma_f32_16x16x32_bf16 v[76:79], v[144:147], v[212:215], v[76:79]
	v_mfma_f32_16x16x32_bf16 v[72:75], v[152:155], v[212:215], v[72:75]
	v_mfma_f32_16x16x32_bf16 v[124:127], v[148:151], v[188:191], v[124:127]
	v_mfma_f32_16x16x32_bf16 v[120:123], v[156:159], v[188:191], v[120:123]
	v_mfma_f32_16x16x32_bf16 v[108:111], v[148:151], v[200:203], v[108:111]
	v_mfma_f32_16x16x32_bf16 v[104:107], v[156:159], v[200:203], v[104:107]
	v_mfma_f32_16x16x32_bf16 v[92:95], v[148:151], v[208:211], v[92:95]
	v_mfma_f32_16x16x32_bf16 v[88:91], v[156:159], v[208:211], v[88:91]
	v_mfma_f32_16x16x32_bf16 v[76:79], v[148:151], v[216:219], v[76:79]
	v_mfma_f32_16x16x32_bf16 v[72:75], v[156:159], v[216:219], v[72:75]
	v_mfma_f32_16x16x32_bf16 v[116:119], v[160:163], v[184:187], v[116:119]
	v_mfma_f32_16x16x32_bf16 v[112:115], v[176:179], v[184:187], v[112:115]
	v_mfma_f32_16x16x32_bf16 v[100:103], v[160:163], v[192:195], v[100:103]
	v_mfma_f32_16x16x32_bf16 v[96:99], v[176:179], v[192:195], v[96:99]
	v_mfma_f32_16x16x32_bf16 v[84:87], v[160:163], v[204:207], v[84:87]
	v_mfma_f32_16x16x32_bf16 v[80:83], v[176:179], v[204:207], v[80:83]
	v_mfma_f32_16x16x32_bf16 v[68:71], v[160:163], v[212:215], v[68:71]
	v_mfma_f32_16x16x32_bf16 v[64:67], v[176:179], v[212:215], v[64:67]
	v_mfma_f32_16x16x32_bf16 v[116:119], v[172:175], v[188:191], v[116:119]
	v_mfma_f32_16x16x32_bf16 v[112:115], v[180:183], v[188:191], v[112:115]
	v_mfma_f32_16x16x32_bf16 v[100:103], v[172:175], v[200:203], v[100:103]
	v_mfma_f32_16x16x32_bf16 v[96:99], v[180:183], v[200:203], v[96:99]
	v_mfma_f32_16x16x32_bf16 v[84:87], v[172:175], v[208:211], v[84:87]
	v_mfma_f32_16x16x32_bf16 v[80:83], v[180:183], v[208:211], v[80:83]
	v_mfma_f32_16x16x32_bf16 v[68:71], v[172:175], v[216:219], v[68:71]
	v_mfma_f32_16x16x32_bf16 v[64:67], v[180:183], v[216:219], v[64:67]
	s_barrier
	s_mov_b32 m0, s48
	s_add_u32 s98, s98, s18
	s_addc_u32 s99, s99, s19
	s_add_u32 s26, s30, 0xb0080
	ds_read_b128 v[184:187], v168 offset:49152
	ds_read_b128 v[188:191], v168 offset:50176
	ds_read_b128 v[192:195], v168 offset:51200
	ds_read_b128 v[200:203], v168 offset:52224
	ds_read_b128 v[204:207], v168 offset:53248
	ds_read_b128 v[208:211], v168 offset:54272
	ds_read_b128 v[212:215], v168 offset:55296
	ds_read_b128 v[216:219], v168 offset:56320
	global_load_lds_dwordx4 v130, s[98:99]
	s_mov_b32 m0, s49
	s_addc_u32 s27, s31, 0
	global_load_lds_dwordx4 v134, s[98:99]
	s_mov_b32 m0, s52
	s_nop 0
	global_load_lds_dwordx4 v130, s[26:27]
	s_mov_b32 m0, s53
	s_nop 0
	global_load_lds_dwordx4 v134, s[26:27]
	s_add_u32 s100, s100, s18
	s_addc_u32 s101, s101, s19
	s_mov_b32 m0, s50
	s_nop 0
	global_load_lds_dwordx4 v128, s[100:101]
	s_mov_b32 m0, s51
	s_nop 0
	global_load_lds_dwordx4 v132, s[100:101]
	s_waitcnt vmcnt(8)
	s_waitcnt lgkmcnt(0)
	s_barrier
	s_waitcnt lgkmcnt(0)
	v_mfma_f32_16x16x32_bf16 v[60:63], v[144:147], v[184:187], v[60:63]
	v_mfma_f32_16x16x32_bf16 v[56:59], v[152:155], v[184:187], v[56:59]
	v_mfma_f32_16x16x32_bf16 v[44:47], v[144:147], v[192:195], v[44:47]
	v_mfma_f32_16x16x32_bf16 v[40:43], v[152:155], v[192:195], v[40:43]
	v_mfma_f32_16x16x32_bf16 v[28:31], v[144:147], v[204:207], v[28:31]
	v_mfma_f32_16x16x32_bf16 v[24:27], v[152:155], v[204:207], v[24:27]
	v_mfma_f32_16x16x32_bf16 v[12:15], v[144:147], v[212:215], v[12:15]
	v_mfma_f32_16x16x32_bf16 v[8:11], v[152:155], v[212:215], v[8:11]
	v_mfma_f32_16x16x32_bf16 v[60:63], v[148:151], v[188:191], v[60:63]
	v_mfma_f32_16x16x32_bf16 v[56:59], v[156:159], v[188:191], v[56:59]
	v_mfma_f32_16x16x32_bf16 v[44:47], v[148:151], v[200:203], v[44:47]
	v_mfma_f32_16x16x32_bf16 v[40:43], v[156:159], v[200:203], v[40:43]
	v_mfma_f32_16x16x32_bf16 v[28:31], v[148:151], v[208:211], v[28:31]
	v_mfma_f32_16x16x32_bf16 v[24:27], v[156:159], v[208:211], v[24:27]
	v_mfma_f32_16x16x32_bf16 v[12:15], v[148:151], v[216:219], v[12:15]
	v_mfma_f32_16x16x32_bf16 v[8:11], v[156:159], v[216:219], v[8:11]
	v_mfma_f32_16x16x32_bf16 v[52:55], v[160:163], v[184:187], v[52:55]
	v_mfma_f32_16x16x32_bf16 v[48:51], v[176:179], v[184:187], v[48:51]
	v_mfma_f32_16x16x32_bf16 v[36:39], v[160:163], v[192:195], v[36:39]
	v_mfma_f32_16x16x32_bf16 v[32:35], v[176:179], v[192:195], v[32:35]
	v_mfma_f32_16x16x32_bf16 v[20:23], v[160:163], v[204:207], v[20:23]
	v_mfma_f32_16x16x32_bf16 v[16:19], v[176:179], v[204:207], v[16:19]
	v_mfma_f32_16x16x32_bf16 v[4:7], v[160:163], v[212:215], v[4:7]
	v_mfma_f32_16x16x32_bf16 v[0:3], v[176:179], v[212:215], v[0:3]
	v_mfma_f32_16x16x32_bf16 v[52:55], v[172:175], v[188:191], v[52:55]
	v_mfma_f32_16x16x32_bf16 v[48:51], v[180:183], v[188:191], v[48:51]
	v_mfma_f32_16x16x32_bf16 v[36:39], v[172:175], v[200:203], v[36:39]
	v_mfma_f32_16x16x32_bf16 v[32:35], v[180:183], v[200:203], v[32:35]
	v_mfma_f32_16x16x32_bf16 v[20:23], v[172:175], v[208:211], v[20:23]
	v_mfma_f32_16x16x32_bf16 v[16:19], v[180:183], v[208:211], v[16:19]
	v_mfma_f32_16x16x32_bf16 v[4:7], v[172:175], v[216:219], v[4:7]
	v_mfma_f32_16x16x32_bf16 v[0:3], v[180:183], v[216:219], v[0:3]
	s_barrier
	s_add_i32 s63, s63, 2
	s_add_u32 s61, s61, 0x100
	s_addc_u32 s62, s62, 0
	s_cmp_gt_u32 s63, 41
	s_mov_b64 s[26:27], s[28:29]
	s_cbranch_scc0 .LBB0_923
	s_setprio 0
	s_and_b64 vcc, exec, s[20:21]
	s_cbranch_vccnz .LBB0_927
	s_andn2_b64 vcc, exec, s[22:23]
	s_cbranch_vccz .LBB0_928

; #define PG8_STAGE(bufoff, gbase, voff) do { _Pragma("unroll") for (int _i = 0; _i < 2; ++_i) \
;         __builtin_amdgcn_global_load_lds((const unsigned*)((const char*)(gbase) + (voff)[_i]), (PG8_LAS unsigned*)(lds + (bufoff) + ldsw + _i * 8192), 16, 0, 0); } while (0)
; #define PG8_LDA(dst, b, h) do { _Pragma("unroll") for (int m = 0; m < 4; ++m) _Pragma("unroll") for (int k = 0; k < 2; ++k) dst[m][k] = *(const PG8_LAS bf16x8*)(lds + PG8_SA(b, h) + aoff + m * 2048 + k * 1024); } while (0)
; #define PG8_LDB(dst, b, h) do { _Pragma("unroll") for (int n = 0; n < 2; ++n) _Pragma("unroll") for (int k = 0; k < 2; ++k) dst[n][k] = *(const PG8_LAS bf16x8*)(lds + PG8_SB(b, h) + boff + n * 2048 + k * 1024); } while (0)
; #define PG8_MMA(ai, bj, At, Bt) do { __builtin_amdgcn_s_setprio(1); _Pragma("unroll") for (int m = 0; m < 4; ++m) _Pragma("unroll") for (int n = 0; n < 2; ++n) _Pragma("unroll") for (int k = 0; k < 2; ++k) \
;         acc[ai][bj][m][n] = __builtin_amdgcn_mfma_f32_16x16x32_bf16(Bt[n][k], At[m][k], acc[ai][bj][m][n], 0, 0, 0); __builtin_amdgcn_s_setprio(0); } while (0)
; #define PG8_WAIT_V(n) asm volatile("s_waitcnt vmcnt(" #n ")" ::: "memory")
; #define PG8_WAIT_L(n) asm volatile("s_waitcnt lgkmcnt(" #n ")" ::: "memory")
; #define PG8_BAR __builtin_amdgcn_s_barrier()
; #define PG8_SCHED __builtin_amdgcn_sched_barrier(0)
; template <class Epi, class Sched, bool ALIGN_EPI = false, bool SP2 = false>
; __device__ __forceinline__ void gemm_phase(PG8_LAS unsigned char* lds, const Gemm g, const Sched& S, const Epi& E, const int tid) {
;     ...
;             PG8_LDB(B0, 0, 0); PG8_LDB(B1, 0, 1); PG8_SCHED; PG8_LDA(At, 0, 0); PG8_STAGE(PG8_SA(1, 1), a1 + hstepA, voffA);
;             PG8_WAIT_V(8); PG8_WAIT_L(0); PG8_BAR; PG8_MMA(0, 0, At, B0); PG8_MMA(0, 1, At, B1); PG8_BAR; PG8_SCHED;
;             PG8_LDA(At, 0, 1); PG8_STAGE(PG8_SB(0, 0), b2, voffB); PG8_STAGE(PG8_SB(0, 1), b2 + hstep, voffB); PG8_STAGE(PG8_SA(0, 0), a2, voffA);
;             PG8_WAIT_V(8); PG8_WAIT_L(0); PG8_BAR; PG8_MMA(1, 0, At, B0); PG8_MMA(1, 1, At, B1); PG8_BAR; PG8_SCHED;
.Lsp_6:
	ds_read_b128 v[144:147], v156
	ds_read_b128 v[148:151], v156 offset:1024
	ds_read_b128 v[162:165], v156 offset:2048
	ds_read_b128 v[166:169], v156 offset:3072
	ds_read_b128 v[170:173], v157
	ds_read_b128 v[174:177], v157 offset:1024
	ds_read_b128 v[178:181], v157 offset:2048
	ds_read_b128 v[182:185], v157 offset:3072
	s_add_u32 s28, s26, 0xfffc0080
	s_addc_u32 s29, s27, -1
	s_cmp_eq_u32 s60, 12
	s_cselect_b32 s31, s19, s29
	s_cselect_b32 s30, s56, s28
	s_cselect_b32 s29, s17, s59
	s_cselect_b32 s28, s57, s58
	s_add_i32 m0, s41, 0xc000
	ds_read_b128 v[186:189], v158
	ds_read_b128 v[190:193], v158 offset:1024
	ds_read_b128 v[194:197], v158 offset:2048
	ds_read_b128 v[200:203], v158 offset:3072
	ds_read_b128 v[204:207], v158 offset:4096
	ds_read_b128 v[208:211], v158 offset:5120
	ds_read_b128 v[212:215], v158 offset:6144
	ds_read_b128 v[216:219], v158 offset:7168
	global_load_lds_dwordx4 v136, s[26:27]
	s_add_i32 m0, s41, 0xe000
	s_nop 0
	global_load_lds_dwordx4 v138, s[26:27]
	s_waitcnt vmcnt(8)
	s_waitcnt lgkmcnt(0)
	s_barrier
	s_waitcnt lgkmcnt(0)
	v_mfma_f32_16x16x32_bf16 v[124:127], v[144:147], v[186:189], v[124:127]
	v_mfma_f32_16x16x32_bf16 v[120:123], v[162:165], v[186:189], v[120:123]
	v_mfma_f32_16x16x32_bf16 v[108:111], v[144:147], v[194:197], v[108:111]
	v_mfma_f32_16x16x32_bf16 v[104:107], v[162:165], v[194:197], v[104:107]
	v_mfma_f32_16x16x32_bf16 v[92:95], v[144:147], v[204:207], v[92:95]
	v_mfma_f32_16x16x32_bf16 v[88:91], v[162:165], v[204:207], v[88:91]
	v_mfma_f32_16x16x32_bf16 v[76:79], v[144:147], v[212:215], v[76:79]
	v_mfma_f32_16x16x32_bf16 v[72:75], v[162:165], v[212:215], v[72:75]
	v_mfma_f32_16x16x32_bf16 v[124:127], v[148:151], v[190:193], v[124:127]
	v_mfma_f32_16x16x32_bf16 v[120:123], v[166:169], v[190:193], v[120:123]
	v_mfma_f32_16x16x32_bf16 v[108:111], v[148:151], v[200:203], v[108:111]
	v_mfma_f32_16x16x32_bf16 v[104:107], v[166:169], v[200:203], v[104:107]
	v_mfma_f32_16x16x32_bf16 v[92:95], v[148:151], v[208:211], v[92:95]
	v_mfma_f32_16x16x32_bf16 v[88:91], v[166:169], v[208:211], v[88:91]
	v_mfma_f32_16x16x32_bf16 v[76:79], v[148:151], v[216:219], v[76:79]
	v_mfma_f32_16x16x32_bf16 v[72:75], v[166:169], v[216:219], v[72:75]
	v_mfma_f32_16x16x32_bf16 v[116:119], v[170:173], v[186:189], v[116:119]
	v_mfma_f32_16x16x32_bf16 v[112:115], v[178:181], v[186:189], v[112:115]
	v_mfma_f32_16x16x32_bf16 v[100:103], v[170:173], v[194:197], v[100:103]
	v_mfma_f32_16x16x32_bf16 v[96:99], v[178:181], v[194:197], v[96:99]
	v_mfma_f32_16x16x32_bf16 v[84:87], v[170:173], v[204:207], v[84:87]
	v_mfma_f32_16x16x32_bf16 v[80:83], v[178:181], v[204:207], v[80:83]
	v_mfma_f32_16x16x32_bf16 v[68:71], v[170:173], v[212:215], v[68:71]
	v_mfma_f32_16x16x32_bf16 v[64:67], v[178:181], v[212:215], v[64:67]
	v_mfma_f32_16x16x32_bf16 v[116:119], v[174:177], v[190:193], v[116:119]
	v_mfma_f32_16x16x32_bf16 v[112:115], v[182:185], v[190:193], v[112:115]
	v_mfma_f32_16x16x32_bf16 v[100:103], v[174:177], v[200:203], v[100:103]
	v_mfma_f32_16x16x32_bf16 v[96:99], v[182:185], v[200:203], v[96:99]
	v_mfma_f32_16x16x32_bf16 v[84:87], v[174:177], v[208:211], v[84:87]
	v_mfma_f32_16x16x32_bf16 v[80:83], v[182:185], v[208:211], v[80:83]
	v_mfma_f32_16x16x32_bf16 v[68:71], v[174:177], v[216:219], v[68:71]
	v_mfma_f32_16x16x32_bf16 v[64:67], v[182:185], v[216:219], v[64:67]
	s_barrier
	s_mov_b32 m0, s25
	s_mov_b64 s[98:99], s[28:29]
	s_add_u32 s62, s28, 0x40000
	ds_read_b128 v[186:189], v158 offset:16384
	ds_read_b128 v[190:193], v158 offset:17408
	ds_read_b128 v[194:197], v158 offset:18432
	ds_read_b128 v[200:203], v158 offset:19456
	ds_read_b128 v[204:207], v158 offset:20480
	ds_read_b128 v[208:211], v158 offset:21504
	ds_read_b128 v[212:215], v158 offset:22528
	ds_read_b128 v[216:219], v158 offset:23552
	global_load_lds_dwordx4 v132, s[28:29]
	s_mov_b32 m0, s38
	s_addc_u32 s63, s29, 0
	global_load_lds_dwordx4 v128, s[28:29]
	s_mov_b32 m0, s39
	s_nop 0
	global_load_lds_dwordx4 v132, s[62:63]
	s_mov_b32 m0, s40
	s_nop 0
	global_load_lds_dwordx4 v128, s[62:63]
	s_mov_b64 s[100:101], s[30:31]
	s_mov_b32 m0, s41
	s_nop 0
	global_load_lds_dwordx4 v134, s[30:31]
	s_mov_b32 m0, s42
	s_nop 0
	global_load_lds_dwordx4 v130, s[30:31]
	s_waitcnt vmcnt(8)
	s_waitcnt lgkmcnt(0)
	s_barrier
	s_waitcnt lgkmcnt(0)
	v_mfma_f32_16x16x32_bf16 v[60:63], v[144:147], v[186:189], v[60:63]
	v_mfma_f32_16x16x32_bf16 v[56:59], v[162:165], v[186:189], v[56:59]
	v_mfma_f32_16x16x32_bf16 v[44:47], v[144:147], v[194:197], v[44:47]
	v_mfma_f32_16x16x32_bf16 v[40:43], v[162:165], v[194:197], v[40:43]
	v_mfma_f32_16x16x32_bf16 v[28:31], v[144:147], v[204:207], v[28:31]
	v_mfma_f32_16x16x32_bf16 v[24:27], v[162:165], v[204:207], v[24:27]
	v_mfma_f32_16x16x32_bf16 v[12:15], v[144:147], v[212:215], v[12:15]
	v_mfma_f32_16x16x32_bf16 v[8:11], v[162:165], v[212:215], v[8:11]
	v_mfma_f32_16x16x32_bf16 v[60:63], v[148:151], v[190:193], v[60:63]
	v_mfma_f32_16x16x32_bf16 v[56:59], v[166:169], v[190:193], v[56:59]
	v_mfma_f32_16x16x32_bf16 v[44:47], v[148:151], v[200:203], v[44:47]
	v_mfma_f32_16x16x32_bf16 v[40:43], v[166:169], v[200:203], v[40:43]
	v_mfma_f32_16x16x32_bf16 v[28:31], v[148:151], v[208:211], v[28:31]
	v_mfma_f32_16x16x32_bf16 v[24:27], v[166:169], v[208:211], v[24:27]
	v_mfma_f32_16x16x32_bf16 v[12:15], v[148:151], v[216:219], v[12:15]
	v_mfma_f32_16x16x32_bf16 v[8:11], v[166:169], v[216:219], v[8:11]
	v_mfma_f32_16x16x32_bf16 v[52:55], v[170:173], v[186:189], v[52:55]
	v_mfma_f32_16x16x32_bf16 v[48:51], v[178:181], v[186:189], v[48:51]
	v_mfma_f32_16x16x32_bf16 v[36:39], v[170:173], v[194:197], v[36:39]
	v_mfma_f32_16x16x32_bf16 v[32:35], v[178:181], v[194:197], v[32:35]
	v_mfma_f32_16x16x32_bf16 v[20:23], v[170:173], v[204:207], v[20:23]
	v_mfma_f32_16x16x32_bf16 v[16:19], v[178:181], v[204:207], v[16:19]
	v_mfma_f32_16x16x32_bf16 v[4:7], v[170:173], v[212:215], v[4:7]
	v_mfma_f32_16x16x32_bf16 v[0:3], v[178:181], v[212:215], v[0:3]
	v_mfma_f32_16x16x32_bf16 v[52:55], v[174:177], v[190:193], v[52:55]
	v_mfma_f32_16x16x32_bf16 v[48:51], v[182:185], v[190:193], v[48:51]
	v_mfma_f32_16x16x32_bf16 v[36:39], v[174:177], v[200:203], v[36:39]
	v_mfma_f32_16x16x32_bf16 v[32:35], v[182:185], v[200:203], v[32:35]
	v_mfma_f32_16x16x32_bf16 v[20:23], v[174:177], v[208:211], v[20:23]
	v_mfma_f32_16x16x32_bf16 v[16:19], v[182:185], v[208:211], v[16:19]
	v_mfma_f32_16x16x32_bf16 v[4:7], v[174:177], v[216:219], v[4:7]
	v_mfma_f32_16x16x32_bf16 v[0:3], v[182:185], v[216:219], v[0:3]
	s_barrier
; #define PG8_STAGE(bufoff, gbase, voff) do { _Pragma("unroll") for (int _i = 0; _i < 2; ++_i) \
;         __builtin_amdgcn_global_load_lds((const unsigned*)((const char*)(gbase) + (voff)[_i]), (PG8_LAS unsigned*)(lds + (bufoff) + ldsw + _i * 8192), 16, 0, 0); } while (0)
; #define PG8_LDA(dst, b, h) do { _Pragma("unroll") for (int m = 0; m < 4; ++m) _Pragma("unroll") for (int k = 0; k < 2; ++k) dst[m][k] = *(const PG8_LAS bf16x8*)(lds + PG8_SA(b, h) + aoff + m * 2048 + k * 1024); } while (0)
; #define PG8_LDB(dst, b, h) do { _Pragma("unroll") for (int n = 0; n < 2; ++n) _Pragma("unroll") for (int k = 0; k < 2; ++k) dst[n][k] = *(const PG8_LAS bf16x8*)(lds + PG8_SB(b, h) + boff + n * 2048 + k * 1024); } while (0)
; #define PG8_MMA(ai, bj, At, Bt) do { __builtin_amdgcn_s_setprio(1); _Pragma("unroll") for (int m = 0; m < 4; ++m) _Pragma("unroll") for (int n = 0; n < 2; ++n) _Pragma("unroll") for (int k = 0; k < 2; ++k) \
;         acc[ai][bj][m][n] = __builtin_amdgcn_mfma_f32_16x16x32_bf16(Bt[n][k], At[m][k], acc[ai][bj][m][n], 0, 0, 0); __builtin_amdgcn_s_setprio(0); } while (0)
; #define PG8_WAIT_V(n) asm volatile("s_waitcnt vmcnt(" #n ")" ::: "memory")
; #define PG8_WAIT_L(n) asm volatile("s_waitcnt lgkmcnt(" #n ")" ::: "memory")
; #define PG8_BAR __builtin_amdgcn_s_barrier()
; #define PG8_SCHED __builtin_amdgcn_sched_barrier(0)
; template <class Epi, class Sched, bool ALIGN_EPI = false, bool SP2 = false>
; __device__ __forceinline__ void gemm_phase(PG8_LAS unsigned char* lds, const Gemm g, const Sched& S, const Epi& E, const int tid) {
;     ...
;             PG8_LDB(B0, 1, 0); PG8_LDB(B1, 1, 1); PG8_SCHED; PG8_LDA(At, 1, 0); PG8_STAGE(PG8_SA(0, 1), a2 + hstepA, voffA);
;             PG8_WAIT_V(8); PG8_WAIT_L(0); PG8_BAR; PG8_MMA(0, 0, At, B0); PG8_MMA(0, 1, At, B1); PG8_BAR; PG8_SCHED;
;             PG8_LDA(At, 1, 1); PG8_STAGE(PG8_SB(1, 0), b3, voffB); PG8_STAGE(PG8_SB(1, 1), b3 + hstep, voffB); PG8_STAGE(PG8_SA(1, 0), a3, voffA);
;             PG8_WAIT_V(8); PG8_WAIT_L(0); PG8_BAR; PG8_MMA(1, 0, At, B0); PG8_MMA(1, 1, At, B1); PG8_BAR; PG8_SCHED;
	ds_read_b128 v[144:147], v159
	ds_read_b128 v[148:151], v159 offset:1024
	ds_read_b128 v[162:165], v159 offset:2048
	ds_read_b128 v[166:169], v159 offset:3072
	ds_read_b128 v[170:173], v160
	ds_read_b128 v[174:177], v160 offset:1024
	ds_read_b128 v[178:181], v160 offset:2048
	ds_read_b128 v[182:185], v160 offset:3072
	s_add_u32 s30, s30, 0x40000
	s_addc_u32 s31, s31, 0
	s_mov_b32 m0, s43
	ds_read_b128 v[186:189], v158 offset:32768
	ds_read_b128 v[190:193], v158 offset:33792
	ds_read_b128 v[194:197], v158 offset:34816
	ds_read_b128 v[200:203], v158 offset:35840
	ds_read_b128 v[204:207], v158 offset:36864
	ds_read_b128 v[208:211], v158 offset:37888
	ds_read_b128 v[212:215], v158 offset:38912
	ds_read_b128 v[216:219], v158 offset:39936
	global_load_lds_dwordx4 v134, s[30:31]
	s_mov_b32 m0, s44
	s_nop 0
	global_load_lds_dwordx4 v130, s[30:31]
	s_waitcnt vmcnt(8)
	s_waitcnt lgkmcnt(0)
	s_barrier
	s_waitcnt lgkmcnt(0)
	v_mfma_f32_16x16x32_bf16 v[124:127], v[144:147], v[186:189], v[124:127]
	v_mfma_f32_16x16x32_bf16 v[120:123], v[162:165], v[186:189], v[120:123]
	v_mfma_f32_16x16x32_bf16 v[108:111], v[144:147], v[194:197], v[108:111]
	v_mfma_f32_16x16x32_bf16 v[104:107], v[162:165], v[194:197], v[104:107]
	v_mfma_f32_16x16x32_bf16 v[92:95], v[144:147], v[204:207], v[92:95]
	v_mfma_f32_16x16x32_bf16 v[88:91], v[162:165], v[204:207], v[88:91]
	v_mfma_f32_16x16x32_bf16 v[76:79], v[144:147], v[212:215], v[76:79]
	v_mfma_f32_16x16x32_bf16 v[72:75], v[162:165], v[212:215], v[72:75]
	v_mfma_f32_16x16x32_bf16 v[124:127], v[148:151], v[190:193], v[124:127]
	v_mfma_f32_16x16x32_bf16 v[120:123], v[166:169], v[190:193], v[120:123]
	v_mfma_f32_16x16x32_bf16 v[108:111], v[148:151], v[200:203], v[108:111]
	v_mfma_f32_16x16x32_bf16 v[104:107], v[166:169], v[200:203], v[104:107]
	v_mfma_f32_16x16x32_bf16 v[92:95], v[148:151], v[208:211], v[92:95]
	v_mfma_f32_16x16x32_bf16 v[88:91], v[166:169], v[208:211], v[88:91]
	v_mfma_f32_16x16x32_bf16 v[76:79], v[148:151], v[216:219], v[76:79]
	v_mfma_f32_16x16x32_bf16 v[72:75], v[166:169], v[216:219], v[72:75]
	v_mfma_f32_16x16x32_bf16 v[116:119], v[170:173], v[186:189], v[116:119]
	v_mfma_f32_16x16x32_bf16 v[112:115], v[178:181], v[186:189], v[112:115]
	v_mfma_f32_16x16x32_bf16 v[100:103], v[170:173], v[194:197], v[100:103]
	v_mfma_f32_16x16x32_bf16 v[96:99], v[178:181], v[194:197], v[96:99]
	v_mfma_f32_16x16x32_bf16 v[84:87], v[170:173], v[204:207], v[84:87]
	v_mfma_f32_16x16x32_bf16 v[80:83], v[178:181], v[204:207], v[80:83]
	v_mfma_f32_16x16x32_bf16 v[68:71], v[170:173], v[212:215], v[68:71]
	v_mfma_f32_16x16x32_bf16 v[64:67], v[178:181], v[212:215], v[64:67]
	v_mfma_f32_16x16x32_bf16 v[116:119], v[174:177], v[190:193], v[116:119]
	v_mfma_f32_16x16x32_bf16 v[112:115], v[182:185], v[190:193], v[112:115]
	v_mfma_f32_16x16x32_bf16 v[100:103], v[174:177], v[200:203], v[100:103]
	v_mfma_f32_16x16x32_bf16 v[96:99], v[182:185], v[200:203], v[96:99]
	v_mfma_f32_16x16x32_bf16 v[84:87], v[174:177], v[208:211], v[84:87]
	v_mfma_f32_16x16x32_bf16 v[80:83], v[182:185], v[208:211], v[80:83]
	v_mfma_f32_16x16x32_bf16 v[68:71], v[174:177], v[216:219], v[68:71]
	v_mfma_f32_16x16x32_bf16 v[64:67], v[182:185], v[216:219], v[64:67]
	s_barrier
	s_mov_b32 m0, s47
	s_add_u32 s98, s98, s12
	s_addc_u32 s99, s99, s13
	s_add_u32 s28, s28, 0x40080
	ds_read_b128 v[186:189], v158 offset:49152
	ds_read_b128 v[190:193], v158 offset:50176
	ds_read_b128 v[194:197], v158 offset:51200
	ds_read_b128 v[200:203], v158 offset:52224
	ds_read_b128 v[204:207], v158 offset:53248
	ds_read_b128 v[208:211], v158 offset:54272
	ds_read_b128 v[212:215], v158 offset:55296
	ds_read_b128 v[216:219], v158 offset:56320
	global_load_lds_dwordx4 v132, s[98:99]
	s_mov_b32 m0, s48
	s_addc_u32 s29, s29, 0
	global_load_lds_dwordx4 v128, s[98:99]
	s_mov_b32 m0, s51
	s_nop 0
	global_load_lds_dwordx4 v132, s[28:29]
	s_mov_b32 m0, s52
	s_nop 0
	global_load_lds_dwordx4 v128, s[28:29]
	s_add_u32 s100, s100, s12
	s_addc_u32 s101, s101, s13
	s_mov_b32 m0, s49
	s_nop 0
	global_load_lds_dwordx4 v134, s[100:101]
	s_mov_b32 m0, s50
	s_nop 0
	global_load_lds_dwordx4 v130, s[100:101]
	s_waitcnt vmcnt(8)
	s_waitcnt lgkmcnt(0)
	s_barrier
; #define PG8_STAGE(bufoff, gbase, voff) do { _Pragma("unroll") for (int _i = 0; _i < 2; ++_i) \
;         __builtin_amdgcn_global_load_lds((const unsigned*)((const char*)(gbase) + (voff)[_i]), (PG8_LAS unsigned*)(lds + (bufoff) + ldsw + _i * 8192), 16, 0, 0); } while (0)
; #define PG8_LDA(dst, b, h) do { _Pragma("unroll") for (int m = 0; m < 4; ++m) _Pragma("unroll") for (int k = 0; k < 2; ++k) dst[m][k] = *(const PG8_LAS bf16x8*)(lds + PG8_SA(b, h) + aoff + m * 2048 + k * 1024); } while (0)
; #define PG8_MMA(ai, bj, At, Bt) do { __builtin_amdgcn_s_setprio(1); _Pragma("unroll") for (int m = 0; m < 4; ++m) _Pragma("unroll") for (int n = 0; n < 2; ++n) _Pragma("unroll") for (int k = 0; k < 2; ++k) \
;         acc[ai][bj][m][n] = __builtin_amdgcn_mfma_f32_16x16x32_bf16(Bt[n][k], At[m][k], acc[ai][bj][m][n], 0, 0, 0); __builtin_amdgcn_s_setprio(0); } while (0)
; #define PG8_WAIT_V(n) asm volatile("s_waitcnt vmcnt(" #n ")" ::: "memory")
; #define PG8_WAIT_L(n) asm volatile("s_waitcnt lgkmcnt(" #n ")" ::: "memory")
; #define PG8_BAR __builtin_amdgcn_s_barrier()
; #define PG8_SCHED __builtin_amdgcn_sched_barrier(0)
; __device__ __forceinline__ float ss_scale(const u64* ss, int row) { return __builtin_amdgcn_rsqf((float)ss[row] * (1.f / 4294967296.f / 1024.f) + EPS); }
; template <class Epi, class Sched, bool ALIGN_EPI = false, bool SP2 = false>
; __device__ __forceinline__ void gemm_phase(PG8_LAS unsigned char* lds, const Gemm g, const Sched& S, const Epi& E, const int tid) {
;     ...
;             PG8_LDA(At, 1, 1); PG8_STAGE(PG8_SB(1, 0), b3, voffB); PG8_STAGE(PG8_SB(1, 1), b3 + hstep, voffB); PG8_STAGE(PG8_SA(1, 0), a3, voffA);
;             PG8_WAIT_V(8); PG8_WAIT_L(0); PG8_BAR; PG8_MMA(1, 0, At, B0); PG8_MMA(1, 1, At, B1); PG8_BAR; PG8_SCHED;
;     __device__ __forceinline__ void operator()(const f32x4 (&acc)[2][2][4][2], const pg8::Unit& u, int wr, int wc, int fr, int fq) const {
;         const int row0 = u.pm * 256 + wr * 64 + fr, col0 = u.pn * 128 + wc * 32 + 8 * fq;
; #pragma unroll
;         for (int ai = 0; ai < 2; ++ai)
; #pragma unroll
;             for (int m = 0; m < 4; ++m) {
;                 const int row = row0 + ai * 128 + m * 16;
;                 float s = ss_scale(ss, row);
;                 if constexpr (NN) s *= __builtin_amdgcn_rsqf(s * s * (float)ssw[row] * (1.f / 4294967296.f / 1024.f) + EPS);
	s_waitcnt lgkmcnt(0)
	v_mfma_f32_16x16x32_bf16 v[60:63], v[144:147], v[186:189], v[60:63]
	v_mfma_f32_16x16x32_bf16 v[56:59], v[162:165], v[186:189], v[56:59]
	v_mfma_f32_16x16x32_bf16 v[44:47], v[144:147], v[194:197], v[44:47]
	v_mfma_f32_16x16x32_bf16 v[40:43], v[162:165], v[194:197], v[40:43]
	v_mfma_f32_16x16x32_bf16 v[28:31], v[144:147], v[204:207], v[28:31]
	v_mfma_f32_16x16x32_bf16 v[24:27], v[162:165], v[204:207], v[24:27]
	v_mfma_f32_16x16x32_bf16 v[12:15], v[144:147], v[212:215], v[12:15]
	v_mfma_f32_16x16x32_bf16 v[8:11], v[162:165], v[212:215], v[8:11]
	v_mfma_f32_16x16x32_bf16 v[60:63], v[148:151], v[190:193], v[60:63]
	v_mfma_f32_16x16x32_bf16 v[56:59], v[166:169], v[190:193], v[56:59]
	v_mfma_f32_16x16x32_bf16 v[44:47], v[148:151], v[200:203], v[44:47]
	v_mfma_f32_16x16x32_bf16 v[40:43], v[166:169], v[200:203], v[40:43]
	v_mfma_f32_16x16x32_bf16 v[28:31], v[148:151], v[208:211], v[28:31]
	v_mfma_f32_16x16x32_bf16 v[24:27], v[166:169], v[208:211], v[24:27]
	v_mfma_f32_16x16x32_bf16 v[12:15], v[148:151], v[216:219], v[12:15]
	v_mfma_f32_16x16x32_bf16 v[8:11], v[166:169], v[216:219], v[8:11]
	v_mfma_f32_16x16x32_bf16 v[52:55], v[170:173], v[186:189], v[52:55]
	v_mfma_f32_16x16x32_bf16 v[48:51], v[178:181], v[186:189], v[48:51]
	v_mfma_f32_16x16x32_bf16 v[36:39], v[170:173], v[194:197], v[36:39]
	v_mfma_f32_16x16x32_bf16 v[32:35], v[178:181], v[194:197], v[32:35]
	v_mfma_f32_16x16x32_bf16 v[20:23], v[170:173], v[204:207], v[20:23]
	v_mfma_f32_16x16x32_bf16 v[16:19], v[178:181], v[204:207], v[16:19]
	v_mfma_f32_16x16x32_bf16 v[4:7], v[170:173], v[212:215], v[4:7]
	v_mfma_f32_16x16x32_bf16 v[0:3], v[178:181], v[212:215], v[0:3]
	v_mfma_f32_16x16x32_bf16 v[52:55], v[174:177], v[190:193], v[52:55]
	v_mfma_f32_16x16x32_bf16 v[48:51], v[182:185], v[190:193], v[48:51]
	v_mfma_f32_16x16x32_bf16 v[36:39], v[174:177], v[200:203], v[36:39]
	v_mfma_f32_16x16x32_bf16 v[32:35], v[182:185], v[200:203], v[32:35]
	v_mfma_f32_16x16x32_bf16 v[20:23], v[174:177], v[208:211], v[20:23]
	v_mfma_f32_16x16x32_bf16 v[16:19], v[182:185], v[208:211], v[16:19]
	v_mfma_f32_16x16x32_bf16 v[4:7], v[174:177], v[216:219], v[4:7]
	v_mfma_f32_16x16x32_bf16 v[0:3], v[182:185], v[216:219], v[0:3]
	s_barrier
	s_add_i32 s60, s60, 2
	s_add_u32 s26, s26, 0x100
	s_addc_u32 s27, s27, 0
	s_add_u32 s58, s58, 0x100
	s_addc_u32 s59, s59, 0
	s_cmp_gt_u32 s60, 13
	s_cbranch_scc0 .LBB0_1007
	s_setprio 0
	v_lshl_add_u32 v144, s24, 8, v154
	v_mov_b32_e32 v145, 0
	v_lshl_add_u64 v[150:151], v[144:145], 3, s[8:9]
	global_load_dwordx2 v[176:177], v[150:151], off
	global_load_dwordx2 v[178:179], v[150:151], off offset:128
	global_load_dwordx2 v[180:181], v[150:151], off offset:256
	global_load_dwordx2 v[182:183], v[150:151], off offset:384
	global_load_dwordx2 v[184:185], v[150:151], off offset:1024
	global_load_dwordx2 v[186:187], v[150:151], off offset:1152
	global_load_dwordx2 v[188:189], v[150:151], off offset:1280
	global_load_dwordx2 v[190:191], v[150:151], off offset:1408
	v_lshl_add_u64 v[210:211], v[144:145], 3, s[10:11]
	global_load_dwordx2 v[192:193], v[210:211], off
	global_load_dwordx2 v[194:195], v[210:211], off offset:128
	global_load_dwordx2 v[196:197], v[210:211], off offset:256
	global_load_dwordx2 v[200:201], v[210:211], off offset:384
	global_load_dwordx2 v[202:203], v[210:211], off offset:1024
	global_load_dwordx2 v[204:205], v[210:211], off offset:1152
	global_load_dwordx2 v[206:207], v[210:211], off offset:1280
	global_load_dwordx2 v[208:209], v[210:211], off offset:1408
	v_lshl_or_b32 v148, s55, 7, v155
	v_mul_u32_u24_e32 v146, s54, v144
	v_lshl_add_u32 v146, v148, 1, v146
	v_mov_b32_e32 v147, 0
	v_lshl_add_u64 v[146:147], v[146:147], 0, s[6:7]
	v_mov_b32_e32 v164, 1.0
	v_mov_b32_e32 v165, 1.0
	s_mov_b32 s101, 0
	s_and_b64 vcc, exec, s[14:15]
	s_cbranch_vccz .LBB0_1010
	s_barrier

; #define PG8_STAGE(bufoff, gbase, voff) do { _Pragma("unroll") for (int _i = 0; _i < 2; ++_i) \
;         __builtin_amdgcn_global_load_lds((const unsigned*)((const char*)(gbase) + (voff)[_i]), (PG8_LAS unsigned*)(lds + (bufoff) + ldsw + _i * 8192), 16, 0, 0); } while (0)
; #define PG8_LDA(dst, b, h) do { _Pragma("unroll") for (int m = 0; m < 4; ++m) _Pragma("unroll") for (int k = 0; k < 2; ++k) dst[m][k] = *(const PG8_LAS bf16x8*)(lds + PG8_SA(b, h) + aoff + m * 2048 + k * 1024); } while (0)
; #define PG8_LDB(dst, b, h) do { _Pragma("unroll") for (int n = 0; n < 2; ++n) _Pragma("unroll") for (int k = 0; k < 2; ++k) dst[n][k] = *(const PG8_LAS bf16x8*)(lds + PG8_SB(b, h) + boff + n * 2048 + k * 1024); } while (0)
; #define PG8_MMA(ai, bj, At, Bt) do { __builtin_amdgcn_s_setprio(1); _Pragma("unroll") for (int m = 0; m < 4; ++m) _Pragma("unroll") for (int n = 0; n < 2; ++n) _Pragma("unroll") for (int k = 0; k < 2; ++k) \
;         acc[ai][bj][m][n] = __builtin_amdgcn_mfma_f32_16x16x32_bf16(Bt[n][k], At[m][k], acc[ai][bj][m][n], 0, 0, 0); __builtin_amdgcn_s_setprio(0); } while (0)
; #define PG8_WAIT_V(n) asm volatile("s_waitcnt vmcnt(" #n ")" ::: "memory")
; #define PG8_WAIT_L(n) asm volatile("s_waitcnt lgkmcnt(" #n ")" ::: "memory")
; #define PG8_BAR __builtin_amdgcn_s_barrier()
; #define PG8_SCHED __builtin_amdgcn_sched_barrier(0)
; template <class Epi, class Sched, bool ALIGN_EPI = false, bool SP2 = false>
; __device__ __forceinline__ void gemm_phase(PG8_LAS unsigned char* lds, const Gemm g, const Sched& S, const Epi& E, const int tid) {
;     ...
;             PG8_LDB(B0, 0, 0); PG8_LDB(B1, 0, 1); PG8_SCHED; PG8_LDA(At, 0, 0); PG8_STAGE(PG8_SA(1, 1), a1 + hstepA, voffA);
;             PG8_WAIT_V(8); PG8_WAIT_L(0); PG8_BAR; PG8_MMA(0, 0, At, B0); PG8_MMA(0, 1, At, B1); PG8_BAR; PG8_SCHED;
;             PG8_LDA(At, 0, 1); PG8_STAGE(PG8_SB(0, 0), b2, voffB); PG8_STAGE(PG8_SB(0, 1), b2 + hstep, voffB); PG8_STAGE(PG8_SA(0, 0), a2, voffA);
;             PG8_WAIT_V(8); PG8_WAIT_L(0); PG8_BAR; PG8_MMA(1, 0, At, B0); PG8_MMA(1, 1, At, B1); PG8_BAR; PG8_SCHED;
.Lsp_7:
	ds_read_b128 v[80:83], v168
	ds_read_b128 v[84:87], v168 offset:1024
	ds_read_b128 v[88:91], v168 offset:2048
	ds_read_b128 v[92:95], v168 offset:3072
	ds_read_b128 v[160:163], v169
	ds_read_b128 v[176:179], v169 offset:1024
	ds_read_b128 v[180:183], v169 offset:2048
	ds_read_b128 v[184:187], v169 offset:3072
	s_add_u32 s28, s26, 0x100
	s_addc_u32 s29, s27, 0
	s_cmp_eq_u32 s63, 40
	s_cselect_b32 s35, s7, s29
	s_cselect_b32 s34, s6, s28
	s_cselect_b32 s31, s25, s62
	s_cselect_b32 s30, s24, s61
	s_add_i32 m0, s42, 0xc000
	ds_read_b128 v[188:191], v170
	ds_read_b128 v[192:195], v170 offset:1024
	ds_read_b128 v[200:203], v170 offset:2048
	ds_read_b128 v[204:207], v170 offset:3072
	ds_read_b128 v[208:211], v170 offset:4096
	ds_read_b128 v[212:215], v170 offset:5120
	ds_read_b128 v[216:219], v170 offset:6144
	ds_read_b128 v[220:223], v170 offset:7168
	global_load_lds_dwordx4 v152, s[26:27]
	s_add_i32 m0, s42, 0xe000
	s_nop 0
	global_load_lds_dwordx4 v154, s[26:27]
	s_waitcnt vmcnt(8)
	s_waitcnt lgkmcnt(0)
	s_barrier
	s_waitcnt lgkmcnt(0)
	v_mfma_f32_16x16x32_bf16 v[140:143], v[80:83], v[188:191], v[140:143]
	v_mfma_f32_16x16x32_bf16 v[136:139], v[88:91], v[188:191], v[136:139]
	v_mfma_f32_16x16x32_bf16 v[124:127], v[80:83], v[200:203], v[124:127]
	v_mfma_f32_16x16x32_bf16 v[120:123], v[88:91], v[200:203], v[120:123]
	v_mfma_f32_16x16x32_bf16 v[108:111], v[80:83], v[208:211], v[108:111]
	v_mfma_f32_16x16x32_bf16 v[104:107], v[88:91], v[208:211], v[104:107]
	v_mfma_f32_16x16x32_bf16 v[76:79], v[80:83], v[216:219], v[76:79]
	v_mfma_f32_16x16x32_bf16 v[72:75], v[88:91], v[216:219], v[72:75]
	v_mfma_f32_16x16x32_bf16 v[140:143], v[84:87], v[192:195], v[140:143]
	v_mfma_f32_16x16x32_bf16 v[136:139], v[92:95], v[192:195], v[136:139]
	v_mfma_f32_16x16x32_bf16 v[124:127], v[84:87], v[204:207], v[124:127]
	v_mfma_f32_16x16x32_bf16 v[120:123], v[92:95], v[204:207], v[120:123]
	v_mfma_f32_16x16x32_bf16 v[108:111], v[84:87], v[212:215], v[108:111]
	v_mfma_f32_16x16x32_bf16 v[104:107], v[92:95], v[212:215], v[104:107]
	v_mfma_f32_16x16x32_bf16 v[76:79], v[84:87], v[220:223], v[76:79]
	v_mfma_f32_16x16x32_bf16 v[72:75], v[92:95], v[220:223], v[72:75]
	v_mfma_f32_16x16x32_bf16 v[132:135], v[160:163], v[188:191], v[132:135]
	v_mfma_f32_16x16x32_bf16 v[128:131], v[180:183], v[188:191], v[128:131]
	v_mfma_f32_16x16x32_bf16 v[116:119], v[160:163], v[200:203], v[116:119]
	v_mfma_f32_16x16x32_bf16 v[112:115], v[180:183], v[200:203], v[112:115]
	v_mfma_f32_16x16x32_bf16 v[100:103], v[160:163], v[208:211], v[100:103]
	v_mfma_f32_16x16x32_bf16 v[96:99], v[180:183], v[208:211], v[96:99]
	v_mfma_f32_16x16x32_bf16 v[68:71], v[160:163], v[216:219], v[68:71]
	v_mfma_f32_16x16x32_bf16 v[64:67], v[180:183], v[216:219], v[64:67]
	v_mfma_f32_16x16x32_bf16 v[132:135], v[176:179], v[192:195], v[132:135]
	v_mfma_f32_16x16x32_bf16 v[128:131], v[184:187], v[192:195], v[128:131]
	v_mfma_f32_16x16x32_bf16 v[116:119], v[176:179], v[204:207], v[116:119]
	v_mfma_f32_16x16x32_bf16 v[112:115], v[184:187], v[204:207], v[112:115]
	v_mfma_f32_16x16x32_bf16 v[100:103], v[176:179], v[212:215], v[100:103]
	v_mfma_f32_16x16x32_bf16 v[96:99], v[184:187], v[212:215], v[96:99]
	v_mfma_f32_16x16x32_bf16 v[68:71], v[176:179], v[220:223], v[68:71]
	v_mfma_f32_16x16x32_bf16 v[64:67], v[184:187], v[220:223], v[64:67]
	s_barrier
	s_mov_b32 m0, s38
	s_mov_b64 s[98:99], s[30:31]
	s_add_u32 s26, s30, 0xb0000
	ds_read_b128 v[188:191], v170 offset:16384
	ds_read_b128 v[192:195], v170 offset:17408
	ds_read_b128 v[200:203], v170 offset:18432
	ds_read_b128 v[204:207], v170 offset:19456
	ds_read_b128 v[208:211], v170 offset:20480
	ds_read_b128 v[212:215], v170 offset:21504
	ds_read_b128 v[216:219], v170 offset:22528
	ds_read_b128 v[220:223], v170 offset:23552
	global_load_lds_dwordx4 v146, s[30:31]
	s_mov_b32 m0, s39
	s_addc_u32 s27, s31, 0
	global_load_lds_dwordx4 v150, s[30:31]
	s_mov_b32 m0, s40
	s_nop 0
	global_load_lds_dwordx4 v146, s[26:27]
	s_mov_b32 m0, s41
	s_nop 0
	global_load_lds_dwordx4 v150, s[26:27]
	s_mov_b64 s[100:101], s[34:35]
	s_mov_b32 m0, s42
	s_nop 0
	global_load_lds_dwordx4 v144, s[34:35]
	s_mov_b32 m0, s43
	s_nop 0
	global_load_lds_dwordx4 v148, s[34:35]
	s_waitcnt vmcnt(8)
	s_waitcnt lgkmcnt(0)
	s_barrier
	s_waitcnt lgkmcnt(0)
	v_mfma_f32_16x16x32_bf16 v[60:63], v[80:83], v[188:191], v[60:63]
	v_mfma_f32_16x16x32_bf16 v[56:59], v[88:91], v[188:191], v[56:59]
	v_mfma_f32_16x16x32_bf16 v[44:47], v[80:83], v[200:203], v[44:47]
	v_mfma_f32_16x16x32_bf16 v[40:43], v[88:91], v[200:203], v[40:43]
	v_mfma_f32_16x16x32_bf16 v[28:31], v[80:83], v[208:211], v[28:31]
	v_mfma_f32_16x16x32_bf16 v[24:27], v[88:91], v[208:211], v[24:27]
	v_mfma_f32_16x16x32_bf16 v[12:15], v[80:83], v[216:219], v[12:15]
	v_mfma_f32_16x16x32_bf16 v[8:11], v[88:91], v[216:219], v[8:11]
	v_mfma_f32_16x16x32_bf16 v[60:63], v[84:87], v[192:195], v[60:63]
	v_mfma_f32_16x16x32_bf16 v[56:59], v[92:95], v[192:195], v[56:59]
	v_mfma_f32_16x16x32_bf16 v[44:47], v[84:87], v[204:207], v[44:47]
	v_mfma_f32_16x16x32_bf16 v[40:43], v[92:95], v[204:207], v[40:43]
	v_mfma_f32_16x16x32_bf16 v[28:31], v[84:87], v[212:215], v[28:31]
	v_mfma_f32_16x16x32_bf16 v[24:27], v[92:95], v[212:215], v[24:27]
	v_mfma_f32_16x16x32_bf16 v[12:15], v[84:87], v[220:223], v[12:15]
	v_mfma_f32_16x16x32_bf16 v[8:11], v[92:95], v[220:223], v[8:11]
	v_mfma_f32_16x16x32_bf16 v[52:55], v[160:163], v[188:191], v[52:55]
	v_mfma_f32_16x16x32_bf16 v[48:51], v[180:183], v[188:191], v[48:51]
	v_mfma_f32_16x16x32_bf16 v[36:39], v[160:163], v[200:203], v[36:39]
	v_mfma_f32_16x16x32_bf16 v[32:35], v[180:183], v[200:203], v[32:35]
	v_mfma_f32_16x16x32_bf16 v[20:23], v[160:163], v[208:211], v[20:23]
	v_mfma_f32_16x16x32_bf16 v[16:19], v[180:183], v[208:211], v[16:19]
	v_mfma_f32_16x16x32_bf16 v[4:7], v[160:163], v[216:219], v[4:7]
	v_mfma_f32_16x16x32_bf16 v[0:3], v[180:183], v[216:219], v[0:3]
	v_mfma_f32_16x16x32_bf16 v[52:55], v[176:179], v[192:195], v[52:55]
	v_mfma_f32_16x16x32_bf16 v[48:51], v[184:187], v[192:195], v[48:51]
	v_mfma_f32_16x16x32_bf16 v[36:39], v[176:179], v[204:207], v[36:39]
	v_mfma_f32_16x16x32_bf16 v[32:35], v[184:187], v[204:207], v[32:35]
	v_mfma_f32_16x16x32_bf16 v[20:23], v[176:179], v[212:215], v[20:23]
	v_mfma_f32_16x16x32_bf16 v[16:19], v[184:187], v[212:215], v[16:19]
	v_mfma_f32_16x16x32_bf16 v[4:7], v[176:179], v[220:223], v[4:7]
	v_mfma_f32_16x16x32_bf16 v[0:3], v[184:187], v[220:223], v[0:3]
	s_barrier
; #define PG8_STAGE(bufoff, gbase, voff) do { _Pragma("unroll") for (int _i = 0; _i < 2; ++_i) \
;         __builtin_amdgcn_global_load_lds((const unsigned*)((const char*)(gbase) + (voff)[_i]), (PG8_LAS unsigned*)(lds + (bufoff) + ldsw + _i * 8192), 16, 0, 0); } while (0)
; #define PG8_LDA(dst, b, h) do { _Pragma("unroll") for (int m = 0; m < 4; ++m) _Pragma("unroll") for (int k = 0; k < 2; ++k) dst[m][k] = *(const PG8_LAS bf16x8*)(lds + PG8_SA(b, h) + aoff + m * 2048 + k * 1024); } while (0)
; #define PG8_LDB(dst, b, h) do { _Pragma("unroll") for (int n = 0; n < 2; ++n) _Pragma("unroll") for (int k = 0; k < 2; ++k) dst[n][k] = *(const PG8_LAS bf16x8*)(lds + PG8_SB(b, h) + boff + n * 2048 + k * 1024); } while (0)
; #define PG8_MMA(ai, bj, At, Bt) do { __builtin_amdgcn_s_setprio(1); _Pragma("unroll") for (int m = 0; m < 4; ++m) _Pragma("unroll") for (int n = 0; n < 2; ++n) _Pragma("unroll") for (int k = 0; k < 2; ++k) \
;         acc[ai][bj][m][n] = __builtin_amdgcn_mfma_f32_16x16x32_bf16(Bt[n][k], At[m][k], acc[ai][bj][m][n], 0, 0, 0); __builtin_amdgcn_s_setprio(0); } while (0)
; #define PG8_WAIT_V(n) asm volatile("s_waitcnt vmcnt(" #n ")" ::: "memory")
; #define PG8_WAIT_L(n) asm volatile("s_waitcnt lgkmcnt(" #n ")" ::: "memory")
; #define PG8_BAR __builtin_amdgcn_s_barrier()
; #define PG8_SCHED __builtin_amdgcn_sched_barrier(0)
; template <class Epi, class Sched, bool ALIGN_EPI = false, bool SP2 = false>
; __device__ __forceinline__ void gemm_phase(PG8_LAS unsigned char* lds, const Gemm g, const Sched& S, const Epi& E, const int tid) {
;     ...
;             PG8_LDB(B0, 1, 0); PG8_LDB(B1, 1, 1); PG8_SCHED; PG8_LDA(At, 1, 0); PG8_STAGE(PG8_SA(0, 1), a2 + hstepA, voffA);
;             PG8_WAIT_V(8); PG8_WAIT_L(0); PG8_BAR; PG8_MMA(0, 0, At, B0); PG8_MMA(0, 1, At, B1); PG8_BAR; PG8_SCHED;
;             PG8_LDA(At, 1, 1); PG8_STAGE(PG8_SB(1, 0), b3, voffB); PG8_STAGE(PG8_SB(1, 1), b3 + hstep, voffB); PG8_STAGE(PG8_SA(1, 0), a3, voffA);
;             PG8_WAIT_V(8); PG8_WAIT_L(0); PG8_BAR; PG8_MMA(1, 0, At, B0); PG8_MMA(1, 1, At, B1); PG8_BAR; PG8_SCHED;
	ds_read_b128 v[80:83], v171
	ds_read_b128 v[84:87], v171 offset:1024
	ds_read_b128 v[88:91], v171 offset:2048
	ds_read_b128 v[92:95], v171 offset:3072
	ds_read_b128 v[160:163], v172
	ds_read_b128 v[176:179], v172 offset:1024
	ds_read_b128 v[180:183], v172 offset:2048
	ds_read_b128 v[184:187], v172 offset:3072
	s_add_u32 s26, s34, 0xb0000
	s_addc_u32 s27, s35, 0
	s_mov_b32 m0, s44
	ds_read_b128 v[188:191], v170 offset:32768
	ds_read_b128 v[192:195], v170 offset:33792
	ds_read_b128 v[200:203], v170 offset:34816
	ds_read_b128 v[204:207], v170 offset:35840
	ds_read_b128 v[208:211], v170 offset:36864
	ds_read_b128 v[212:215], v170 offset:37888
	ds_read_b128 v[216:219], v170 offset:38912
	ds_read_b128 v[220:223], v170 offset:39936
	global_load_lds_dwordx4 v144, s[26:27]
	s_mov_b32 m0, s45
	s_nop 0
	global_load_lds_dwordx4 v148, s[26:27]
	s_waitcnt vmcnt(8)
	s_waitcnt lgkmcnt(0)
	s_barrier
	s_waitcnt lgkmcnt(0)
	v_mfma_f32_16x16x32_bf16 v[140:143], v[80:83], v[188:191], v[140:143]
	v_mfma_f32_16x16x32_bf16 v[136:139], v[88:91], v[188:191], v[136:139]
	v_mfma_f32_16x16x32_bf16 v[124:127], v[80:83], v[200:203], v[124:127]
	v_mfma_f32_16x16x32_bf16 v[120:123], v[88:91], v[200:203], v[120:123]
	v_mfma_f32_16x16x32_bf16 v[108:111], v[80:83], v[208:211], v[108:111]
	v_mfma_f32_16x16x32_bf16 v[104:107], v[88:91], v[208:211], v[104:107]
	v_mfma_f32_16x16x32_bf16 v[76:79], v[80:83], v[216:219], v[76:79]
	v_mfma_f32_16x16x32_bf16 v[72:75], v[88:91], v[216:219], v[72:75]
	v_mfma_f32_16x16x32_bf16 v[140:143], v[84:87], v[192:195], v[140:143]
	v_mfma_f32_16x16x32_bf16 v[136:139], v[92:95], v[192:195], v[136:139]
	v_mfma_f32_16x16x32_bf16 v[124:127], v[84:87], v[204:207], v[124:127]
	v_mfma_f32_16x16x32_bf16 v[120:123], v[92:95], v[204:207], v[120:123]
	v_mfma_f32_16x16x32_bf16 v[108:111], v[84:87], v[212:215], v[108:111]
	v_mfma_f32_16x16x32_bf16 v[104:107], v[92:95], v[212:215], v[104:107]
	v_mfma_f32_16x16x32_bf16 v[76:79], v[84:87], v[220:223], v[76:79]
	v_mfma_f32_16x16x32_bf16 v[72:75], v[92:95], v[220:223], v[72:75]
	v_mfma_f32_16x16x32_bf16 v[132:135], v[160:163], v[188:191], v[132:135]
	v_mfma_f32_16x16x32_bf16 v[128:131], v[180:183], v[188:191], v[128:131]
	v_mfma_f32_16x16x32_bf16 v[116:119], v[160:163], v[200:203], v[116:119]
	v_mfma_f32_16x16x32_bf16 v[112:115], v[180:183], v[200:203], v[112:115]
	v_mfma_f32_16x16x32_bf16 v[100:103], v[160:163], v[208:211], v[100:103]
	v_mfma_f32_16x16x32_bf16 v[96:99], v[180:183], v[208:211], v[96:99]
	v_mfma_f32_16x16x32_bf16 v[68:71], v[160:163], v[216:219], v[68:71]
	v_mfma_f32_16x16x32_bf16 v[64:67], v[180:183], v[216:219], v[64:67]
	v_mfma_f32_16x16x32_bf16 v[132:135], v[176:179], v[192:195], v[132:135]
	v_mfma_f32_16x16x32_bf16 v[128:131], v[184:187], v[192:195], v[128:131]
	v_mfma_f32_16x16x32_bf16 v[116:119], v[176:179], v[204:207], v[116:119]
	v_mfma_f32_16x16x32_bf16 v[112:115], v[184:187], v[204:207], v[112:115]
	v_mfma_f32_16x16x32_bf16 v[100:103], v[176:179], v[212:215], v[100:103]
	v_mfma_f32_16x16x32_bf16 v[96:99], v[184:187], v[212:215], v[96:99]
	v_mfma_f32_16x16x32_bf16 v[68:71], v[176:179], v[220:223], v[68:71]
	v_mfma_f32_16x16x32_bf16 v[64:67], v[184:187], v[220:223], v[64:67]
	s_barrier
	s_mov_b32 m0, s48
	s_add_u32 s98, s98, s18
	s_addc_u32 s99, s99, s19
	s_add_u32 s26, s30, 0xb0080
	ds_read_b128 v[188:191], v170 offset:49152
	ds_read_b128 v[192:195], v170 offset:50176
	ds_read_b128 v[200:203], v170 offset:51200
	ds_read_b128 v[204:207], v170 offset:52224
	ds_read_b128 v[208:211], v170 offset:53248
	ds_read_b128 v[212:215], v170 offset:54272
	ds_read_b128 v[216:219], v170 offset:55296
	ds_read_b128 v[220:223], v170 offset:56320
	global_load_lds_dwordx4 v146, s[98:99]
	s_mov_b32 m0, s49
	s_addc_u32 s27, s31, 0
	global_load_lds_dwordx4 v150, s[98:99]
	s_mov_b32 m0, s52
	s_nop 0
	global_load_lds_dwordx4 v146, s[26:27]
	s_mov_b32 m0, s53
	s_nop 0
	global_load_lds_dwordx4 v150, s[26:27]
	s_add_u32 s100, s100, s18
	s_addc_u32 s101, s101, s19
	s_mov_b32 m0, s50
	s_nop 0
	global_load_lds_dwordx4 v144, s[100:101]
	s_mov_b32 m0, s51
	s_nop 0
	global_load_lds_dwordx4 v148, s[100:101]
	s_waitcnt vmcnt(8)
	s_waitcnt lgkmcnt(0)
	s_barrier
	s_waitcnt lgkmcnt(0)
	v_mfma_f32_16x16x32_bf16 v[60:63], v[80:83], v[188:191], v[60:63]
	v_mfma_f32_16x16x32_bf16 v[56:59], v[88:91], v[188:191], v[56:59]
	v_mfma_f32_16x16x32_bf16 v[44:47], v[80:83], v[200:203], v[44:47]
	v_mfma_f32_16x16x32_bf16 v[40:43], v[88:91], v[200:203], v[40:43]
	v_mfma_f32_16x16x32_bf16 v[28:31], v[80:83], v[208:211], v[28:31]
	v_mfma_f32_16x16x32_bf16 v[24:27], v[88:91], v[208:211], v[24:27]
	v_mfma_f32_16x16x32_bf16 v[12:15], v[80:83], v[216:219], v[12:15]
	v_mfma_f32_16x16x32_bf16 v[8:11], v[88:91], v[216:219], v[8:11]
	v_mfma_f32_16x16x32_bf16 v[60:63], v[84:87], v[192:195], v[60:63]
	v_mfma_f32_16x16x32_bf16 v[56:59], v[92:95], v[192:195], v[56:59]
	v_mfma_f32_16x16x32_bf16 v[44:47], v[84:87], v[204:207], v[44:47]
	v_mfma_f32_16x16x32_bf16 v[40:43], v[92:95], v[204:207], v[40:43]
	v_mfma_f32_16x16x32_bf16 v[28:31], v[84:87], v[212:215], v[28:31]
	v_mfma_f32_16x16x32_bf16 v[24:27], v[92:95], v[212:215], v[24:27]
	v_mfma_f32_16x16x32_bf16 v[12:15], v[84:87], v[220:223], v[12:15]
	v_mfma_f32_16x16x32_bf16 v[8:11], v[92:95], v[220:223], v[8:11]
	v_mfma_f32_16x16x32_bf16 v[52:55], v[160:163], v[188:191], v[52:55]
	v_mfma_f32_16x16x32_bf16 v[48:51], v[180:183], v[188:191], v[48:51]
	v_mfma_f32_16x16x32_bf16 v[36:39], v[160:163], v[200:203], v[36:39]
	v_mfma_f32_16x16x32_bf16 v[32:35], v[180:183], v[200:203], v[32:35]
	v_mfma_f32_16x16x32_bf16 v[20:23], v[160:163], v[208:211], v[20:23]
	v_mfma_f32_16x16x32_bf16 v[16:19], v[180:183], v[208:211], v[16:19]
	v_mfma_f32_16x16x32_bf16 v[4:7], v[160:163], v[216:219], v[4:7]
	v_mfma_f32_16x16x32_bf16 v[0:3], v[180:183], v[216:219], v[0:3]
	v_mfma_f32_16x16x32_bf16 v[52:55], v[176:179], v[192:195], v[52:55]
	v_mfma_f32_16x16x32_bf16 v[48:51], v[184:187], v[192:195], v[48:51]
	v_mfma_f32_16x16x32_bf16 v[36:39], v[176:179], v[204:207], v[36:39]
	v_mfma_f32_16x16x32_bf16 v[32:35], v[184:187], v[204:207], v[32:35]
	v_mfma_f32_16x16x32_bf16 v[20:23], v[176:179], v[212:215], v[20:23]
	v_mfma_f32_16x16x32_bf16 v[16:19], v[184:187], v[212:215], v[16:19]
	v_mfma_f32_16x16x32_bf16 v[4:7], v[176:179], v[220:223], v[4:7]
	v_mfma_f32_16x16x32_bf16 v[0:3], v[184:187], v[220:223], v[0:3]
	s_barrier
	s_add_i32 s63, s63, 2
	s_add_u32 s61, s61, 0x100
	s_addc_u32 s62, s62, 0
	s_cmp_gt_u32 s63, 41
	s_mov_b64 s[26:27], s[28:29]
	s_cbranch_scc0 .LBB0_1081
	s_setprio 0
	s_and_b64 vcc, exec, s[20:21]
	s_cbranch_vccnz .LBB0_1085
	s_andn2_b64 vcc, exec, s[22:23]
	s_cbranch_vccz .LBB0_1086
